# baseline (speedup 1.0000x reference)
; #define PG8_STAGE(bufoff, gbase, voff) do { _Pragma("unroll") for (int _i = 0; _i < 2; ++_i) \
;         __builtin_amdgcn_global_load_lds((const unsigned*)((const char*)(gbase) + (voff)[_i]), (LAS unsigned*)(lds + (bufoff) + ldsw + _i * 8192), 16, 0, 0); } while (0)
; #define PG8_LDA(dst, b, h) do { _Pragma("unroll") for (int m = 0; m < 4; ++m) _Pragma("unroll") for (int k = 0; k < 2; ++k) dst[m][k] = *(const LAS bf16x8*)(lds + PG8_SA(b, h) + aoff + m * 2048 + k * 1024); } while (0)
; #define PG8_LDB(dst, b, h) do { _Pragma("unroll") for (int n = 0; n < 2; ++n) _Pragma("unroll") for (int k = 0; k < 2; ++k) dst[n][k] = *(const LAS bf16x8*)(lds + PG8_SB(b, h) + boff + n * 2048 + k * 1024); } while (0)
; #define PG8_MMA(ai, bj, At, Bt) do { __builtin_amdgcn_s_setprio(1); _Pragma("unroll") for (int m = 0; m < 4; ++m) _Pragma("unroll") for (int n = 0; n < 2; ++n) _Pragma("unroll") for (int k = 0; k < 2; ++k) \
;         acc[ai][bj][m][n] = __builtin_amdgcn_mfma_f32_16x16x32_bf16(Bt[n][k], At[m][k], acc[ai][bj][m][n], 0, 0, 0); __builtin_amdgcn_s_setprio(0); } while (0)
; #define PG8_WAIT_L(n) asm volatile("s_waitcnt lgkmcnt(" #n ")" ::: "memory")
; #define PG8_BAR __builtin_amdgcn_s_barrier()
; #define PG8_SCHED __builtin_amdgcn_sched_barrier(0)
; template <class Epi>
; DEV void gemm_phase(LAS unsigned char* lds, const Gemm g, const StaticOrder& S, const Epi& E) {
;     ...
;             PG8_LDB(B0, 0, 0); PG8_SCHED; PG8_LDA(At, 0, 0); PG8_STAGE(PG8_SA(1, 1), a1 + hstep, voffA);
;             PG8_WAIT_L(8); PG8_BAR; PG8_WAIT_L(0); PG8_MMA(0, 0, At, B0); PG8_BAR; PG8_SCHED;
;             PG8_LDB(B1, 0, 1); PG8_STAGE(PG8_SB(0, 0), b2, voffB);
;             PG8_BAR; PG8_WAIT_L(0); PG8_MMA(0, 1, At, B1); PG8_BAR;
;             PG8_LDA(At, 0, 1); PG8_STAGE(PG8_SA(0, 0), a2, voffA);
;             PG8_BAR; PG8_WAIT_L(0); PG8_MMA(1, 0, At, B0); PG8_BAR; PG8_SCHED;
.LBB0_344:
	s_add_u32 s20, s18, 0xfff80080
	s_addc_u32 s21, s19, -1
	s_add_i32 s45, 0, 0x10000
	v_add_u32_e32 v146, s45, v149
	ds_read_b128 v[128:131], v146
	ds_read_b128 v[132:135], v146 offset:1024
	ds_read_b128 v[142:145], v146 offset:2048
	ds_read_b128 v[150:153], v146 offset:3072
	s_cmp_eq_u32 s44, 28
	s_cselect_b32 s23, s1, s21
	s_cselect_b32 s22, s13, s20
	s_cselect_b32 s21, s11, s43
	s_cselect_b32 s20, s41, s42
	v_lshl_add_u64 v[154:155], s[18:19], 0, v[138:139]
	s_add_i32 m0, s30, 0xc000
	ds_read_b128 v[174:177], v159
	ds_read_b128 v[178:181], v159 offset:1024
	ds_read_b128 v[182:185], v159 offset:2048
	ds_read_b128 v[186:189], v159 offset:3072
	ds_read_b128 v[190:193], v159 offset:4096
	ds_read_b128 v[194:197], v159 offset:5120
	ds_read_b128 v[214:217], v159 offset:6144
	ds_read_b128 v[218:221], v159 offset:7168
	global_load_lds_dwordx4 v[154:155], off
	v_lshl_add_u64 v[154:155], s[18:19], 0, v[140:141]
	s_add_i32 m0, s30, 0xe000
	s_nop 0
	global_load_lds_dwordx4 v[154:155], off
	s_waitcnt lgkmcnt(8)
	s_barrier
	s_waitcnt lgkmcnt(0)
	s_setprio 1
	s_waitcnt lgkmcnt(0)
	v_mfma_f32_16x16x32_bf16 v[124:127], v[128:131], v[174:177], v[124:127]
	v_mfma_f32_16x16x32_bf16 v[120:123], v[142:145], v[174:177], v[120:123]
	v_mfma_f32_16x16x32_bf16 v[116:119], v[128:131], v[182:185], v[116:119]
	v_mfma_f32_16x16x32_bf16 v[108:111], v[142:145], v[182:185], v[108:111]
	v_mfma_f32_16x16x32_bf16 v[100:103], v[128:131], v[190:193], v[100:103]
	v_mfma_f32_16x16x32_bf16 v[92:95], v[142:145], v[190:193], v[92:95]
	v_mfma_f32_16x16x32_bf16 v[84:87], v[128:131], v[214:217], v[84:87]
	v_mfma_f32_16x16x32_bf16 v[76:79], v[142:145], v[214:217], v[76:79]
	v_mfma_f32_16x16x32_bf16 v[124:127], v[132:135], v[178:181], v[124:127]
	v_mfma_f32_16x16x32_bf16 v[120:123], v[150:153], v[178:181], v[120:123]
	v_mfma_f32_16x16x32_bf16 v[116:119], v[132:135], v[186:189], v[116:119]
	v_mfma_f32_16x16x32_bf16 v[108:111], v[150:153], v[186:189], v[108:111]
	v_mfma_f32_16x16x32_bf16 v[100:103], v[132:135], v[194:197], v[100:103]
	v_mfma_f32_16x16x32_bf16 v[92:95], v[150:153], v[194:197], v[92:95]
	v_mfma_f32_16x16x32_bf16 v[84:87], v[132:135], v[218:221], v[84:87]
	v_mfma_f32_16x16x32_bf16 v[76:79], v[150:153], v[218:221], v[76:79]
	s_setprio 0
	s_barrier
	s_add_i32 s48, 0, 0x14000
	s_add_i32 s45, s45, s29
	v_add_u32_e32 v146, s48, v149
	v_lshl_add_u64 v[154:155], s[20:21], 0, v[160:161]
	s_mov_b32 m0, s45
	ds_read_b128 v[222:225], v146
	ds_read_b128 v[226:229], v146 offset:1024
	ds_read_b128 v[230:233], v146 offset:2048
	ds_read_b128 v[234:237], v146 offset:3072
	global_load_lds_dwordx4 v[154:155], off
	v_lshl_add_u64 v[238:239], s[20:21], 0, v[136:137]
	s_add_i32 m0, s45, 0x2000
	s_nop 0
	global_load_lds_dwordx4 v[238:239], off
	s_barrier
	s_waitcnt lgkmcnt(0)
	s_setprio 1
	s_waitcnt lgkmcnt(0)
	v_mfma_f32_16x16x32_bf16 v[112:115], v[222:225], v[174:177], v[112:115]
	v_mfma_f32_16x16x32_bf16 v[104:107], v[230:233], v[174:177], v[104:107]
	v_mfma_f32_16x16x32_bf16 v[96:99], v[222:225], v[182:185], v[96:99]
	v_mfma_f32_16x16x32_bf16 v[88:91], v[230:233], v[182:185], v[88:91]
	v_mfma_f32_16x16x32_bf16 v[80:83], v[222:225], v[190:193], v[80:83]
	v_mfma_f32_16x16x32_bf16 v[72:75], v[230:233], v[190:193], v[72:75]
	v_mfma_f32_16x16x32_bf16 v[68:71], v[222:225], v[214:217], v[68:71]
	v_mfma_f32_16x16x32_bf16 v[64:67], v[230:233], v[214:217], v[64:67]
	v_mfma_f32_16x16x32_bf16 v[112:115], v[226:229], v[178:181], v[112:115]
	v_mfma_f32_16x16x32_bf16 v[104:107], v[234:237], v[178:181], v[104:107]
	v_mfma_f32_16x16x32_bf16 v[96:99], v[226:229], v[186:189], v[96:99]
	v_mfma_f32_16x16x32_bf16 v[88:91], v[234:237], v[186:189], v[88:91]
	v_mfma_f32_16x16x32_bf16 v[80:83], v[226:229], v[194:197], v[80:83]
	v_mfma_f32_16x16x32_bf16 v[72:75], v[234:237], v[194:197], v[72:75]
	v_mfma_f32_16x16x32_bf16 v[68:71], v[226:229], v[218:221], v[68:71]
	v_mfma_f32_16x16x32_bf16 v[64:67], v[234:237], v[218:221], v[64:67]
	s_setprio 0
	s_mov_b32 m0, s30
	v_lshl_add_u64 v[240:241], s[22:23], 0, v[160:161]
	s_barrier
	ds_read_b128 v[174:177], v159 offset:16384
	ds_read_b128 v[178:181], v159 offset:17408
	ds_read_b128 v[182:185], v159 offset:18432
	ds_read_b128 v[186:189], v159 offset:19456
	ds_read_b128 v[190:193], v159 offset:20480
	ds_read_b128 v[194:197], v159 offset:21504
	ds_read_b128 v[214:217], v159 offset:22528
	ds_read_b128 v[218:221], v159 offset:23552
	global_load_lds_dwordx4 v[240:241], off
	v_lshl_add_u64 v[242:243], s[22:23], 0, v[136:137]
	s_mov_b32 m0, s31
	s_nop 0
	global_load_lds_dwordx4 v[242:243], off
	s_barrier
	s_waitcnt lgkmcnt(0)
	s_setprio 1
	s_waitcnt lgkmcnt(0)
	v_mfma_f32_16x16x32_bf16 v[60:63], v[128:131], v[174:177], v[60:63]
	v_mfma_f32_16x16x32_bf16 v[56:59], v[142:145], v[174:177], v[56:59]
	v_mfma_f32_16x16x32_bf16 v[52:55], v[128:131], v[182:185], v[52:55]
	v_mfma_f32_16x16x32_bf16 v[44:47], v[142:145], v[182:185], v[44:47]
	v_mfma_f32_16x16x32_bf16 v[36:39], v[128:131], v[190:193], v[36:39]
	v_mfma_f32_16x16x32_bf16 v[28:31], v[142:145], v[190:193], v[28:31]
	v_mfma_f32_16x16x32_bf16 v[20:23], v[128:131], v[214:217], v[20:23]
	v_mfma_f32_16x16x32_bf16 v[12:15], v[142:145], v[214:217], v[12:15]
	v_mfma_f32_16x16x32_bf16 v[60:63], v[132:135], v[178:181], v[60:63]
	v_mfma_f32_16x16x32_bf16 v[56:59], v[150:153], v[178:181], v[56:59]
	v_mfma_f32_16x16x32_bf16 v[52:55], v[132:135], v[186:189], v[52:55]
	v_mfma_f32_16x16x32_bf16 v[44:47], v[150:153], v[186:189], v[44:47]
	v_mfma_f32_16x16x32_bf16 v[36:39], v[132:135], v[194:197], v[36:39]
	v_mfma_f32_16x16x32_bf16 v[28:31], v[150:153], v[194:197], v[28:31]
	v_mfma_f32_16x16x32_bf16 v[20:23], v[132:135], v[218:221], v[20:23]
	v_mfma_f32_16x16x32_bf16 v[12:15], v[150:153], v[218:221], v[12:15]
	s_setprio 0
	s_barrier
; #define PG8_STAGE(bufoff, gbase, voff) do { _Pragma("unroll") for (int _i = 0; _i < 2; ++_i) \
;         __builtin_amdgcn_global_load_lds((const unsigned*)((const char*)(gbase) + (voff)[_i]), (LAS unsigned*)(lds + (bufoff) + ldsw + _i * 8192), 16, 0, 0); } while (0)
; #define PG8_LDA(dst, b, h) do { _Pragma("unroll") for (int m = 0; m < 4; ++m) _Pragma("unroll") for (int k = 0; k < 2; ++k) dst[m][k] = *(const LAS bf16x8*)(lds + PG8_SA(b, h) + aoff + m * 2048 + k * 1024); } while (0)
; #define PG8_LDB(dst, b, h) do { _Pragma("unroll") for (int n = 0; n < 2; ++n) _Pragma("unroll") for (int k = 0; k < 2; ++k) dst[n][k] = *(const LAS bf16x8*)(lds + PG8_SB(b, h) + boff + n * 2048 + k * 1024); } while (0)
; #define PG8_MMA(ai, bj, At, Bt) do { __builtin_amdgcn_s_setprio(1); _Pragma("unroll") for (int m = 0; m < 4; ++m) _Pragma("unroll") for (int n = 0; n < 2; ++n) _Pragma("unroll") for (int k = 0; k < 2; ++k) \
;         acc[ai][bj][m][n] = __builtin_amdgcn_mfma_f32_16x16x32_bf16(Bt[n][k], At[m][k], acc[ai][bj][m][n], 0, 0, 0); __builtin_amdgcn_s_setprio(0); } while (0)
; #define PG8_WAIT_V(n) asm volatile("s_waitcnt vmcnt(" #n ")" ::: "memory")
; #define PG8_WAIT_L(n) asm volatile("s_waitcnt lgkmcnt(" #n ")" ::: "memory")
; #define PG8_BAR __builtin_amdgcn_s_barrier()
; #define PG8_SCHED __builtin_amdgcn_sched_barrier(0)
; template <class Epi>
; DEV void gemm_phase(LAS unsigned char* lds, const Gemm g, const StaticOrder& S, const Epi& E) {
;     ...
;             PG8_STAGE(PG8_SB(0, 1), b2 + hstep, voffB);
;             PG8_WAIT_V(6); PG8_BAR; PG8_MMA(1, 1, At, B1); PG8_BAR;
;             PG8_LDB(B0, 1, 0); PG8_SCHED; PG8_LDA(At, 1, 0); PG8_STAGE(PG8_SA(0, 1), a2 + hstep, voffA);
;             PG8_WAIT_L(8); PG8_BAR; PG8_WAIT_L(0); PG8_MMA(0, 0, At, B0); PG8_BAR; PG8_SCHED;
;             PG8_LDB(B1, 1, 1); PG8_STAGE(PG8_SB(1, 0), b3, voffB);
;             PG8_BAR; PG8_WAIT_L(0); PG8_MMA(0, 1, At, B1); PG8_BAR;
;             PG8_LDA(At, 1, 1); PG8_STAGE(PG8_SA(1, 0), a3, voffA);
;             PG8_BAR; PG8_WAIT_L(0); PG8_MMA(1, 0, At, B0); PG8_BAR; PG8_SCHED;
	s_add_u32 s46, s20, 0x80000
	s_addc_u32 s47, s21, 0
	s_add_i32 s45, s48, s29
	v_lshl_add_u64 v[128:129], s[46:47], 0, v[160:161]
	s_mov_b32 m0, s45
	s_nop 0
	global_load_lds_dwordx4 v[128:129], off
	v_lshl_add_u64 v[128:129], s[46:47], 0, v[136:137]
	s_add_i32 m0, s45, 0x2000
	s_nop 0
	global_load_lds_dwordx4 v[128:129], off
	s_waitcnt vmcnt(6)
	s_barrier
	s_setprio 1
	v_mfma_f32_16x16x32_bf16 v[48:51], v[222:225], v[174:177], v[48:51]
	v_mfma_f32_16x16x32_bf16 v[40:43], v[230:233], v[174:177], v[40:43]
	v_mfma_f32_16x16x32_bf16 v[32:35], v[222:225], v[182:185], v[32:35]
	v_mfma_f32_16x16x32_bf16 v[24:27], v[230:233], v[182:185], v[24:27]
	v_mfma_f32_16x16x32_bf16 v[16:19], v[222:225], v[190:193], v[16:19]
	v_mfma_f32_16x16x32_bf16 v[8:11], v[230:233], v[190:193], v[8:11]
	v_mfma_f32_16x16x32_bf16 v[4:7], v[222:225], v[214:217], v[4:7]
	v_mfma_f32_16x16x32_bf16 v[0:3], v[230:233], v[214:217], v[0:3]
	v_mfma_f32_16x16x32_bf16 v[48:51], v[226:229], v[178:181], v[48:51]
	v_mfma_f32_16x16x32_bf16 v[40:43], v[234:237], v[178:181], v[40:43]
	v_mfma_f32_16x16x32_bf16 v[32:35], v[226:229], v[186:189], v[32:35]
	v_mfma_f32_16x16x32_bf16 v[24:27], v[234:237], v[186:189], v[24:27]
	v_mfma_f32_16x16x32_bf16 v[16:19], v[226:229], v[194:197], v[16:19]
	v_mfma_f32_16x16x32_bf16 v[8:11], v[234:237], v[194:197], v[8:11]
	v_mfma_f32_16x16x32_bf16 v[4:7], v[226:229], v[218:221], v[4:7]
	v_mfma_f32_16x16x32_bf16 v[0:3], v[234:237], v[218:221], v[0:3]
	s_setprio 0
	s_add_i32 s45, 0, 0x18000
	v_add_u32_e32 v146, s45, v149
	s_barrier
	ds_read_b128 v[128:131], v146
	ds_read_b128 v[132:135], v146 offset:1024
	ds_read_b128 v[142:145], v146 offset:2048
	ds_read_b128 v[150:153], v146 offset:3072
	s_add_u32 s22, s22, 0x80000
	s_addc_u32 s23, s23, 0
	s_mov_b32 m0, s34
	v_lshl_add_u64 v[222:223], s[22:23], 0, v[160:161]
	ds_read_b128 v[174:177], v159 offset:32768
	ds_read_b128 v[178:181], v159 offset:33792
	ds_read_b128 v[182:185], v159 offset:34816
	ds_read_b128 v[186:189], v159 offset:35840
	ds_read_b128 v[190:193], v159 offset:36864
	ds_read_b128 v[194:197], v159 offset:37888
	ds_read_b128 v[214:217], v159 offset:38912
	ds_read_b128 v[218:221], v159 offset:39936
	global_load_lds_dwordx4 v[222:223], off
	v_lshl_add_u64 v[222:223], s[22:23], 0, v[136:137]
	s_mov_b32 m0, s35
	s_nop 0
	global_load_lds_dwordx4 v[222:223], off
	s_waitcnt lgkmcnt(8)
	s_barrier
	s_waitcnt lgkmcnt(0)
	s_setprio 1
	s_waitcnt lgkmcnt(0)
	v_mfma_f32_16x16x32_bf16 v[124:127], v[128:131], v[174:177], v[124:127]
	v_mfma_f32_16x16x32_bf16 v[120:123], v[142:145], v[174:177], v[120:123]
	v_mfma_f32_16x16x32_bf16 v[116:119], v[128:131], v[182:185], v[116:119]
	v_mfma_f32_16x16x32_bf16 v[108:111], v[142:145], v[182:185], v[108:111]
	v_mfma_f32_16x16x32_bf16 v[100:103], v[128:131], v[190:193], v[100:103]
	v_mfma_f32_16x16x32_bf16 v[92:95], v[142:145], v[190:193], v[92:95]
	v_mfma_f32_16x16x32_bf16 v[84:87], v[128:131], v[214:217], v[84:87]
	v_mfma_f32_16x16x32_bf16 v[76:79], v[142:145], v[214:217], v[76:79]
	v_mfma_f32_16x16x32_bf16 v[124:127], v[132:135], v[178:181], v[124:127]
	v_mfma_f32_16x16x32_bf16 v[120:123], v[150:153], v[178:181], v[120:123]
	v_mfma_f32_16x16x32_bf16 v[116:119], v[132:135], v[186:189], v[116:119]
	v_mfma_f32_16x16x32_bf16 v[108:111], v[150:153], v[186:189], v[108:111]
	v_mfma_f32_16x16x32_bf16 v[100:103], v[132:135], v[194:197], v[100:103]
	v_mfma_f32_16x16x32_bf16 v[92:95], v[150:153], v[194:197], v[92:95]
	v_mfma_f32_16x16x32_bf16 v[84:87], v[132:135], v[218:221], v[84:87]
	v_mfma_f32_16x16x32_bf16 v[76:79], v[150:153], v[218:221], v[76:79]
	s_setprio 0
	s_barrier
	s_add_i32 s22, 0, 0x1c000
	s_add_i32 s23, s45, s29
	v_add_u32_e32 v146, s22, v149
	v_lshl_add_u64 v[154:155], v[154:155], 0, s[2:3]
	s_mov_b32 m0, s23
	ds_read_b128 v[222:225], v146
	ds_read_b128 v[226:229], v146 offset:1024
	ds_read_b128 v[230:233], v146 offset:2048
	ds_read_b128 v[234:237], v146 offset:3072
	global_load_lds_dwordx4 v[154:155], off
	v_lshl_add_u64 v[154:155], v[238:239], 0, s[2:3]
	s_add_i32 m0, s23, 0x2000
	s_nop 0
	global_load_lds_dwordx4 v[154:155], off
	s_barrier
	s_waitcnt lgkmcnt(0)
	s_setprio 1
	s_waitcnt lgkmcnt(0)
	v_mfma_f32_16x16x32_bf16 v[112:115], v[222:225], v[174:177], v[112:115]
	v_mfma_f32_16x16x32_bf16 v[104:107], v[230:233], v[174:177], v[104:107]
	v_mfma_f32_16x16x32_bf16 v[96:99], v[222:225], v[182:185], v[96:99]
	v_mfma_f32_16x16x32_bf16 v[88:91], v[230:233], v[182:185], v[88:91]
	v_mfma_f32_16x16x32_bf16 v[80:83], v[222:225], v[190:193], v[80:83]
	v_mfma_f32_16x16x32_bf16 v[72:75], v[230:233], v[190:193], v[72:75]
	v_mfma_f32_16x16x32_bf16 v[68:71], v[222:225], v[214:217], v[68:71]
	v_mfma_f32_16x16x32_bf16 v[64:67], v[230:233], v[214:217], v[64:67]
	v_mfma_f32_16x16x32_bf16 v[112:115], v[226:229], v[178:181], v[112:115]
	v_mfma_f32_16x16x32_bf16 v[104:107], v[234:237], v[178:181], v[104:107]
	v_mfma_f32_16x16x32_bf16 v[96:99], v[226:229], v[186:189], v[96:99]
	v_mfma_f32_16x16x32_bf16 v[88:91], v[234:237], v[186:189], v[88:91]
	v_mfma_f32_16x16x32_bf16 v[80:83], v[226:229], v[194:197], v[80:83]
	v_mfma_f32_16x16x32_bf16 v[72:75], v[234:237], v[194:197], v[72:75]
	v_mfma_f32_16x16x32_bf16 v[68:71], v[226:229], v[218:221], v[68:71]
	v_mfma_f32_16x16x32_bf16 v[64:67], v[234:237], v[218:221], v[64:67]
	s_setprio 0
	s_mov_b32 m0, s37
	v_lshl_add_u64 v[154:155], v[240:241], 0, s[2:3]
	s_barrier
	ds_read_b128 v[174:177], v159 offset:49152
	ds_read_b128 v[178:181], v159 offset:50176
	ds_read_b128 v[182:185], v159 offset:51200
	ds_read_b128 v[186:189], v159 offset:52224
	ds_read_b128 v[190:193], v159 offset:53248
	ds_read_b128 v[194:197], v159 offset:54272
	ds_read_b128 v[214:217], v159 offset:55296
	ds_read_b128 v[218:221], v159 offset:56320
	global_load_lds_dwordx4 v[154:155], off
	v_lshl_add_u64 v[154:155], v[242:243], 0, s[2:3]
	s_mov_b32 m0, s38
	s_nop 0
	global_load_lds_dwordx4 v[154:155], off
	s_barrier
; #define PG8_STAGE(bufoff, gbase, voff) do { _Pragma("unroll") for (int _i = 0; _i < 2; ++_i) \
;         __builtin_amdgcn_global_load_lds((const unsigned*)((const char*)(gbase) + (voff)[_i]), (LAS unsigned*)(lds + (bufoff) + ldsw + _i * 8192), 16, 0, 0); } while (0)
; #define PG8_MMA(ai, bj, At, Bt) do { __builtin_amdgcn_s_setprio(1); _Pragma("unroll") for (int m = 0; m < 4; ++m) _Pragma("unroll") for (int n = 0; n < 2; ++n) _Pragma("unroll") for (int k = 0; k < 2; ++k) \
;         acc[ai][bj][m][n] = __builtin_amdgcn_mfma_f32_16x16x32_bf16(Bt[n][k], At[m][k], acc[ai][bj][m][n], 0, 0, 0); __builtin_amdgcn_s_setprio(0); } while (0)
; #define PG8_WAIT_V(n) asm volatile("s_waitcnt vmcnt(" #n ")" ::: "memory")
; #define PG8_WAIT_L(n) asm volatile("s_waitcnt lgkmcnt(" #n ")" ::: "memory")
; #define PG8_BAR __builtin_amdgcn_s_barrier()
; #define PG8_SCHED __builtin_amdgcn_sched_barrier(0)
; template <class Epi>
; DEV void gemm_phase(LAS unsigned char* lds, const Gemm g, const StaticOrder& S, const Epi& E) {
;     ...
;             PG8_BAR; PG8_WAIT_L(0); PG8_MMA(1, 0, At, B0); PG8_BAR; PG8_SCHED;
;             PG8_STAGE(PG8_SB(1, 1), b3 + hstep, voffB);
;             PG8_WAIT_V(6); PG8_BAR; PG8_MMA(1, 1, At, B1); PG8_BAR;
;         }
; DEV float rowscale(const float* ss, int row) { const f32x4 a = *(const f32x4*)(ss + (size_t)row * 8), b = *(const f32x4*)(ss + (size_t)row * 8 + 4);
;     return rsqrtf(((a[0] + a[1]) + (a[2] + a[3]) + (b[0] + b[1]) + (b[2] + b[3])) * (1.0f / 2048.0f) + EPS); }
	s_waitcnt lgkmcnt(0)
	s_setprio 1
	s_waitcnt lgkmcnt(0)
	v_mfma_f32_16x16x32_bf16 v[60:63], v[128:131], v[174:177], v[60:63]
	v_mfma_f32_16x16x32_bf16 v[56:59], v[142:145], v[174:177], v[56:59]
	v_mfma_f32_16x16x32_bf16 v[52:55], v[128:131], v[182:185], v[52:55]
	v_mfma_f32_16x16x32_bf16 v[44:47], v[142:145], v[182:185], v[44:47]
	v_mfma_f32_16x16x32_bf16 v[36:39], v[128:131], v[190:193], v[36:39]
	v_mfma_f32_16x16x32_bf16 v[28:31], v[142:145], v[190:193], v[28:31]
	v_mfma_f32_16x16x32_bf16 v[20:23], v[128:131], v[214:217], v[20:23]
	v_mfma_f32_16x16x32_bf16 v[12:15], v[142:145], v[214:217], v[12:15]
	v_mfma_f32_16x16x32_bf16 v[60:63], v[132:135], v[178:181], v[60:63]
	v_mfma_f32_16x16x32_bf16 v[56:59], v[150:153], v[178:181], v[56:59]
	v_mfma_f32_16x16x32_bf16 v[52:55], v[132:135], v[186:189], v[52:55]
	v_mfma_f32_16x16x32_bf16 v[44:47], v[150:153], v[186:189], v[44:47]
	v_mfma_f32_16x16x32_bf16 v[36:39], v[132:135], v[194:197], v[36:39]
	v_mfma_f32_16x16x32_bf16 v[28:31], v[150:153], v[194:197], v[28:31]
	v_mfma_f32_16x16x32_bf16 v[20:23], v[132:135], v[218:221], v[20:23]
	v_mfma_f32_16x16x32_bf16 v[12:15], v[150:153], v[218:221], v[12:15]
	s_setprio 0
	s_barrier
	s_add_u32 s20, s20, 0x80080
	s_addc_u32 s21, s21, 0
	s_add_i32 s22, s22, s29
	v_lshl_add_u64 v[128:129], s[20:21], 0, v[160:161]
	s_mov_b32 m0, s22
	s_nop 0
	global_load_lds_dwordx4 v[128:129], off
	v_lshl_add_u64 v[128:129], s[20:21], 0, v[136:137]
	s_add_i32 m0, s22, 0x2000
	s_nop 0
	global_load_lds_dwordx4 v[128:129], off
	s_waitcnt vmcnt(6)
	s_barrier
	s_setprio 1
	v_mfma_f32_16x16x32_bf16 v[48:51], v[222:225], v[174:177], v[48:51]
	v_mfma_f32_16x16x32_bf16 v[40:43], v[230:233], v[174:177], v[40:43]
	v_mfma_f32_16x16x32_bf16 v[32:35], v[222:225], v[182:185], v[32:35]
	v_mfma_f32_16x16x32_bf16 v[24:27], v[230:233], v[182:185], v[24:27]
	v_mfma_f32_16x16x32_bf16 v[16:19], v[222:225], v[190:193], v[16:19]
	v_mfma_f32_16x16x32_bf16 v[8:11], v[230:233], v[190:193], v[8:11]
	v_mfma_f32_16x16x32_bf16 v[4:7], v[222:225], v[214:217], v[4:7]
	v_mfma_f32_16x16x32_bf16 v[0:3], v[230:233], v[214:217], v[0:3]
	v_mfma_f32_16x16x32_bf16 v[48:51], v[226:229], v[178:181], v[48:51]
	v_mfma_f32_16x16x32_bf16 v[40:43], v[234:237], v[178:181], v[40:43]
	v_mfma_f32_16x16x32_bf16 v[32:35], v[226:229], v[186:189], v[32:35]
	v_mfma_f32_16x16x32_bf16 v[24:27], v[234:237], v[186:189], v[24:27]
	v_mfma_f32_16x16x32_bf16 v[16:19], v[226:229], v[194:197], v[16:19]
	v_mfma_f32_16x16x32_bf16 v[8:11], v[234:237], v[194:197], v[8:11]
	v_mfma_f32_16x16x32_bf16 v[4:7], v[226:229], v[218:221], v[4:7]
	v_mfma_f32_16x16x32_bf16 v[0:3], v[234:237], v[218:221], v[0:3]
	s_setprio 0
	s_add_i32 s44, s44, 2
	s_add_u32 s18, s18, 0x100
	s_addc_u32 s19, s19, 0
	s_add_u32 s42, s42, 0x100
	s_addc_u32 s43, s43, 0
	s_cmp_gt_u32 s44, 29
	s_barrier
	s_cbranch_scc0 .LBB0_344
	v_lshl_add_u32 v142, s0, 8, v147
	v_lshlrev_b32_e32 v255, 5, v142
	global_load_dwordx4 v[216:219], v255, s[4:5]
	global_load_dwordx4 v[220:223], v255, s[4:5] offset:16
	global_load_dwordx4 v[224:227], v255, s[4:5] offset:512
	global_load_dwordx4 v[228:231], v255, s[4:5] offset:528
	global_load_dwordx4 v[232:235], v255, s[4:5] offset:1024
	global_load_dwordx4 v[236:239], v255, s[4:5] offset:1040
	global_load_dwordx4 v[240:243], v255, s[4:5] offset:1536
	global_load_dwordx4 v[244:247], v255, s[4:5] offset:1552
	v_add_u32_e32 v255, 0x1000, v255
	s_waitcnt vmcnt(6)
	v_add_f32_e32 v216, v216, v217
	v_add_f32_e32 v218, v218, v219
	v_add_f32_e32 v220, v220, v221
	v_add_f32_e32 v222, v222, v223
	v_add_f32_e32 v216, v216, v218
	v_add_f32_e32 v216, v216, v220
	v_add_f32_e32 v192, v216, v222
	s_waitcnt vmcnt(4)
	v_add_f32_e32 v224, v224, v225
	v_add_f32_e32 v226, v226, v227
	v_add_f32_e32 v228, v228, v229
	v_add_f32_e32 v230, v230, v231
	v_add_f32_e32 v224, v224, v226
	v_add_f32_e32 v224, v224, v228
	v_add_f32_e32 v193, v224, v230
	s_waitcnt vmcnt(2)
	v_add_f32_e32 v232, v232, v233
	v_add_f32_e32 v234, v234, v235
	v_add_f32_e32 v236, v236, v237
	v_add_f32_e32 v238, v238, v239
	v_add_f32_e32 v232, v232, v234
	v_add_f32_e32 v232, v232, v236
	v_add_f32_e32 v194, v232, v238
	s_waitcnt vmcnt(0)
	v_add_f32_e32 v240, v240, v241
	v_add_f32_e32 v242, v242, v243
	v_add_f32_e32 v244, v244, v245
	v_add_f32_e32 v246, v246, v247
	v_add_f32_e32 v240, v240, v242
	v_add_f32_e32 v240, v240, v244
	v_add_f32_e32 v195, v240, v246
	global_load_dwordx4 v[216:219], v255, s[4:5]
	global_load_dwordx4 v[220:223], v255, s[4:5] offset:16
	global_load_dwordx4 v[224:227], v255, s[4:5] offset:512
	global_load_dwordx4 v[228:231], v255, s[4:5] offset:528
	global_load_dwordx4 v[232:235], v255, s[4:5] offset:1024
	global_load_dwordx4 v[236:239], v255, s[4:5] offset:1040
	global_load_dwordx4 v[240:243], v255, s[4:5] offset:1536
	global_load_dwordx4 v[244:247], v255, s[4:5] offset:1552
	s_waitcnt vmcnt(6)
	v_add_f32_e32 v216, v216, v217
	v_add_f32_e32 v218, v218, v219
	v_add_f32_e32 v220, v220, v221
	v_add_f32_e32 v222, v222, v223
	v_add_f32_e32 v216, v216, v218
	v_add_f32_e32 v216, v216, v220
	v_add_f32_e32 v196, v216, v222
	s_waitcnt vmcnt(4)
	v_add_f32_e32 v224, v224, v225
	v_add_f32_e32 v226, v226, v227
	v_add_f32_e32 v228, v228, v229
	v_add_f32_e32 v230, v230, v231
	v_add_f32_e32 v224, v224, v226
	v_add_f32_e32 v224, v224, v228
	v_add_f32_e32 v197, v224, v230
	s_waitcnt vmcnt(2)
	v_add_f32_e32 v232, v232, v233
	v_add_f32_e32 v234, v234, v235
	v_add_f32_e32 v236, v236, v237
	v_add_f32_e32 v238, v238, v239
	v_add_f32_e32 v232, v232, v234
	v_add_f32_e32 v232, v232, v236
	v_add_f32_e32 v214, v232, v238
	s_waitcnt vmcnt(0)
; DEV bf16x8 pack8(f32x4 a, f32x4 b) { u32x4 w; w.x = cvt_pk_bf16(a[0], a[1]); w.y = cvt_pk_bf16(a[2], a[3]); w.z = cvt_pk_bf16(b[0], b[1]); w.w = cvt_pk_bf16(b[2], b[3]); return __builtin_bit_cast(bf16x8, w); }
; DEV u32x2 pack4(f32x4 a) { u32x2 w; w.x = cvt_pk_bf16(a[0], a[1]); w.y = cvt_pk_bf16(a[2], a[3]); return w; }
; DEV f32x4 gelu4(f32x4 v) { f32x2 a = gelu_pk((f32x2){v[0], v[1]}), b = gelu_pk((f32x2){v[2], v[3]}); return (f32x4){a.x, a.y, b.x, b.y}; }
; DEV float rowscale(const float* ss, int row) { const f32x4 a = *(const f32x4*)(ss + (size_t)row * 8), b = *(const f32x4*)(ss + (size_t)row * 8 + 4);
;     return rsqrtf(((a[0] + a[1]) + (a[2] + a[3]) + (b[0] + b[1]) + (b[2] + b[3])) * (1.0f / 2048.0f) + EPS); }
; template <int ACT, bool PERM>
; DEV void store_bf16_tile(AccRef acc, u16* O, int ld, int row0, int col0, const float* ss) {
;     float rsv[2][4];
; #pragma unroll
;     for (int ai = 0; ai < 2; ++ai)
; #pragma unroll
;         for (int m = 0; m < 4; ++m) rsv[ai][m] = ss ? rowscale(ss, row0 + ai * 128 + m * 16) : 1.0f;
; #pragma unroll
;     for (int ai = 0; ai < 2; ++ai)
; #pragma unroll
;         for (int m = 0; m < 4; ++m) { u16* rowp = O + (size_t)(row0 + ai * 128 + m * 16) * ld + col0; const float rs = rsv[ai][m];
; #pragma unroll
;             for (int bj = 0; bj < 2; ++bj) { f32x4 v0 = acc[ai][bj][m][0] * rs, v1 = acc[ai][bj][m][1] * rs; if (ACT == 1) { v0 = gelu4(v0); v1 = gelu4(v1); }
;                 if (PERM) *(u32x4*)(rowp + bj * 128) = __builtin_bit_cast(u32x4, pack8(v0, v1));
;                 else { *(u32x2*)(rowp + bj * 128) = pack4(v0); *(u32x2*)(rowp + bj * 128 + 16) = pack4(v1); } } }
; }
	v_add_f32_e32 v240, v240, v241
	v_add_f32_e32 v242, v242, v243
	v_add_f32_e32 v244, v244, v245
	v_add_f32_e32 v246, v246, v247
	v_add_f32_e32 v240, v240, v242
	v_add_f32_e32 v240, v240, v244
	v_add_f32_e32 v215, v240, v246
	v_ashrrev_i32_e32 v143, 31, v142
	v_lshlrev_b64 v[128:129], 5, v[142:143]
	v_lshl_add_u64 v[132:133], s[4:5], 0, v[128:129]
	v_mov_b32_e32 v128, 0
	v_mov_b32_e32 v129, 0
	v_mov_b32_e32 v130, 0
	v_mov_b32_e32 v131, 0
	s_nop 0
	v_mov_b32_e32 v132, v192
	v_mov_b32_e32 v133, 0
	v_mov_b32_e32 v134, 0
	v_mov_b32_e32 v135, 0
	s_mov_b32 s0, 0x3727c5ac
	s_mov_b32 s18, 0x3a000000
	s_mov_b32 s11, 0x800000
	s_mov_b64 s[20:21], s[16:17]
	s_waitcnt vmcnt(0)
	v_mov_b32_e32 v144, v133
	v_mov_b32_e32 v145, v134
	v_mov_b32_e32 v133, v135
	v_pk_add_f32 v[150:151], v[144:145], v[132:133]
	v_or_b32_e32 v144, 16, v142
	v_mov_b32_e32 v132, v130
	v_mov_b32_e32 v133, v128
	v_mov_b32_e32 v128, v131
	v_ashrrev_i32_e32 v145, 31, v144
	v_pk_add_f32 v[152:153], v[132:133], v[128:129]
	v_lshlrev_b64 v[128:129], 5, v[144:145]
	v_lshl_add_u64 v[132:133], s[4:5], 0, v[128:129]
	v_mov_b32_e32 v128, 0
	v_mov_b32_e32 v129, 0
	v_mov_b32_e32 v130, 0
	v_mov_b32_e32 v131, 0
	s_nop 0
	v_mov_b32_e32 v132, v193
	v_mov_b32_e32 v133, 0
	v_mov_b32_e32 v134, 0
	v_mov_b32_e32 v135, 0
	s_waitcnt vmcnt(0)
	v_mov_b32_e32 v154, v133
	v_mov_b32_e32 v155, v134
	v_mov_b32_e32 v133, v135
	v_pk_add_f32 v[132:133], v[154:155], v[132:133]
	v_mov_b32_e32 v134, v130
	v_mov_b32_e32 v135, v128
	v_mov_b32_e32 v128, v131
	v_pk_add_f32 v[128:129], v[134:135], v[128:129]
	v_mov_b32_e32 v130, v132
	v_mov_b32_e32 v131, v150
	v_mov_b32_e32 v150, v133
	v_pk_add_f32 v[130:131], v[130:131], v[150:151]
	v_mov_b32_e32 v132, v129
	v_mov_b32_e32 v133, v153
	v_pk_add_f32 v[130:131], v[130:131], v[132:133]
	v_mov_b32_e32 v129, v152
	v_pk_add_f32 v[128:129], v[128:129], v[130:131]
	v_mov_b64_e32 v[150:151], s[0:1]
	v_pk_fma_f32 v[128:129], v[128:129], s[18:19], v[150:151] op_sel_hi:[1,0,0]
	v_or_b32_e32 v152, 32, v142
	v_mul_f32_e32 v130, 0x4b800000, v129
	v_cmp_gt_f32_e64 s[0:1], s11, v129
	v_cmp_gt_f32_e32 vcc, s11, v128
	v_ashrrev_i32_e32 v153, 31, v152
	v_cndmask_b32_e64 v129, v129, v130, s[0:1]
	v_rsq_f32_e32 v129, v129
	s_nop 0
	v_mul_f32_e32 v130, 0x45800000, v129
	v_cndmask_b32_e64 v148, v129, v130, s[0:1]
	v_mul_f32_e32 v129, 0x4b800000, v128
	v_cndmask_b32_e32 v128, v128, v129, vcc
	v_rsq_f32_e32 v128, v128
	v_pk_mul_f32 v[106:107], v[106:107], v[148:149] op_sel_hi:[1,0]
	v_pk_mul_f32 v[104:105], v[104:105], v[148:149] op_sel_hi:[1,0]
	v_pk_mul_f32 v[114:115], v[114:115], v[148:149] op_sel_hi:[1,0]
	v_mul_f32_e32 v129, 0x45800000, v128
	v_cndmask_b32_e32 v146, v128, v129, vcc
	v_lshlrev_b64 v[128:129], 5, v[152:153]
	v_lshl_add_u64 v[132:133], s[4:5], 0, v[128:129]
	v_mov_b32_e32 v128, 0
	v_mov_b32_e32 v129, 0
	v_mov_b32_e32 v130, 0
	v_mov_b32_e32 v131, 0
	s_nop 0
	v_mov_b32_e32 v132, v194
	v_mov_b32_e32 v133, 0
	v_mov_b32_e32 v134, 0
	v_mov_b32_e32 v135, 0
	v_cvt_pk_bf16_f32 v104, v104, v105
	v_cvt_pk_bf16_f32 v105, v106, v107
	v_pk_mul_f32 v[90:91], v[90:91], v[146:147] op_sel_hi:[1,0]
	v_pk_mul_f32 v[88:89], v[88:89], v[146:147] op_sel_hi:[1,0]
	v_pk_mul_f32 v[112:113], v[112:113], v[148:149] op_sel_hi:[1,0]
	v_cvt_pk_bf16_f32 v88, v88, v89
	v_cvt_pk_bf16_f32 v89, v90, v91
	v_pk_mul_f32 v[98:99], v[98:99], v[146:147] op_sel_hi:[1,0]
	v_pk_mul_f32 v[96:97], v[96:97], v[146:147] op_sel_hi:[1,0]
	v_cvt_pk_bf16_f32 v112, v112, v113
	v_cvt_pk_bf16_f32 v113, v114, v115
	v_cvt_pk_bf16_f32 v96, v96, v97
	v_cvt_pk_bf16_f32 v97, v98, v99
	v_pk_mul_f32 v[126:127], v[126:127], v[148:149] op_sel_hi:[1,0]
	v_pk_mul_f32 v[124:125], v[124:125], v[148:149] op_sel_hi:[1,0]
	v_pk_mul_f32 v[122:123], v[122:123], v[148:149] op_sel_hi:[1,0]
	v_pk_mul_f32 v[120:121], v[120:121], v[148:149] op_sel_hi:[1,0]
	v_pk_mul_f32 v[106:107], v[118:119], v[146:147] op_sel_hi:[1,0]
	v_pk_mul_f32 v[110:111], v[110:111], v[146:147] op_sel_hi:[1,0]
	v_pk_mul_f32 v[108:109], v[108:109], v[146:147] op_sel_hi:[1,0]
	v_cvt_pk_bf16_f32 v124, v124, v125
	v_cvt_pk_bf16_f32 v125, v126, v127
	v_cvt_pk_bf16_f32 v120, v120, v121
	v_cvt_pk_bf16_f32 v121, v122, v123
	s_waitcnt vmcnt(0)
	v_mov_b32_e32 v154, v133
	v_mov_b32_e32 v155, v134
	v_mov_b32_e32 v133, v135
	v_pk_add_f32 v[174:175], v[154:155], v[132:133]
	v_or_b32_e32 v154, 48, v142
	v_mov_b32_e32 v132, v130
	v_mov_b32_e32 v133, v128
	v_mov_b32_e32 v128, v131
	v_ashrrev_i32_e32 v155, 31, v154
	v_pk_add_f32 v[176:177], v[132:133], v[128:129]
	v_lshlrev_b64 v[128:129], 5, v[154:155]
	v_lshl_add_u64 v[132:133], s[4:5], 0, v[128:129]
	v_mov_b32_e32 v128, 0
	v_mov_b32_e32 v129, 0
	v_mov_b32_e32 v130, 0
	v_mov_b32_e32 v131, 0
	s_nop 0
	v_mov_b32_e32 v132, v195
	v_mov_b32_e32 v133, 0
	v_mov_b32_e32 v134, 0
	v_mov_b32_e32 v135, 0
	s_waitcnt vmcnt(0)
; DEV bf16x8 pack8(f32x4 a, f32x4 b) { u32x4 w; w.x = cvt_pk_bf16(a[0], a[1]); w.y = cvt_pk_bf16(a[2], a[3]); w.z = cvt_pk_bf16(b[0], b[1]); w.w = cvt_pk_bf16(b[2], b[3]); return __builtin_bit_cast(bf16x8, w); }
; DEV u32x2 pack4(f32x4 a) { u32x2 w; w.x = cvt_pk_bf16(a[0], a[1]); w.y = cvt_pk_bf16(a[2], a[3]); return w; }
; DEV f32x4 gelu4(f32x4 v) { f32x2 a = gelu_pk((f32x2){v[0], v[1]}), b = gelu_pk((f32x2){v[2], v[3]}); return (f32x4){a.x, a.y, b.x, b.y}; }
; template <int ACT, bool PERM>
; DEV void store_bf16_tile(AccRef acc, u16* O, int ld, int row0, int col0, const float* ss) {
;     float rsv[2][4];
; #pragma unroll
;     for (int ai = 0; ai < 2; ++ai)
; #pragma unroll
;         for (int m = 0; m < 4; ++m) rsv[ai][m] = ss ? rowscale(ss, row0 + ai * 128 + m * 16) : 1.0f;
; #pragma unroll
;     for (int ai = 0; ai < 2; ++ai)
; #pragma unroll
;         for (int m = 0; m < 4; ++m) { u16* rowp = O + (size_t)(row0 + ai * 128 + m * 16) * ld + col0; const float rs = rsv[ai][m];
; #pragma unroll
;             for (int bj = 0; bj < 2; ++bj) { f32x4 v0 = acc[ai][bj][m][0] * rs, v1 = acc[ai][bj][m][1] * rs; if (ACT == 1) { v0 = gelu4(v0); v1 = gelu4(v1); }
;                 if (PERM) *(u32x4*)(rowp + bj * 128) = __builtin_bit_cast(u32x4, pack8(v0, v1));
;                 else { *(u32x2*)(rowp + bj * 128) = pack4(v0); *(u32x2*)(rowp + bj * 128 + 16) = pack4(v1); } } }
; }
	v_mov_b32_e32 v178, v133
	v_mov_b32_e32 v179, v134
	v_mov_b32_e32 v133, v135
	v_pk_add_f32 v[132:133], v[178:179], v[132:133]
	v_mov_b32_e32 v134, v130
	v_mov_b32_e32 v135, v128
	v_mov_b32_e32 v128, v131
	v_pk_add_f32 v[128:129], v[134:135], v[128:129]
	v_mov_b32_e32 v130, v132
	v_mov_b32_e32 v131, v174
	v_mov_b32_e32 v174, v133
	v_pk_add_f32 v[130:131], v[130:131], v[174:175]
	v_mov_b32_e32 v132, v129
	v_mov_b32_e32 v133, v177
	v_pk_add_f32 v[130:131], v[130:131], v[132:133]
	v_mov_b32_e32 v129, v176
	v_pk_add_f32 v[128:129], v[128:129], v[130:131]
	v_add_u32_e32 v174, 0x80, v142
	v_pk_fma_f32 v[128:129], v[128:129], s[18:19], v[150:151] op_sel_hi:[1,0,0]
	v_ashrrev_i32_e32 v175, 31, v174
	v_mul_f32_e32 v130, 0x4b800000, v129
	v_cmp_gt_f32_e64 s[0:1], s11, v129
	v_cmp_gt_f32_e32 vcc, s11, v128
	s_nop 0
	v_cndmask_b32_e64 v129, v129, v130, s[0:1]
	v_rsq_f32_e32 v129, v129
	s_nop 0
	v_mul_f32_e32 v130, 0x45800000, v129
	v_cndmask_b32_e64 v158, v129, v130, s[0:1]
	v_mul_f32_e32 v129, 0x4b800000, v128
	v_cndmask_b32_e32 v128, v128, v129, vcc
	v_rsq_f32_e32 v128, v128
	v_pk_mul_f32 v[74:75], v[74:75], v[158:159] op_sel_hi:[1,0]
	v_pk_mul_f32 v[72:73], v[72:73], v[158:159] op_sel_hi:[1,0]
	v_pk_mul_f32 v[82:83], v[82:83], v[158:159] op_sel_hi:[1,0]
	v_mul_f32_e32 v129, 0x45800000, v128
	v_cndmask_b32_e32 v156, v128, v129, vcc
	v_lshlrev_b64 v[128:129], 5, v[174:175]
	v_lshl_add_u64 v[132:133], s[4:5], 0, v[128:129]
	v_mov_b32_e32 v128, 0
	v_mov_b32_e32 v129, 0
	v_mov_b32_e32 v130, 0
	v_mov_b32_e32 v131, 0
	s_nop 0
	v_mov_b32_e32 v132, v196
	v_mov_b32_e32 v133, 0
	v_mov_b32_e32 v134, 0
	v_mov_b32_e32 v135, 0
	v_cvt_pk_bf16_f32 v72, v72, v73
	v_cvt_pk_bf16_f32 v73, v74, v75
	v_pk_mul_f32 v[66:67], v[66:67], v[156:157] op_sel_hi:[1,0]
	v_pk_mul_f32 v[64:65], v[64:65], v[156:157] op_sel_hi:[1,0]
	v_pk_mul_f32 v[80:81], v[80:81], v[158:159] op_sel_hi:[1,0]
	v_cvt_pk_bf16_f32 v64, v64, v65
	v_cvt_pk_bf16_f32 v65, v66, v67
	v_cvt_pk_bf16_f32 v80, v80, v81
	v_cvt_pk_bf16_f32 v81, v82, v83
	v_pk_mul_f32 v[90:91], v[102:103], v[158:159] op_sel_hi:[1,0]
	v_pk_mul_f32 v[94:95], v[94:95], v[158:159] op_sel_hi:[1,0]
	v_pk_mul_f32 v[92:93], v[92:93], v[158:159] op_sel_hi:[1,0]
	v_pk_mul_f32 v[74:75], v[86:87], v[156:157] op_sel_hi:[1,0]
	v_pk_mul_f32 v[78:79], v[78:79], v[156:157] op_sel_hi:[1,0]
	v_pk_mul_f32 v[76:77], v[76:77], v[156:157] op_sel_hi:[1,0]
	v_pk_mul_f32 v[70:71], v[70:71], v[156:157] op_sel_hi:[1,0]
	v_pk_mul_f32 v[68:69], v[68:69], v[156:157] op_sel_hi:[1,0]
	s_waitcnt vmcnt(0)
	v_mov_b32_e32 v176, v133
	v_mov_b32_e32 v177, v134
	v_mov_b32_e32 v133, v135
	v_pk_add_f32 v[178:179], v[176:177], v[132:133]
	v_add_u32_e32 v176, 0x90, v142
	v_mov_b32_e32 v132, v130
	v_mov_b32_e32 v133, v128
	v_mov_b32_e32 v128, v131
	v_ashrrev_i32_e32 v177, 31, v176
	v_pk_add_f32 v[180:181], v[132:133], v[128:129]
	v_lshlrev_b64 v[128:129], 5, v[176:177]
	v_lshl_add_u64 v[132:133], s[4:5], 0, v[128:129]
	v_mov_b32_e32 v128, 0
	v_mov_b32_e32 v129, 0
	v_mov_b32_e32 v130, 0
	v_mov_b32_e32 v131, 0
	s_nop 0
	v_mov_b32_e32 v132, v197
	v_mov_b32_e32 v133, 0
	v_mov_b32_e32 v134, 0
	v_mov_b32_e32 v135, 0
	v_cvt_pk_bf16_f32 v68, v68, v69
	v_cvt_pk_bf16_f32 v69, v70, v71
	s_waitcnt vmcnt(0)
	v_mov_b32_e32 v182, v133
	v_mov_b32_e32 v183, v134
	v_mov_b32_e32 v133, v135
	v_pk_add_f32 v[132:133], v[182:183], v[132:133]
	v_mov_b32_e32 v134, v130
	v_mov_b32_e32 v135, v128
	v_mov_b32_e32 v128, v131
	v_pk_add_f32 v[128:129], v[134:135], v[128:129]
	v_mov_b32_e32 v130, v132
	v_mov_b32_e32 v131, v178
	v_mov_b32_e32 v178, v133
	v_pk_add_f32 v[130:131], v[130:131], v[178:179]
	v_mov_b32_e32 v132, v129
	v_mov_b32_e32 v133, v181
	v_pk_add_f32 v[130:131], v[130:131], v[132:133]
	v_mov_b32_e32 v129, v180
	v_pk_add_f32 v[128:129], v[128:129], v[130:131]
	v_add_u32_e32 v182, 0xa0, v142
	v_pk_fma_f32 v[128:129], v[128:129], s[18:19], v[150:151] op_sel_hi:[1,0,0]
	v_ashrrev_i32_e32 v183, 31, v182
	v_mul_f32_e32 v130, 0x4b800000, v129
	v_cmp_gt_f32_e64 s[0:1], s11, v129
	v_cmp_gt_f32_e32 vcc, s11, v128
	s_nop 0
	v_cndmask_b32_e64 v129, v129, v130, s[0:1]
	v_rsq_f32_e32 v129, v129
	s_nop 0
	v_mul_f32_e32 v130, 0x45800000, v129
	v_cndmask_b32_e64 v180, v129, v130, s[0:1]
	v_mul_f32_e32 v129, 0x4b800000, v128
	v_cndmask_b32_e32 v128, v128, v129, vcc
	v_rsq_f32_e32 v128, v128
	v_pk_mul_f32 v[42:43], v[42:43], v[180:181] op_sel_hi:[1,0]
	v_pk_mul_f32 v[40:41], v[40:41], v[180:181] op_sel_hi:[1,0]
	v_pk_mul_f32 v[50:51], v[50:51], v[180:181] op_sel_hi:[1,0]
	v_mul_f32_e32 v129, 0x45800000, v128
	v_cndmask_b32_e32 v178, v128, v129, vcc
	v_lshlrev_b64 v[128:129], 5, v[182:183]
	v_lshl_add_u64 v[132:133], s[4:5], 0, v[128:129]
	v_mov_b32_e32 v128, 0
	v_mov_b32_e32 v129, 0
	v_mov_b32_e32 v130, 0
	v_mov_b32_e32 v131, 0
	s_nop 0
	v_mov_b32_e32 v132, v214
	v_mov_b32_e32 v133, 0
	v_mov_b32_e32 v134, 0
	v_mov_b32_e32 v135, 0
	v_cvt_pk_bf16_f32 v40, v40, v41
	v_cvt_pk_bf16_f32 v41, v42, v43
	v_pk_mul_f32 v[26:27], v[26:27], v[178:179] op_sel_hi:[1,0]
	v_pk_mul_f32 v[24:25], v[24:25], v[178:179] op_sel_hi:[1,0]
	v_pk_mul_f32 v[48:49], v[48:49], v[180:181] op_sel_hi:[1,0]
	v_cvt_pk_bf16_f32 v24, v24, v25
	v_cvt_pk_bf16_f32 v25, v26, v27
	v_pk_mul_f32 v[34:35], v[34:35], v[178:179] op_sel_hi:[1,0]
	v_pk_mul_f32 v[32:33], v[32:33], v[178:179] op_sel_hi:[1,0]
	v_cvt_pk_bf16_f32 v48, v48, v49
	v_cvt_pk_bf16_f32 v49, v50, v51
	v_cvt_pk_bf16_f32 v32, v32, v33
	v_cvt_pk_bf16_f32 v33, v34, v35
	v_pk_mul_f32 v[62:63], v[62:63], v[180:181] op_sel_hi:[1,0]
	v_pk_mul_f32 v[60:61], v[60:61], v[180:181] op_sel_hi:[1,0]
	v_pk_mul_f32 v[58:59], v[58:59], v[180:181] op_sel_hi:[1,0]
	v_pk_mul_f32 v[56:57], v[56:57], v[180:181] op_sel_hi:[1,0]
	v_pk_mul_f32 v[42:43], v[54:55], v[178:179] op_sel_hi:[1,0]
	v_pk_mul_f32 v[46:47], v[46:47], v[178:179] op_sel_hi:[1,0]
	v_pk_mul_f32 v[44:45], v[44:45], v[178:179] op_sel_hi:[1,0]
	v_cvt_pk_bf16_f32 v60, v60, v61
	v_cvt_pk_bf16_f32 v61, v62, v63
	v_cvt_pk_bf16_f32 v56, v56, v57
	v_cvt_pk_bf16_f32 v57, v58, v59
	s_waitcnt vmcnt(0)
; DEV bf16x8 pack8(f32x4 a, f32x4 b) { u32x4 w; w.x = cvt_pk_bf16(a[0], a[1]); w.y = cvt_pk_bf16(a[2], a[3]); w.z = cvt_pk_bf16(b[0], b[1]); w.w = cvt_pk_bf16(b[2], b[3]); return __builtin_bit_cast(bf16x8, w); }
; DEV u32x2 pack4(f32x4 a) { u32x2 w; w.x = cvt_pk_bf16(a[0], a[1]); w.y = cvt_pk_bf16(a[2], a[3]); return w; }
; DEV f32x4 gelu4(f32x4 v) { f32x2 a = gelu_pk((f32x2){v[0], v[1]}), b = gelu_pk((f32x2){v[2], v[3]}); return (f32x4){a.x, a.y, b.x, b.y}; }
; template <int ACT, bool PERM>
; DEV void store_bf16_tile(AccRef acc, u16* O, int ld, int row0, int col0, const float* ss) {
;     float rsv[2][4];
; #pragma unroll
;     for (int ai = 0; ai < 2; ++ai)
; #pragma unroll
;         for (int m = 0; m < 4; ++m) rsv[ai][m] = ss ? rowscale(ss, row0 + ai * 128 + m * 16) : 1.0f;
; #pragma unroll
;     for (int ai = 0; ai < 2; ++ai)
; #pragma unroll
;         for (int m = 0; m < 4; ++m) { u16* rowp = O + (size_t)(row0 + ai * 128 + m * 16) * ld + col0; const float rs = rsv[ai][m];
; #pragma unroll
;             for (int bj = 0; bj < 2; ++bj) { f32x4 v0 = acc[ai][bj][m][0] * rs, v1 = acc[ai][bj][m][1] * rs; if (ACT == 1) { v0 = gelu4(v0); v1 = gelu4(v1); }
;                 if (PERM) *(u32x4*)(rowp + bj * 128) = __builtin_bit_cast(u32x4, pack8(v0, v1));
;                 else { *(u32x2*)(rowp + bj * 128) = pack4(v0); *(u32x2*)(rowp + bj * 128 + 16) = pack4(v1); } } }
; }
	v_mov_b32_e32 v184, v133
	v_mov_b32_e32 v185, v134
	v_mov_b32_e32 v133, v135
	v_pk_add_f32 v[188:189], v[184:185], v[132:133]
	v_add_u32_e32 v184, 0xb0, v142
	v_mov_b32_e32 v132, v130
	v_mov_b32_e32 v133, v128
	v_mov_b32_e32 v128, v131
	v_ashrrev_i32_e32 v185, 31, v184
	v_pk_add_f32 v[186:187], v[132:133], v[128:129]
	v_lshlrev_b64 v[128:129], 5, v[184:185]
	v_lshl_add_u64 v[132:133], s[4:5], 0, v[128:129]
	v_mov_b32_e32 v128, 0
	v_mov_b32_e32 v129, 0
	v_mov_b32_e32 v130, 0
	v_mov_b32_e32 v131, 0
	s_nop 0
	v_mov_b32_e32 v132, v215
	v_mov_b32_e32 v133, 0
	v_mov_b32_e32 v134, 0
	v_mov_b32_e32 v135, 0
	s_waitcnt vmcnt(0)
	v_mov_b32_e32 v190, v133
	v_mov_b32_e32 v191, v134
	v_mov_b32_e32 v133, v135
	v_pk_add_f32 v[132:133], v[190:191], v[132:133]
	v_mov_b32_e32 v134, v130
	v_mov_b32_e32 v135, v128
	v_mov_b32_e32 v128, v131
	v_pk_add_f32 v[128:129], v[134:135], v[128:129]
	v_mov_b32_e32 v130, v132
	v_mov_b32_e32 v131, v188
	v_mov_b32_e32 v188, v133
	v_pk_add_f32 v[130:131], v[130:131], v[188:189]
	v_mov_b32_e32 v132, v129
	v_mov_b32_e32 v133, v187
	v_pk_add_f32 v[130:131], v[130:131], v[132:133]
	v_mov_b32_e32 v129, v186
	v_pk_add_f32 v[128:129], v[128:129], v[130:131]
	v_lshl_or_b32 v132, s40, 8, v157
	v_pk_fma_f32 v[128:129], v[128:129], s[18:19], v[150:151] op_sel_hi:[1,0,0]
	v_ashrrev_i32_e32 v133, 31, v132
	v_mul_f32_e32 v130, 0x4b800000, v129
	v_cmp_gt_f32_e64 s[0:1], s11, v129
	v_lshlrev_b64 v[134:135], 10, v[142:143]
	v_cmp_gt_f32_e32 vcc, s11, v128
	v_cndmask_b32_e64 v129, v129, v130, s[0:1]
	v_rsq_f32_e32 v129, v129
	s_mov_b32 s40, s10
	s_mov_b64 s[18:19], s[14:15]
	v_mul_f32_e32 v130, 0x45800000, v129
	v_cndmask_b32_e64 v130, v129, v130, s[0:1]
	v_readlane_b32 s0, v250, 11
	v_readlane_b32 s1, v250, 12
	v_mul_f32_e32 v129, 0x4b800000, v128
	v_cndmask_b32_e32 v128, v128, v129, vcc
	v_lshl_add_u64 v[132:133], v[132:133], 1, s[0:1]
	v_lshl_add_u64 v[134:135], v[132:133], 0, v[134:135]
	global_store_dwordx2 v[134:135], v[104:105], off offset:288
	v_lshlrev_b64 v[104:105], 10, v[144:145]
	v_lshl_add_u64 v[104:105], v[132:133], 0, v[104:105]
	global_store_dwordx2 v[104:105], v[88:89], off offset:288
	v_lshlrev_b64 v[88:89], 10, v[152:153]
	v_lshl_add_u64 v[88:89], v[132:133], 0, v[88:89]
	global_store_dwordx2 v[88:89], v[72:73], off offset:288
	v_lshlrev_b64 v[72:73], 10, v[154:155]
	v_lshl_add_u64 v[72:73], v[132:133], 0, v[72:73]
	v_rsq_f32_e32 v128, v128
	global_store_dwordx2 v[72:73], v[64:65], off offset:288
	v_lshlrev_b64 v[64:65], 10, v[174:175]
	v_lshl_add_u64 v[64:65], v[132:133], 0, v[64:65]
	global_store_dwordx2 v[64:65], v[40:41], off offset:288
	v_lshlrev_b64 v[40:41], 10, v[176:177]
	v_lshl_add_u64 v[40:41], v[132:133], 0, v[40:41]
	v_mul_f32_e32 v129, 0x45800000, v128
	global_store_dwordx2 v[40:41], v[24:25], off offset:288
	v_lshlrev_b64 v[24:25], 10, v[182:183]
	v_pk_mul_f32 v[18:19], v[18:19], v[130:131] op_sel_hi:[1,0]
	v_pk_mul_f32 v[16:17], v[16:17], v[130:131] op_sel_hi:[1,0]
	v_pk_mul_f32 v[10:11], v[10:11], v[130:131] op_sel_hi:[1,0]
	v_pk_mul_f32 v[8:9], v[8:9], v[130:131] op_sel_hi:[1,0]
	v_cndmask_b32_e32 v128, v128, v129, vcc
	v_lshl_add_u64 v[24:25], v[132:133], 0, v[24:25]
	v_cvt_pk_bf16_f32 v16, v16, v17
	v_cvt_pk_bf16_f32 v17, v18, v19
	v_cvt_pk_bf16_f32 v8, v8, v9
	v_cvt_pk_bf16_f32 v9, v10, v11
	global_store_dwordx2 v[134:135], v[112:113], off offset:256
	v_pk_mul_f32 v[112:113], v[116:117], v[146:147] op_sel_hi:[1,0]
	global_store_dwordx2 v[104:105], v[96:97], off offset:256
	v_pk_mul_f32 v[96:97], v[100:101], v[158:159] op_sel_hi:[1,0]
	global_store_dwordx2 v[88:89], v[80:81], off offset:256
	v_pk_mul_f32 v[80:81], v[84:85], v[156:157] op_sel_hi:[1,0]
	global_store_dwordx2 v[64:65], v[48:49], off offset:256
	v_pk_mul_f32 v[48:49], v[52:53], v[178:179] op_sel_hi:[1,0]
	global_store_dwordx2 v[40:41], v[32:33], off offset:256
	v_pk_mul_f32 v[26:27], v[38:39], v[130:131] op_sel_hi:[1,0]
	v_pk_mul_f32 v[32:33], v[36:37], v[130:131] op_sel_hi:[1,0]
	v_pk_mul_f32 v[30:31], v[30:31], v[130:131] op_sel_hi:[1,0]
	v_pk_mul_f32 v[28:29], v[28:29], v[130:131] op_sel_hi:[1,0]
	global_store_dwordx2 v[24:25], v[16:17], off offset:256
	global_store_dwordx2 v[24:25], v[8:9], off offset:288
	v_lshlrev_b64 v[8:9], 10, v[184:185]
	v_pk_mul_f32 v[10:11], v[22:23], v[128:129] op_sel_hi:[1,0]
	v_pk_mul_f32 v[16:17], v[20:21], v[128:129] op_sel_hi:[1,0]
	v_pk_mul_f32 v[14:15], v[14:15], v[128:129] op_sel_hi:[1,0]
	v_pk_mul_f32 v[12:13], v[12:13], v[128:129] op_sel_hi:[1,0]
	v_pk_mul_f32 v[6:7], v[6:7], v[128:129] op_sel_hi:[1,0]
	v_pk_mul_f32 v[4:5], v[4:5], v[128:129] op_sel_hi:[1,0]
	v_pk_mul_f32 v[2:3], v[2:3], v[128:129] op_sel_hi:[1,0]
	v_pk_mul_f32 v[0:1], v[0:1], v[128:129] op_sel_hi:[1,0]
	v_cvt_pk_bf16_f32 v112, v112, v113
	v_cvt_pk_bf16_f32 v113, v106, v107
	v_cvt_pk_bf16_f32 v106, v108, v109
	v_cvt_pk_bf16_f32 v107, v110, v111
	v_cvt_pk_bf16_f32 v96, v96, v97
	v_cvt_pk_bf16_f32 v97, v90, v91
	v_cvt_pk_bf16_f32 v90, v92, v93
	v_cvt_pk_bf16_f32 v91, v94, v95
	v_cvt_pk_bf16_f32 v80, v80, v81
	v_cvt_pk_bf16_f32 v81, v74, v75
	v_cvt_pk_bf16_f32 v74, v76, v77
	v_cvt_pk_bf16_f32 v75, v78, v79
	v_cvt_pk_bf16_f32 v48, v48, v49
	v_cvt_pk_bf16_f32 v49, v42, v43
	v_cvt_pk_bf16_f32 v42, v44, v45
	v_cvt_pk_bf16_f32 v43, v46, v47
	v_cvt_pk_bf16_f32 v32, v32, v33
	v_cvt_pk_bf16_f32 v33, v26, v27
	v_cvt_pk_bf16_f32 v26, v28, v29
	v_cvt_pk_bf16_f32 v27, v30, v31
	v_lshl_add_u64 v[8:9], v[132:133], 0, v[8:9]
	v_cvt_pk_bf16_f32 v16, v16, v17
	v_cvt_pk_bf16_f32 v17, v10, v11
	v_cvt_pk_bf16_f32 v10, v12, v13
	v_cvt_pk_bf16_f32 v11, v14, v15
	v_cvt_pk_bf16_f32 v4, v4, v5
	v_cvt_pk_bf16_f32 v5, v6, v7
	v_cvt_pk_bf16_f32 v0, v0, v1
	v_cvt_pk_bf16_f32 v1, v2, v3
	s_and_b64 vcc, exec, s[6:7]
	s_mov_b32 s0, s12
	global_store_dwordx2 v[134:135], v[124:125], off
	global_store_dwordx2 v[134:135], v[120:121], off offset:32
	global_store_dwordx2 v[104:105], v[112:113], off
	global_store_dwordx2 v[104:105], v[106:107], off offset:32
	global_store_dwordx2 v[88:89], v[96:97], off
	global_store_dwordx2 v[88:89], v[90:91], off offset:32
	global_store_dwordx2 v[72:73], v[80:81], off
	global_store_dwordx2 v[72:73], v[74:75], off offset:32
	global_store_dwordx2 v[72:73], v[68:69], off offset:256
	global_store_dwordx2 v[64:65], v[60:61], off
	global_store_dwordx2 v[64:65], v[56:57], off offset:32
	global_store_dwordx2 v[40:41], v[48:49], off
	global_store_dwordx2 v[40:41], v[42:43], off offset:32
	global_store_dwordx2 v[24:25], v[32:33], off
	global_store_dwordx2 v[24:25], v[26:27], off offset:32
	global_store_dwordx2 v[8:9], v[16:17], off
	global_store_dwordx2 v[8:9], v[10:11], off offset:32
	global_store_dwordx2 v[8:9], v[4:5], off offset:256
	global_store_dwordx2 v[8:9], v[0:1], off offset:288
	s_cbranch_vccz .LBB0_337
	s_waitcnt vmcnt(0)
	s_cmpk_gt_u32 s25, 0xff
	s_cbranch_scc1 .LBB0_348
	s_barrier

; #define PG8_STAGE(bufoff, gbase, voff) do { _Pragma("unroll") for (int _i = 0; _i < 2; ++_i) \
;         __builtin_amdgcn_global_load_lds((const unsigned*)((const char*)(gbase) + (voff)[_i]), (LAS unsigned*)(lds + (bufoff) + ldsw + _i * 8192), 16, 0, 0); } while (0)
; #define PG8_LDA(dst, b, h) do { _Pragma("unroll") for (int m = 0; m < 4; ++m) _Pragma("unroll") for (int k = 0; k < 2; ++k) dst[m][k] = *(const LAS bf16x8*)(lds + PG8_SA(b, h) + aoff + m * 2048 + k * 1024); } while (0)
; #define PG8_LDB(dst, b, h) do { _Pragma("unroll") for (int n = 0; n < 2; ++n) _Pragma("unroll") for (int k = 0; k < 2; ++k) dst[n][k] = *(const LAS bf16x8*)(lds + PG8_SB(b, h) + boff + n * 2048 + k * 1024); } while (0)
; #define PG8_MMA(ai, bj, At, Bt) do { __builtin_amdgcn_s_setprio(1); _Pragma("unroll") for (int m = 0; m < 4; ++m) _Pragma("unroll") for (int n = 0; n < 2; ++n) _Pragma("unroll") for (int k = 0; k < 2; ++k) \
;         acc[ai][bj][m][n] = __builtin_amdgcn_mfma_f32_16x16x32_bf16(Bt[n][k], At[m][k], acc[ai][bj][m][n], 0, 0, 0); __builtin_amdgcn_s_setprio(0); } while (0)
; #define PG8_WAIT_L(n) asm volatile("s_waitcnt lgkmcnt(" #n ")" ::: "memory")
; #define PG8_BAR __builtin_amdgcn_s_barrier()
; #define PG8_SCHED __builtin_amdgcn_sched_barrier(0)
; template <class Epi>
; DEV void gemm_phase(LAS unsigned char* lds, const Gemm g, const StaticOrder& S, const Epi& E) {
;     ...
;             PG8_LDB(B0, 0, 0); PG8_SCHED; PG8_LDA(At, 0, 0); PG8_STAGE(PG8_SA(1, 1), a1 + hstep, voffA);
;             PG8_WAIT_L(8); PG8_BAR; PG8_WAIT_L(0); PG8_MMA(0, 0, At, B0); PG8_BAR; PG8_SCHED;
;             PG8_LDB(B1, 0, 1); PG8_STAGE(PG8_SB(0, 0), b2, voffB);
;             PG8_BAR; PG8_WAIT_L(0); PG8_MMA(0, 1, At, B1); PG8_BAR;
;             PG8_LDA(At, 0, 1); PG8_STAGE(PG8_SA(0, 0), a2, voffA);
;             PG8_BAR; PG8_WAIT_L(0); PG8_MMA(1, 0, At, B0); PG8_BAR; PG8_SCHED;
.LBB0_588:
	s_add_u32 s16, s14, 0xfff80080
	s_addc_u32 s17, s15, -1
	s_add_i32 s41, 0, 0x10000
	v_add_u32_e32 v154, s41, v167
	ds_read_b128 v[128:131], v154
	ds_read_b128 v[132:135], v154 offset:1024
	ds_read_b128 v[150:153], v154 offset:2048
	ds_read_b128 v[174:177], v154 offset:3072
	s_cmp_eq_u32 s40, 28
	s_cselect_b32 s19, s1, s17
	s_cselect_b32 s18, s9, s16
	s_cselect_b32 s17, s7, s37
	s_cselect_b32 s16, s35, s36
	v_lshl_add_u64 v[154:155], s[14:15], 0, v[146:147]
	s_add_i32 m0, s24, 0xc000
	ds_read_b128 v[182:185], v219
	ds_read_b128 v[190:193], v219 offset:1024
	ds_read_b128 v[194:197], v219 offset:2048
	ds_read_b128 v[220:223], v219 offset:3072
	ds_read_b128 v[224:227], v219 offset:4096
	ds_read_b128 v[228:231], v219 offset:5120
	ds_read_b128 v[232:235], v219 offset:6144
	ds_read_b128 v[236:239], v219 offset:7168
	global_load_lds_dwordx4 v[154:155], off
	v_lshl_add_u64 v[154:155], s[14:15], 0, v[148:149]
	s_add_i32 m0, s24, 0xe000
	s_nop 0
	global_load_lds_dwordx4 v[154:155], off
	s_waitcnt lgkmcnt(8)
	s_barrier
	s_waitcnt lgkmcnt(0)
	s_setprio 1
	s_waitcnt lgkmcnt(0)
	v_mfma_f32_16x16x32_bf16 v[124:127], v[128:131], v[182:185], v[124:127]
	v_mfma_f32_16x16x32_bf16 v[120:123], v[150:153], v[182:185], v[120:123]
	v_mfma_f32_16x16x32_bf16 v[108:111], v[128:131], v[194:197], v[108:111]
	v_mfma_f32_16x16x32_bf16 v[104:107], v[150:153], v[194:197], v[104:107]
	v_mfma_f32_16x16x32_bf16 v[92:95], v[128:131], v[224:227], v[92:95]
	v_mfma_f32_16x16x32_bf16 v[88:91], v[150:153], v[224:227], v[88:91]
	v_mfma_f32_16x16x32_bf16 v[76:79], v[128:131], v[232:235], v[76:79]
	v_mfma_f32_16x16x32_bf16 v[72:75], v[150:153], v[232:235], v[72:75]
	v_mfma_f32_16x16x32_bf16 v[124:127], v[132:135], v[190:193], v[124:127]
	v_mfma_f32_16x16x32_bf16 v[120:123], v[174:177], v[190:193], v[120:123]
	v_mfma_f32_16x16x32_bf16 v[108:111], v[132:135], v[220:223], v[108:111]
	v_mfma_f32_16x16x32_bf16 v[104:107], v[174:177], v[220:223], v[104:107]
	v_mfma_f32_16x16x32_bf16 v[92:95], v[132:135], v[228:231], v[92:95]
	v_mfma_f32_16x16x32_bf16 v[88:91], v[174:177], v[228:231], v[88:91]
	v_mfma_f32_16x16x32_bf16 v[76:79], v[132:135], v[236:239], v[76:79]
	v_mfma_f32_16x16x32_bf16 v[72:75], v[174:177], v[236:239], v[72:75]
	s_setprio 0
	s_barrier
	s_add_i32 s44, 0, 0x14000
	v_add_u32_e32 v154, s44, v167
	s_add_i32 s41, s41, s22
	ds_read_b128 v[240:243], v154
	ds_read_b128 v[244:247], v154 offset:1024
	ds_read_b128 v[186:189], v154 offset:2048
	ds_read_b128 v[214:217], v154 offset:3072
	v_lshl_add_u64 v[154:155], s[16:17], 0, v[140:141]
	s_mov_b32 m0, s41
	v_lshl_add_u64 v[158:159], s[16:17], 0, v[136:137]
	global_load_lds_dwordx4 v[154:155], off
	s_add_i32 m0, s41, 0x2000
	s_nop 0
	global_load_lds_dwordx4 v[158:159], off
	s_barrier
	s_waitcnt lgkmcnt(0)
	s_setprio 1
	s_waitcnt lgkmcnt(0)
	v_mfma_f32_16x16x32_bf16 v[116:119], v[240:243], v[182:185], v[116:119]
	v_mfma_f32_16x16x32_bf16 v[112:115], v[186:189], v[182:185], v[112:115]
	v_mfma_f32_16x16x32_bf16 v[100:103], v[240:243], v[194:197], v[100:103]
	v_mfma_f32_16x16x32_bf16 v[96:99], v[186:189], v[194:197], v[96:99]
	v_mfma_f32_16x16x32_bf16 v[84:87], v[240:243], v[224:227], v[84:87]
	v_mfma_f32_16x16x32_bf16 v[80:83], v[186:189], v[224:227], v[80:83]
	v_mfma_f32_16x16x32_bf16 v[68:71], v[240:243], v[232:235], v[68:71]
	v_mfma_f32_16x16x32_bf16 v[64:67], v[186:189], v[232:235], v[64:67]
	v_mfma_f32_16x16x32_bf16 v[116:119], v[244:247], v[190:193], v[116:119]
	v_mfma_f32_16x16x32_bf16 v[112:115], v[214:217], v[190:193], v[112:115]
	v_mfma_f32_16x16x32_bf16 v[100:103], v[244:247], v[220:223], v[100:103]
	v_mfma_f32_16x16x32_bf16 v[96:99], v[214:217], v[220:223], v[96:99]
	v_mfma_f32_16x16x32_bf16 v[84:87], v[244:247], v[228:231], v[84:87]
	v_mfma_f32_16x16x32_bf16 v[80:83], v[214:217], v[228:231], v[80:83]
	v_mfma_f32_16x16x32_bf16 v[68:71], v[244:247], v[236:239], v[68:71]
	v_mfma_f32_16x16x32_bf16 v[64:67], v[214:217], v[236:239], v[64:67]
	s_setprio 0
	s_mov_b32 m0, s24
	v_lshl_add_u64 v[178:179], s[18:19], 0, v[142:143]
	s_barrier
	ds_read_b128 v[182:185], v219 offset:16384
	ds_read_b128 v[190:193], v219 offset:17408
	ds_read_b128 v[194:197], v219 offset:18432
	ds_read_b128 v[220:223], v219 offset:19456
	ds_read_b128 v[224:227], v219 offset:20480
	ds_read_b128 v[228:231], v219 offset:21504
	ds_read_b128 v[232:235], v219 offset:22528
	ds_read_b128 v[236:239], v219 offset:23552
	global_load_lds_dwordx4 v[178:179], off
	v_lshl_add_u64 v[248:249], s[18:19], 0, v[138:139]
	s_mov_b32 m0, s25
	s_nop 0
	global_load_lds_dwordx4 v[248:249], off
	s_barrier
	s_waitcnt lgkmcnt(0)
	s_setprio 1
	s_waitcnt lgkmcnt(0)
	v_mfma_f32_16x16x32_bf16 v[60:63], v[128:131], v[182:185], v[60:63]
	v_mfma_f32_16x16x32_bf16 v[56:59], v[150:153], v[182:185], v[56:59]
	v_mfma_f32_16x16x32_bf16 v[44:47], v[128:131], v[194:197], v[44:47]
	v_mfma_f32_16x16x32_bf16 v[40:43], v[150:153], v[194:197], v[40:43]
	v_mfma_f32_16x16x32_bf16 v[28:31], v[128:131], v[224:227], v[28:31]
	v_mfma_f32_16x16x32_bf16 v[24:27], v[150:153], v[224:227], v[24:27]
	v_mfma_f32_16x16x32_bf16 v[12:15], v[128:131], v[232:235], v[12:15]
	v_mfma_f32_16x16x32_bf16 v[8:11], v[150:153], v[232:235], v[8:11]
	v_mfma_f32_16x16x32_bf16 v[60:63], v[132:135], v[190:193], v[60:63]
	v_mfma_f32_16x16x32_bf16 v[56:59], v[174:177], v[190:193], v[56:59]
	v_mfma_f32_16x16x32_bf16 v[44:47], v[132:135], v[220:223], v[44:47]
	v_mfma_f32_16x16x32_bf16 v[40:43], v[174:177], v[220:223], v[40:43]
	v_mfma_f32_16x16x32_bf16 v[28:31], v[132:135], v[228:231], v[28:31]
	v_mfma_f32_16x16x32_bf16 v[24:27], v[174:177], v[228:231], v[24:27]
	v_mfma_f32_16x16x32_bf16 v[12:15], v[132:135], v[236:239], v[12:15]
	v_mfma_f32_16x16x32_bf16 v[8:11], v[174:177], v[236:239], v[8:11]
	s_setprio 0
	s_barrier
; #define PG8_STAGE(bufoff, gbase, voff) do { _Pragma("unroll") for (int _i = 0; _i < 2; ++_i) \
;         __builtin_amdgcn_global_load_lds((const unsigned*)((const char*)(gbase) + (voff)[_i]), (LAS unsigned*)(lds + (bufoff) + ldsw + _i * 8192), 16, 0, 0); } while (0)
; #define PG8_LDA(dst, b, h) do { _Pragma("unroll") for (int m = 0; m < 4; ++m) _Pragma("unroll") for (int k = 0; k < 2; ++k) dst[m][k] = *(const LAS bf16x8*)(lds + PG8_SA(b, h) + aoff + m * 2048 + k * 1024); } while (0)
; #define PG8_LDB(dst, b, h) do { _Pragma("unroll") for (int n = 0; n < 2; ++n) _Pragma("unroll") for (int k = 0; k < 2; ++k) dst[n][k] = *(const LAS bf16x8*)(lds + PG8_SB(b, h) + boff + n * 2048 + k * 1024); } while (0)
; #define PG8_MMA(ai, bj, At, Bt) do { __builtin_amdgcn_s_setprio(1); _Pragma("unroll") for (int m = 0; m < 4; ++m) _Pragma("unroll") for (int n = 0; n < 2; ++n) _Pragma("unroll") for (int k = 0; k < 2; ++k) \
;         acc[ai][bj][m][n] = __builtin_amdgcn_mfma_f32_16x16x32_bf16(Bt[n][k], At[m][k], acc[ai][bj][m][n], 0, 0, 0); __builtin_amdgcn_s_setprio(0); } while (0)
; #define PG8_WAIT_V(n) asm volatile("s_waitcnt vmcnt(" #n ")" ::: "memory")
; #define PG8_WAIT_L(n) asm volatile("s_waitcnt lgkmcnt(" #n ")" ::: "memory")
; #define PG8_BAR __builtin_amdgcn_s_barrier()
; #define PG8_SCHED __builtin_amdgcn_sched_barrier(0)
; template <class Epi>
; DEV void gemm_phase(LAS unsigned char* lds, const Gemm g, const StaticOrder& S, const Epi& E) {
;     ...
;             PG8_STAGE(PG8_SB(0, 1), b2 + hstep, voffB);
;             PG8_WAIT_V(6); PG8_BAR; PG8_MMA(1, 1, At, B1); PG8_BAR;
;             PG8_LDB(B0, 1, 0); PG8_SCHED; PG8_LDA(At, 1, 0); PG8_STAGE(PG8_SA(0, 1), a2 + hstep, voffA);
;             PG8_WAIT_L(8); PG8_BAR; PG8_WAIT_L(0); PG8_MMA(0, 0, At, B0); PG8_BAR; PG8_SCHED;
;             PG8_LDB(B1, 1, 1); PG8_STAGE(PG8_SB(1, 0), b3, voffB);
;             PG8_BAR; PG8_WAIT_L(0); PG8_MMA(0, 1, At, B1); PG8_BAR;
;             PG8_LDA(At, 1, 1); PG8_STAGE(PG8_SA(1, 0), a3, voffA);
;             PG8_BAR; PG8_WAIT_L(0); PG8_MMA(1, 0, At, B0); PG8_BAR; PG8_SCHED;
	s_add_u32 s42, s16, 0x80000
	s_addc_u32 s43, s17, 0
	s_add_i32 s41, s44, s22
	v_lshl_add_u64 v[128:129], s[42:43], 0, v[140:141]
	s_mov_b32 m0, s41
	s_nop 0
	global_load_lds_dwordx4 v[128:129], off
	v_lshl_add_u64 v[128:129], s[42:43], 0, v[136:137]
	s_add_i32 m0, s41, 0x2000
	s_nop 0
	global_load_lds_dwordx4 v[128:129], off
	s_waitcnt vmcnt(6)
	s_barrier
	s_setprio 1
	v_mfma_f32_16x16x32_bf16 v[52:55], v[240:243], v[182:185], v[52:55]
	v_mfma_f32_16x16x32_bf16 v[48:51], v[186:189], v[182:185], v[48:51]
	v_mfma_f32_16x16x32_bf16 v[36:39], v[240:243], v[194:197], v[36:39]
	v_mfma_f32_16x16x32_bf16 v[32:35], v[186:189], v[194:197], v[32:35]
	v_mfma_f32_16x16x32_bf16 v[20:23], v[240:243], v[224:227], v[20:23]
	v_mfma_f32_16x16x32_bf16 v[16:19], v[186:189], v[224:227], v[16:19]
	v_mfma_f32_16x16x32_bf16 v[4:7], v[240:243], v[232:235], v[4:7]
	v_mfma_f32_16x16x32_bf16 v[0:3], v[186:189], v[232:235], v[0:3]
	v_mfma_f32_16x16x32_bf16 v[52:55], v[244:247], v[190:193], v[52:55]
	v_mfma_f32_16x16x32_bf16 v[48:51], v[214:217], v[190:193], v[48:51]
	v_mfma_f32_16x16x32_bf16 v[36:39], v[244:247], v[220:223], v[36:39]
	v_mfma_f32_16x16x32_bf16 v[32:35], v[214:217], v[220:223], v[32:35]
	v_mfma_f32_16x16x32_bf16 v[20:23], v[244:247], v[228:231], v[20:23]
	v_mfma_f32_16x16x32_bf16 v[16:19], v[214:217], v[228:231], v[16:19]
	v_mfma_f32_16x16x32_bf16 v[4:7], v[244:247], v[236:239], v[4:7]
	v_mfma_f32_16x16x32_bf16 v[0:3], v[214:217], v[236:239], v[0:3]
	s_setprio 0
	s_add_i32 s41, 0, 0x18000
	v_add_u32_e32 v156, s41, v167
	s_barrier
	ds_read_b128 v[128:131], v156
	ds_read_b128 v[132:135], v156 offset:1024
	ds_read_b128 v[150:153], v156 offset:2048
	ds_read_b128 v[174:177], v156 offset:3072
	s_add_u32 s18, s18, 0x80000
	s_addc_u32 s19, s19, 0
	s_mov_b32 m0, s26
	v_lshl_add_u64 v[232:233], s[18:19], 0, v[142:143]
	ds_read_b128 v[182:185], v219 offset:32768
	ds_read_b128 v[186:189], v219 offset:33792
	ds_read_b128 v[190:193], v219 offset:34816
	ds_read_b128 v[194:197], v219 offset:35840
	ds_read_b128 v[214:217], v219 offset:36864
	ds_read_b128 v[220:223], v219 offset:37888
	ds_read_b128 v[224:227], v219 offset:38912
	ds_read_b128 v[228:231], v219 offset:39936
	global_load_lds_dwordx4 v[232:233], off
	v_lshl_add_u64 v[232:233], s[18:19], 0, v[138:139]
	s_mov_b32 m0, s27
	s_nop 0
	global_load_lds_dwordx4 v[232:233], off
	s_waitcnt lgkmcnt(8)
	s_barrier
	s_waitcnt lgkmcnt(0)
	s_setprio 1
	s_waitcnt lgkmcnt(0)
	v_mfma_f32_16x16x32_bf16 v[124:127], v[128:131], v[182:185], v[124:127]
	v_mfma_f32_16x16x32_bf16 v[120:123], v[150:153], v[182:185], v[120:123]
	v_mfma_f32_16x16x32_bf16 v[108:111], v[128:131], v[190:193], v[108:111]
	v_mfma_f32_16x16x32_bf16 v[104:107], v[150:153], v[190:193], v[104:107]
	v_mfma_f32_16x16x32_bf16 v[92:95], v[128:131], v[214:217], v[92:95]
	v_mfma_f32_16x16x32_bf16 v[88:91], v[150:153], v[214:217], v[88:91]
	v_mfma_f32_16x16x32_bf16 v[76:79], v[128:131], v[224:227], v[76:79]
	v_mfma_f32_16x16x32_bf16 v[72:75], v[150:153], v[224:227], v[72:75]
	v_mfma_f32_16x16x32_bf16 v[124:127], v[132:135], v[186:189], v[124:127]
	v_mfma_f32_16x16x32_bf16 v[120:123], v[174:177], v[186:189], v[120:123]
	v_mfma_f32_16x16x32_bf16 v[108:111], v[132:135], v[194:197], v[108:111]
	v_mfma_f32_16x16x32_bf16 v[104:107], v[174:177], v[194:197], v[104:107]
	v_mfma_f32_16x16x32_bf16 v[92:95], v[132:135], v[220:223], v[92:95]
	v_mfma_f32_16x16x32_bf16 v[88:91], v[174:177], v[220:223], v[88:91]
	v_mfma_f32_16x16x32_bf16 v[76:79], v[132:135], v[228:231], v[76:79]
	v_mfma_f32_16x16x32_bf16 v[72:75], v[174:177], v[228:231], v[72:75]
	s_setprio 0
	s_barrier
	s_add_i32 s18, 0, 0x1c000
	s_add_i32 s19, s41, s22
	v_add_u32_e32 v156, s18, v167
	v_lshl_add_u64 v[154:155], v[154:155], 0, s[2:3]
	s_mov_b32 m0, s19
	ds_read_b128 v[232:235], v156
	ds_read_b128 v[236:239], v156 offset:1024
	ds_read_b128 v[240:243], v156 offset:2048
	ds_read_b128 v[244:247], v156 offset:3072
	global_load_lds_dwordx4 v[154:155], off
	v_lshl_add_u64 v[154:155], v[158:159], 0, s[2:3]
	s_add_i32 m0, s19, 0x2000
	s_nop 0
	global_load_lds_dwordx4 v[154:155], off
	s_barrier
	s_waitcnt lgkmcnt(0)
	s_setprio 1
	s_waitcnt lgkmcnt(0)
	v_mfma_f32_16x16x32_bf16 v[116:119], v[232:235], v[182:185], v[116:119]
	v_mfma_f32_16x16x32_bf16 v[112:115], v[240:243], v[182:185], v[112:115]
	v_mfma_f32_16x16x32_bf16 v[100:103], v[232:235], v[190:193], v[100:103]
	v_mfma_f32_16x16x32_bf16 v[96:99], v[240:243], v[190:193], v[96:99]
	v_mfma_f32_16x16x32_bf16 v[84:87], v[232:235], v[214:217], v[84:87]
	v_mfma_f32_16x16x32_bf16 v[80:83], v[240:243], v[214:217], v[80:83]
	v_mfma_f32_16x16x32_bf16 v[68:71], v[232:235], v[224:227], v[68:71]
	v_mfma_f32_16x16x32_bf16 v[64:67], v[240:243], v[224:227], v[64:67]
	v_mfma_f32_16x16x32_bf16 v[116:119], v[236:239], v[186:189], v[116:119]
	v_mfma_f32_16x16x32_bf16 v[112:115], v[244:247], v[186:189], v[112:115]
	v_mfma_f32_16x16x32_bf16 v[100:103], v[236:239], v[194:197], v[100:103]
	v_mfma_f32_16x16x32_bf16 v[96:99], v[244:247], v[194:197], v[96:99]
	v_mfma_f32_16x16x32_bf16 v[84:87], v[236:239], v[220:223], v[84:87]
	v_mfma_f32_16x16x32_bf16 v[80:83], v[244:247], v[220:223], v[80:83]
	v_mfma_f32_16x16x32_bf16 v[68:71], v[236:239], v[228:231], v[68:71]
	v_mfma_f32_16x16x32_bf16 v[64:67], v[244:247], v[228:231], v[64:67]
	s_setprio 0
	s_mov_b32 m0, s28
	v_lshl_add_u64 v[154:155], v[178:179], 0, s[2:3]
	s_barrier
	ds_read_b128 v[182:185], v219 offset:49152
	ds_read_b128 v[186:189], v219 offset:50176
	ds_read_b128 v[190:193], v219 offset:51200
	ds_read_b128 v[194:197], v219 offset:52224
	ds_read_b128 v[214:217], v219 offset:53248
	ds_read_b128 v[220:223], v219 offset:54272
	ds_read_b128 v[224:227], v219 offset:55296
	ds_read_b128 v[228:231], v219 offset:56320
	global_load_lds_dwordx4 v[154:155], off
	v_lshl_add_u64 v[154:155], v[248:249], 0, s[2:3]
	s_mov_b32 m0, s29
	s_nop 0
	global_load_lds_dwordx4 v[154:155], off
	s_barrier
; #define PG8_STAGE(bufoff, gbase, voff) do { _Pragma("unroll") for (int _i = 0; _i < 2; ++_i) \
;         __builtin_amdgcn_global_load_lds((const unsigned*)((const char*)(gbase) + (voff)[_i]), (LAS unsigned*)(lds + (bufoff) + ldsw + _i * 8192), 16, 0, 0); } while (0)
; #define PG8_MMA(ai, bj, At, Bt) do { __builtin_amdgcn_s_setprio(1); _Pragma("unroll") for (int m = 0; m < 4; ++m) _Pragma("unroll") for (int n = 0; n < 2; ++n) _Pragma("unroll") for (int k = 0; k < 2; ++k) \
;         acc[ai][bj][m][n] = __builtin_amdgcn_mfma_f32_16x16x32_bf16(Bt[n][k], At[m][k], acc[ai][bj][m][n], 0, 0, 0); __builtin_amdgcn_s_setprio(0); } while (0)
; #define PG8_WAIT_V(n) asm volatile("s_waitcnt vmcnt(" #n ")" ::: "memory")
; #define PG8_WAIT_L(n) asm volatile("s_waitcnt lgkmcnt(" #n ")" ::: "memory")
; #define PG8_BAR __builtin_amdgcn_s_barrier()
; #define PG8_SCHED __builtin_amdgcn_sched_barrier(0)
; template <class Epi>
; DEV void gemm_phase(LAS unsigned char* lds, const Gemm g, const StaticOrder& S, const Epi& E) {
;     ...
;             PG8_BAR; PG8_WAIT_L(0); PG8_MMA(1, 0, At, B0); PG8_BAR; PG8_SCHED;
;             PG8_STAGE(PG8_SB(1, 1), b3 + hstep, voffB);
;             PG8_WAIT_V(6); PG8_BAR; PG8_MMA(1, 1, At, B1); PG8_BAR;
;         }
; DEV float rowscale(const float* ss, int row) { const f32x4 a = *(const f32x4*)(ss + (size_t)row * 8), b = *(const f32x4*)(ss + (size_t)row * 8 + 4);
;     return rsqrtf(((a[0] + a[1]) + (a[2] + a[3]) + (b[0] + b[1]) + (b[2] + b[3])) * (1.0f / 2048.0f) + EPS); }
	s_waitcnt lgkmcnt(0)
	s_setprio 1
	s_waitcnt lgkmcnt(0)
	v_mfma_f32_16x16x32_bf16 v[60:63], v[128:131], v[182:185], v[60:63]
	v_mfma_f32_16x16x32_bf16 v[56:59], v[150:153], v[182:185], v[56:59]
	v_mfma_f32_16x16x32_bf16 v[44:47], v[128:131], v[190:193], v[44:47]
	v_mfma_f32_16x16x32_bf16 v[40:43], v[150:153], v[190:193], v[40:43]
	v_mfma_f32_16x16x32_bf16 v[28:31], v[128:131], v[214:217], v[28:31]
	v_mfma_f32_16x16x32_bf16 v[24:27], v[150:153], v[214:217], v[24:27]
	v_mfma_f32_16x16x32_bf16 v[12:15], v[128:131], v[224:227], v[12:15]
	v_mfma_f32_16x16x32_bf16 v[8:11], v[150:153], v[224:227], v[8:11]
	v_mfma_f32_16x16x32_bf16 v[60:63], v[132:135], v[186:189], v[60:63]
	v_mfma_f32_16x16x32_bf16 v[56:59], v[174:177], v[186:189], v[56:59]
	v_mfma_f32_16x16x32_bf16 v[44:47], v[132:135], v[194:197], v[44:47]
	v_mfma_f32_16x16x32_bf16 v[40:43], v[174:177], v[194:197], v[40:43]
	v_mfma_f32_16x16x32_bf16 v[28:31], v[132:135], v[220:223], v[28:31]
	v_mfma_f32_16x16x32_bf16 v[24:27], v[174:177], v[220:223], v[24:27]
	v_mfma_f32_16x16x32_bf16 v[12:15], v[132:135], v[228:231], v[12:15]
	v_mfma_f32_16x16x32_bf16 v[8:11], v[174:177], v[228:231], v[8:11]
	s_setprio 0
	s_barrier
	s_add_u32 s16, s16, 0x80080
	s_addc_u32 s17, s17, 0
	s_add_i32 s18, s18, s22
	v_lshl_add_u64 v[128:129], s[16:17], 0, v[140:141]
	s_mov_b32 m0, s18
	s_nop 0
	global_load_lds_dwordx4 v[128:129], off
	v_lshl_add_u64 v[128:129], s[16:17], 0, v[136:137]
	s_add_i32 m0, s18, 0x2000
	s_nop 0
	global_load_lds_dwordx4 v[128:129], off
	s_waitcnt vmcnt(6)
	s_barrier
	s_setprio 1
	v_mfma_f32_16x16x32_bf16 v[52:55], v[232:235], v[182:185], v[52:55]
	v_mfma_f32_16x16x32_bf16 v[48:51], v[240:243], v[182:185], v[48:51]
	v_mfma_f32_16x16x32_bf16 v[36:39], v[232:235], v[190:193], v[36:39]
	v_mfma_f32_16x16x32_bf16 v[32:35], v[240:243], v[190:193], v[32:35]
	v_mfma_f32_16x16x32_bf16 v[20:23], v[232:235], v[214:217], v[20:23]
	v_mfma_f32_16x16x32_bf16 v[16:19], v[240:243], v[214:217], v[16:19]
	v_mfma_f32_16x16x32_bf16 v[4:7], v[232:235], v[224:227], v[4:7]
	v_mfma_f32_16x16x32_bf16 v[0:3], v[240:243], v[224:227], v[0:3]
	v_mfma_f32_16x16x32_bf16 v[52:55], v[236:239], v[186:189], v[52:55]
	v_mfma_f32_16x16x32_bf16 v[48:51], v[244:247], v[186:189], v[48:51]
	v_mfma_f32_16x16x32_bf16 v[36:39], v[236:239], v[194:197], v[36:39]
	v_mfma_f32_16x16x32_bf16 v[32:35], v[244:247], v[194:197], v[32:35]
	v_mfma_f32_16x16x32_bf16 v[20:23], v[236:239], v[220:223], v[20:23]
	v_mfma_f32_16x16x32_bf16 v[16:19], v[244:247], v[220:223], v[16:19]
	v_mfma_f32_16x16x32_bf16 v[4:7], v[236:239], v[228:231], v[4:7]
	v_mfma_f32_16x16x32_bf16 v[0:3], v[244:247], v[228:231], v[0:3]
	s_setprio 0
	s_add_i32 s40, s40, 2
	s_add_u32 s14, s14, 0x100
	s_addc_u32 s15, s15, 0
	s_add_u32 s36, s36, 0x100
	s_addc_u32 s37, s37, 0
	s_cmp_gt_u32 s40, 29
	s_barrier
	s_cbranch_scc0 .LBB0_588
	s_lshl_b32 s7, s34, 8
	v_lshl_add_u32 v150, s0, 8, v157
	v_readlane_b32 s100, v251, 39
	v_readlane_b32 s101, v251, 40
	v_lshlrev_b32_e32 v249, 5, v150
	s_nop 3
	global_load_dwordx4 v[220:223], v249, s[100:101]
	global_load_dwordx4 v[224:227], v249, s[100:101] offset:16
	global_load_dwordx4 v[228:231], v249, s[100:101] offset:512
	global_load_dwordx4 v[232:235], v249, s[100:101] offset:528
	global_load_dwordx4 v[236:239], v249, s[100:101] offset:1024
	global_load_dwordx4 v[128:131], v249, s[100:101] offset:1040
	global_load_dwordx4 v[132:135], v249, s[100:101] offset:1536
	global_load_dwordx4 v[190:193], v249, s[100:101] offset:1552
	v_add_u32_e32 v249, 0x1000, v249
	s_waitcnt vmcnt(6)
	v_add_f32_e32 v220, v220, v221
	v_add_f32_e32 v222, v222, v223
	v_add_f32_e32 v224, v224, v225
	v_add_f32_e32 v226, v226, v227
	v_add_f32_e32 v220, v220, v222
	v_add_f32_e32 v220, v220, v224
	v_add_f32_e32 v240, v220, v226
	s_waitcnt vmcnt(4)
	v_add_f32_e32 v228, v228, v229
	v_add_f32_e32 v230, v230, v231
	v_add_f32_e32 v232, v232, v233
	v_add_f32_e32 v234, v234, v235
	v_add_f32_e32 v228, v228, v230
	v_add_f32_e32 v228, v228, v232
	v_add_f32_e32 v241, v228, v234
	s_waitcnt vmcnt(2)
	v_add_f32_e32 v236, v236, v237
	v_add_f32_e32 v238, v238, v239
	v_add_f32_e32 v128, v128, v129
	v_add_f32_e32 v130, v130, v131
	v_add_f32_e32 v236, v236, v238
	v_add_f32_e32 v236, v236, v128
	v_add_f32_e32 v242, v236, v130
	s_waitcnt vmcnt(0)
	v_add_f32_e32 v132, v132, v133
	v_add_f32_e32 v134, v134, v135
	v_add_f32_e32 v190, v190, v191
	v_add_f32_e32 v192, v192, v193
	v_add_f32_e32 v132, v132, v134
	v_add_f32_e32 v132, v132, v190
	v_add_f32_e32 v243, v132, v192
	global_load_dwordx4 v[220:223], v249, s[100:101]
	global_load_dwordx4 v[224:227], v249, s[100:101] offset:16
	global_load_dwordx4 v[228:231], v249, s[100:101] offset:512
	global_load_dwordx4 v[232:235], v249, s[100:101] offset:528
	global_load_dwordx4 v[236:239], v249, s[100:101] offset:1024
	global_load_dwordx4 v[128:131], v249, s[100:101] offset:1040
	global_load_dwordx4 v[132:135], v249, s[100:101] offset:1536
	global_load_dwordx4 v[190:193], v249, s[100:101] offset:1552
	s_waitcnt vmcnt(6)
	v_add_f32_e32 v220, v220, v221
	v_add_f32_e32 v222, v222, v223
	v_add_f32_e32 v224, v224, v225
	v_add_f32_e32 v226, v226, v227
	v_add_f32_e32 v220, v220, v222
	v_add_f32_e32 v220, v220, v224
	v_add_f32_e32 v244, v220, v226
	s_waitcnt vmcnt(4)
	v_add_f32_e32 v228, v228, v229
	v_add_f32_e32 v230, v230, v231
	v_add_f32_e32 v232, v232, v233
	v_add_f32_e32 v234, v234, v235
	v_add_f32_e32 v228, v228, v230
	v_add_f32_e32 v228, v228, v232
	v_add_f32_e32 v245, v228, v234
	s_waitcnt vmcnt(2)
	v_add_f32_e32 v236, v236, v237
	v_add_f32_e32 v238, v238, v239
	v_add_f32_e32 v128, v128, v129
	v_add_f32_e32 v130, v130, v131
	v_add_f32_e32 v236, v236, v238
	v_add_f32_e32 v236, v236, v128
	v_add_f32_e32 v246, v236, v130
	s_waitcnt vmcnt(0)
	v_add_f32_e32 v132, v132, v133
	v_add_f32_e32 v134, v134, v135
	v_add_f32_e32 v190, v190, v191
	v_add_f32_e32 v192, v192, v193
	v_add_f32_e32 v132, v132, v134
	v_add_f32_e32 v132, v132, v190
	v_add_f32_e32 v247, v132, v192
	s_cmp_gt_i32 s34, 15
	s_mov_b64 s[0:1], -1
	s_cbranch_scc0 .LBB0_601
;     DEV void operator()(AccRef acc, const pg8::Unit& u, int wr, int wc, int fr, int fq) const { store_bf16_tile<0, false>(acc, O, ld, u.pm * 256 + wr * 64 + fr, u.pn * 256 + wc * 32 + 4 * fq, ss); }
; DEV float rowscale(const float* ss, int row) { const f32x4 a = *(const f32x4*)(ss + (size_t)row * 8), b = *(const f32x4*)(ss + (size_t)row * 8 + 4);
;     return rsqrtf(((a[0] + a[1]) + (a[2] + a[3]) + (b[0] + b[1]) + (b[2] + b[3])) * (1.0f / 2048.0f) + EPS); }
;     DEV void operator()(AccRef acc, const pg8::Unit& u, int wr, int wc, int fr, int fq) const {
;         const int ct = u.pn * 256, row0 = u.pm * 256 + wr * 64 + fr, cw = wc * 32 + 8 * fq;
;         if (ct < 4096) store_bf16_tile<1, true>(acc, UV, 4096, row0, ct + cw, ss);
;         else if (ct < 6144) store_bf16_tile<0, true>(acc, Z, 2048, row0, ct - 4096 + cw, ss);
;         else if (ct < 9216) store_bf16_tile<0, true>(acc, XBC, 3072, row0, ct - 6144 + cw, ss);
;         else if (wc == 0) {
; #pragma unroll
;             for (int ai = 0; ai < 2; ++ai)
; #pragma unroll
;                 for (int m = 0; m < 4; ++m) { const float rs = rowscale(ss, row0 + ai * 128 + m * 16);
; #pragma unroll
;                     for (int n = 0; n < 2; ++n) *(f32x4*)(DTR + (size_t)(row0 + ai * 128 + m * 16) * 32 + 8 * fq + 4 * n) = acc[ai][0][m][n] * rs; }
	s_cmp_gt_u32 s34, 23
	s_cbranch_scc0 .LBB0_598
	s_cmp_gt_u32 s34, 35
	s_cbranch_scc0 .LBB0_595
	s_andn2_b64 vcc, exec, s[4:5]
	s_cbranch_vccnz .LBB0_594
	v_ashrrev_i32_e32 v151, 31, v150
	v_readlane_b32 s0, v251, 39
	v_lshlrev_b64 v[128:129], 5, v[150:151]
	v_readlane_b32 s1, v251, 40
	s_mov_b32 s9, 0x800000
	s_nop 0
	v_lshl_add_u64 v[132:133], s[0:1], 0, v[128:129]
	v_mov_b32_e32 v128, 0
	v_mov_b32_e32 v129, 0
	v_mov_b32_e32 v130, 0
	v_mov_b32_e32 v131, 0
	s_nop 0
	v_mov_b32_e32 v132, v240
	v_mov_b32_e32 v133, 0
	v_mov_b32_e32 v134, 0
	v_mov_b32_e32 v135, 0
	s_waitcnt vmcnt(0)
	v_mov_b32_e32 v152, v133
	v_mov_b32_e32 v153, v134
	v_mov_b32_e32 v133, v135
	v_pk_add_f32 v[132:133], v[152:153], v[132:133]
	v_mov_b32_e32 v134, v130
	v_mov_b32_e32 v135, v128
	v_mov_b32_e32 v128, v131
	v_pk_add_f32 v[128:129], v[134:135], v[128:129]
	v_add_f32_e32 v130, v132, v133
	v_add_f32_e32 v129, v130, v129
	v_add_f32_e32 v128, v128, v129
	v_fmamk_f32 v128, v128, 0x3a000000, v199
	v_cmp_gt_f32_e32 vcc, s9, v128
	v_mul_f32_e32 v129, 0x4b800000, v128
	v_lshlrev_b64 v[134:135], 7, v[150:151]
	v_cndmask_b32_e32 v128, v128, v129, vcc
	v_rsq_f32_e32 v128, v128
	v_lshl_add_u64 v[134:135], v[144:145], 0, v[134:135]
	v_or_b32_e32 v152, 16, v150
	v_ashrrev_i32_e32 v153, 31, v152
	v_mul_f32_e32 v129, 0x45800000, v128
	v_cndmask_b32_e32 v132, v128, v129, vcc
	v_pk_mul_f32 v[130:131], v[126:127], v[132:133] op_sel_hi:[1,0]
	v_pk_mul_f32 v[128:129], v[124:125], v[132:133] op_sel_hi:[1,0]
	global_store_dwordx4 v[134:135], v[128:131], off
	s_nop 1
	v_pk_mul_f32 v[130:131], v[122:123], v[132:133] op_sel_hi:[1,0]
	v_pk_mul_f32 v[128:129], v[120:121], v[132:133] op_sel_hi:[1,0]
	global_store_dwordx4 v[134:135], v[128:131], off offset:16
	s_nop 1
	v_lshlrev_b64 v[128:129], 5, v[152:153]
	v_lshl_add_u64 v[132:133], s[0:1], 0, v[128:129]
	v_mov_b32_e32 v128, 0
	v_mov_b32_e32 v129, 0
	v_mov_b32_e32 v130, 0
	v_mov_b32_e32 v131, 0
	s_nop 0
	v_mov_b32_e32 v132, v241
	v_mov_b32_e32 v133, 0
	v_mov_b32_e32 v134, 0
	v_mov_b32_e32 v135, 0
	s_waitcnt vmcnt(0)
	v_mov_b32_e32 v154, v133
	v_mov_b32_e32 v155, v134
	v_mov_b32_e32 v133, v135
	v_pk_add_f32 v[132:133], v[154:155], v[132:133]
	v_mov_b32_e32 v134, v130
	v_mov_b32_e32 v135, v128
	v_mov_b32_e32 v128, v131
	v_pk_add_f32 v[128:129], v[134:135], v[128:129]
	v_add_f32_e32 v130, v132, v133
	v_add_f32_e32 v129, v130, v129
	v_add_f32_e32 v128, v128, v129
	v_fmamk_f32 v128, v128, 0x3a000000, v199
	v_cmp_gt_f32_e32 vcc, s9, v128
	v_mul_f32_e32 v129, 0x4b800000, v128
	v_lshlrev_b64 v[134:135], 7, v[152:153]
	v_cndmask_b32_e32 v128, v128, v129, vcc
	v_rsq_f32_e32 v128, v128
	v_lshl_add_u64 v[134:135], v[144:145], 0, v[134:135]
	v_or_b32_e32 v152, 32, v150
	v_ashrrev_i32_e32 v153, 31, v152
	v_mul_f32_e32 v129, 0x45800000, v128
	v_cndmask_b32_e32 v132, v128, v129, vcc
	v_pk_mul_f32 v[130:131], v[110:111], v[132:133] op_sel_hi:[1,0]
	v_pk_mul_f32 v[128:129], v[108:109], v[132:133] op_sel_hi:[1,0]
	global_store_dwordx4 v[134:135], v[128:131], off
	s_nop 1
	v_pk_mul_f32 v[130:131], v[106:107], v[132:133] op_sel_hi:[1,0]
	v_pk_mul_f32 v[128:129], v[104:105], v[132:133] op_sel_hi:[1,0]
	global_store_dwordx4 v[134:135], v[128:131], off offset:16
	s_nop 1
	v_lshlrev_b64 v[128:129], 5, v[152:153]
	v_lshl_add_u64 v[132:133], s[0:1], 0, v[128:129]
	v_mov_b32_e32 v128, 0
	v_mov_b32_e32 v129, 0
	v_mov_b32_e32 v130, 0
	v_mov_b32_e32 v131, 0
	s_nop 0
	v_mov_b32_e32 v132, v242
	v_mov_b32_e32 v133, 0
	v_mov_b32_e32 v134, 0
	v_mov_b32_e32 v135, 0
	s_waitcnt vmcnt(0)
	v_mov_b32_e32 v154, v133
	v_mov_b32_e32 v155, v134
	v_mov_b32_e32 v133, v135
	v_pk_add_f32 v[132:133], v[154:155], v[132:133]
	v_mov_b32_e32 v134, v130
	v_mov_b32_e32 v135, v128
	v_mov_b32_e32 v128, v131
	v_pk_add_f32 v[128:129], v[134:135], v[128:129]
	v_add_f32_e32 v130, v132, v133
	v_add_f32_e32 v129, v130, v129
	v_add_f32_e32 v128, v128, v129
	v_fmamk_f32 v128, v128, 0x3a000000, v199
	v_cmp_gt_f32_e32 vcc, s9, v128
	v_mul_f32_e32 v129, 0x4b800000, v128
	v_lshlrev_b64 v[134:135], 7, v[152:153]
	v_cndmask_b32_e32 v128, v128, v129, vcc
	v_rsq_f32_e32 v128, v128
	v_lshl_add_u64 v[134:135], v[144:145], 0, v[134:135]
	v_or_b32_e32 v152, 48, v150
	v_ashrrev_i32_e32 v153, 31, v152
	v_mul_f32_e32 v129, 0x45800000, v128
	v_cndmask_b32_e32 v132, v128, v129, vcc
	v_pk_mul_f32 v[130:131], v[94:95], v[132:133] op_sel_hi:[1,0]
	v_pk_mul_f32 v[128:129], v[92:93], v[132:133] op_sel_hi:[1,0]
	global_store_dwordx4 v[134:135], v[128:131], off
	s_nop 1
	v_pk_mul_f32 v[130:131], v[90:91], v[132:133] op_sel_hi:[1,0]
	v_pk_mul_f32 v[128:129], v[88:89], v[132:133] op_sel_hi:[1,0]
	global_store_dwordx4 v[134:135], v[128:131], off offset:16
	s_nop 1
	v_lshlrev_b64 v[128:129], 5, v[152:153]
	v_lshl_add_u64 v[132:133], s[0:1], 0, v[128:129]
	v_mov_b32_e32 v128, 0
	v_mov_b32_e32 v129, 0
	v_mov_b32_e32 v130, 0
	v_mov_b32_e32 v131, 0
	s_nop 0
	v_mov_b32_e32 v132, v243
	v_mov_b32_e32 v133, 0
	v_mov_b32_e32 v134, 0
	v_mov_b32_e32 v135, 0
	s_waitcnt vmcnt(0)
; DEV float rowscale(const float* ss, int row) { const f32x4 a = *(const f32x4*)(ss + (size_t)row * 8), b = *(const f32x4*)(ss + (size_t)row * 8 + 4);
;     return rsqrtf(((a[0] + a[1]) + (a[2] + a[3]) + (b[0] + b[1]) + (b[2] + b[3])) * (1.0f / 2048.0f) + EPS); }
;     DEV void operator()(AccRef acc, const pg8::Unit& u, int wr, int wc, int fr, int fq) const {
;     ...
;                 for (int m = 0; m < 4; ++m) { const float rs = rowscale(ss, row0 + ai * 128 + m * 16);
; #pragma unroll
;                     for (int n = 0; n < 2; ++n) *(f32x4*)(DTR + (size_t)(row0 + ai * 128 + m * 16) * 32 + 8 * fq + 4 * n) = acc[ai][0][m][n] * rs; }
	v_mov_b32_e32 v154, v133
	v_mov_b32_e32 v155, v134
	v_mov_b32_e32 v133, v135
	v_pk_add_f32 v[132:133], v[154:155], v[132:133]
	v_mov_b32_e32 v134, v130
	v_mov_b32_e32 v135, v128
	v_mov_b32_e32 v128, v131
	v_pk_add_f32 v[128:129], v[134:135], v[128:129]
	v_add_f32_e32 v130, v132, v133
	v_add_f32_e32 v129, v130, v129
	v_add_f32_e32 v128, v128, v129
	v_fmamk_f32 v128, v128, 0x3a000000, v199
	v_cmp_gt_f32_e32 vcc, s9, v128
	v_mul_f32_e32 v129, 0x4b800000, v128
	v_lshlrev_b64 v[134:135], 7, v[152:153]
	v_cndmask_b32_e32 v128, v128, v129, vcc
	v_rsq_f32_e32 v128, v128
	v_lshl_add_u64 v[134:135], v[144:145], 0, v[134:135]
	v_add_u32_e32 v152, 0x80, v150
	v_ashrrev_i32_e32 v153, 31, v152
	v_mul_f32_e32 v129, 0x45800000, v128
	v_cndmask_b32_e32 v132, v128, v129, vcc
	v_pk_mul_f32 v[130:131], v[78:79], v[132:133] op_sel_hi:[1,0]
	v_pk_mul_f32 v[128:129], v[76:77], v[132:133] op_sel_hi:[1,0]
	global_store_dwordx4 v[134:135], v[128:131], off
	s_nop 1
	v_pk_mul_f32 v[130:131], v[74:75], v[132:133] op_sel_hi:[1,0]
	v_pk_mul_f32 v[128:129], v[72:73], v[132:133] op_sel_hi:[1,0]
	global_store_dwordx4 v[134:135], v[128:131], off offset:16
	s_nop 1
	v_lshlrev_b64 v[128:129], 5, v[152:153]
	v_lshl_add_u64 v[132:133], s[0:1], 0, v[128:129]
	v_mov_b32_e32 v128, 0
	v_mov_b32_e32 v129, 0
	v_mov_b32_e32 v130, 0
	v_mov_b32_e32 v131, 0
	s_nop 0
	v_mov_b32_e32 v132, v244
	v_mov_b32_e32 v133, 0
	v_mov_b32_e32 v134, 0
	v_mov_b32_e32 v135, 0
	s_waitcnt vmcnt(0)
	v_mov_b32_e32 v154, v133
	v_mov_b32_e32 v155, v134
	v_mov_b32_e32 v133, v135
	v_pk_add_f32 v[132:133], v[154:155], v[132:133]
	v_mov_b32_e32 v134, v130
	v_mov_b32_e32 v135, v128
	v_mov_b32_e32 v128, v131
	v_pk_add_f32 v[128:129], v[134:135], v[128:129]
	v_add_f32_e32 v130, v132, v133
	v_add_f32_e32 v129, v130, v129
	v_add_f32_e32 v128, v128, v129
	v_fmamk_f32 v128, v128, 0x3a000000, v199
	v_cmp_gt_f32_e32 vcc, s9, v128
	v_mul_f32_e32 v129, 0x4b800000, v128
	v_lshlrev_b64 v[134:135], 7, v[152:153]
	v_cndmask_b32_e32 v128, v128, v129, vcc
	v_rsq_f32_e32 v128, v128
	v_lshl_add_u64 v[134:135], v[144:145], 0, v[134:135]
	v_add_u32_e32 v152, 0x90, v150
	v_ashrrev_i32_e32 v153, 31, v152
	v_mul_f32_e32 v129, 0x45800000, v128
	v_cndmask_b32_e32 v132, v128, v129, vcc
	v_pk_mul_f32 v[130:131], v[62:63], v[132:133] op_sel_hi:[1,0]
	v_pk_mul_f32 v[128:129], v[60:61], v[132:133] op_sel_hi:[1,0]
	global_store_dwordx4 v[134:135], v[128:131], off
	s_nop 1
	v_pk_mul_f32 v[130:131], v[58:59], v[132:133] op_sel_hi:[1,0]
	v_pk_mul_f32 v[128:129], v[56:57], v[132:133] op_sel_hi:[1,0]
	global_store_dwordx4 v[134:135], v[128:131], off offset:16
	s_nop 1
	v_lshlrev_b64 v[128:129], 5, v[152:153]
	v_lshl_add_u64 v[132:133], s[0:1], 0, v[128:129]
	v_mov_b32_e32 v128, 0
	v_mov_b32_e32 v129, 0
	v_mov_b32_e32 v130, 0
	v_mov_b32_e32 v131, 0
	s_nop 0
	v_mov_b32_e32 v132, v245
	v_mov_b32_e32 v133, 0
	v_mov_b32_e32 v134, 0
	v_mov_b32_e32 v135, 0
	s_waitcnt vmcnt(0)
	v_mov_b32_e32 v154, v133
	v_mov_b32_e32 v155, v134
	v_mov_b32_e32 v133, v135
	v_pk_add_f32 v[132:133], v[154:155], v[132:133]
	v_mov_b32_e32 v134, v130
	v_mov_b32_e32 v135, v128
	v_mov_b32_e32 v128, v131
	v_pk_add_f32 v[128:129], v[134:135], v[128:129]
	v_add_f32_e32 v130, v132, v133
	v_add_f32_e32 v129, v130, v129
	v_add_f32_e32 v128, v128, v129
	v_fmamk_f32 v128, v128, 0x3a000000, v199
	v_cmp_gt_f32_e32 vcc, s9, v128
	v_mul_f32_e32 v129, 0x4b800000, v128
	v_lshlrev_b64 v[134:135], 7, v[152:153]
	v_cndmask_b32_e32 v128, v128, v129, vcc
	v_rsq_f32_e32 v128, v128
	v_lshl_add_u64 v[134:135], v[144:145], 0, v[134:135]
	v_add_u32_e32 v152, 0xa0, v150
	v_ashrrev_i32_e32 v153, 31, v152
	v_mul_f32_e32 v129, 0x45800000, v128
	v_cndmask_b32_e32 v132, v128, v129, vcc
	v_pk_mul_f32 v[130:131], v[46:47], v[132:133] op_sel_hi:[1,0]
	v_pk_mul_f32 v[128:129], v[44:45], v[132:133] op_sel_hi:[1,0]
	global_store_dwordx4 v[134:135], v[128:131], off
	s_nop 1
	v_pk_mul_f32 v[130:131], v[42:43], v[132:133] op_sel_hi:[1,0]
	v_pk_mul_f32 v[128:129], v[40:41], v[132:133] op_sel_hi:[1,0]
	global_store_dwordx4 v[134:135], v[128:131], off offset:16
	s_nop 1
	v_lshlrev_b64 v[128:129], 5, v[152:153]
	v_lshl_add_u64 v[132:133], s[0:1], 0, v[128:129]
	v_mov_b32_e32 v128, 0
	v_mov_b32_e32 v129, 0
	v_mov_b32_e32 v130, 0
	v_mov_b32_e32 v131, 0
	s_nop 0
	v_mov_b32_e32 v132, v246
	v_mov_b32_e32 v133, 0
	v_mov_b32_e32 v134, 0
	v_mov_b32_e32 v135, 0
	s_waitcnt vmcnt(0)
	v_mov_b32_e32 v154, v133
	v_mov_b32_e32 v155, v134
	v_mov_b32_e32 v133, v135
	v_pk_add_f32 v[132:133], v[154:155], v[132:133]
	v_mov_b32_e32 v134, v130
	v_mov_b32_e32 v135, v128
	v_mov_b32_e32 v128, v131
	v_pk_add_f32 v[128:129], v[134:135], v[128:129]
	v_add_f32_e32 v130, v132, v133
	v_add_f32_e32 v129, v130, v129
	v_add_f32_e32 v128, v128, v129
	v_fmamk_f32 v128, v128, 0x3a000000, v199
	v_cmp_gt_f32_e32 vcc, s9, v128
	v_mul_f32_e32 v129, 0x4b800000, v128
	v_lshlrev_b64 v[134:135], 7, v[152:153]
	v_cndmask_b32_e32 v128, v128, v129, vcc
	v_rsq_f32_e32 v128, v128
	v_lshl_add_u64 v[134:135], v[144:145], 0, v[134:135]
	v_add_u32_e32 v152, 0xb0, v150
	v_ashrrev_i32_e32 v153, 31, v152
	v_mul_f32_e32 v129, 0x45800000, v128
	v_cndmask_b32_e32 v132, v128, v129, vcc
	v_pk_mul_f32 v[130:131], v[30:31], v[132:133] op_sel_hi:[1,0]
	v_pk_mul_f32 v[128:129], v[28:29], v[132:133] op_sel_hi:[1,0]
	global_store_dwordx4 v[134:135], v[128:131], off
	s_nop 1
	v_pk_mul_f32 v[130:131], v[26:27], v[132:133] op_sel_hi:[1,0]
	v_pk_mul_f32 v[128:129], v[24:25], v[132:133] op_sel_hi:[1,0]
	global_store_dwordx4 v[134:135], v[128:131], off offset:16
	s_nop 1
	v_lshlrev_b64 v[128:129], 5, v[152:153]
	v_lshl_add_u64 v[132:133], s[0:1], 0, v[128:129]
	v_mov_b32_e32 v128, 0
	v_mov_b32_e32 v129, 0
	v_mov_b32_e32 v130, 0
	v_mov_b32_e32 v131, 0
	s_nop 0
	v_mov_b32_e32 v132, v247
	v_mov_b32_e32 v133, 0
	v_mov_b32_e32 v134, 0
	v_mov_b32_e32 v135, 0
	s_waitcnt vmcnt(0)
	v_mov_b32_e32 v154, v133
	v_mov_b32_e32 v155, v134
	v_mov_b32_e32 v133, v135
	v_pk_add_f32 v[132:133], v[154:155], v[132:133]
	v_mov_b32_e32 v134, v130
	v_mov_b32_e32 v135, v128
	v_mov_b32_e32 v128, v131
	v_pk_add_f32 v[128:129], v[134:135], v[128:129]
	v_add_f32_e32 v130, v132, v133
	v_add_f32_e32 v129, v130, v129
	v_add_f32_e32 v128, v128, v129
	v_fmamk_f32 v128, v128, 0x3a000000, v199
	v_cmp_gt_f32_e32 vcc, s9, v128
	v_mul_f32_e32 v129, 0x4b800000, v128
	v_lshlrev_b64 v[134:135], 7, v[152:153]
	v_cndmask_b32_e32 v128, v128, v129, vcc
	v_rsq_f32_e32 v128, v128
	v_lshl_add_u64 v[134:135], v[144:145], 0, v[134:135]
	v_mul_f32_e32 v129, 0x45800000, v128
	v_cndmask_b32_e32 v132, v128, v129, vcc
	v_pk_mul_f32 v[130:131], v[14:15], v[132:133] op_sel_hi:[1,0]
	v_pk_mul_f32 v[128:129], v[12:13], v[132:133] op_sel_hi:[1,0]
	global_store_dwordx4 v[134:135], v[128:131], off
	s_nop 1
	v_pk_mul_f32 v[130:131], v[10:11], v[132:133] op_sel_hi:[1,0]
	v_pk_mul_f32 v[128:129], v[8:9], v[132:133] op_sel_hi:[1,0]
	global_store_dwordx4 v[134:135], v[128:131], off offset:16

; DEV float rowscale(const float* ss, int row) { const f32x4 a = *(const f32x4*)(ss + (size_t)row * 8), b = *(const f32x4*)(ss + (size_t)row * 8 + 4);
;     return rsqrtf(((a[0] + a[1]) + (a[2] + a[3]) + (b[0] + b[1]) + (b[2] + b[3])) * (1.0f / 2048.0f) + EPS); }
; template <int ACT, bool PERM>
; DEV void store_bf16_tile(AccRef acc, u16* O, int ld, int row0, int col0, const float* ss) {
;     ...
;         for (int m = 0; m < 4; ++m) rsv[ai][m] = ss ? rowscale(ss, row0 + ai * 128 + m * 16) : 1.0f;
.LBB0_595:
	s_andn2_b64 vcc, exec, s[0:1]
	s_cbranch_vccnz .LBB0_597
	v_or_b32_e32 v128, 0xffffe800, v181
	v_ashrrev_i32_e32 v151, 31, v150
	v_readlane_b32 s14, v251, 39
	v_add_u32_e32 v160, s7, v128
	v_lshlrev_b64 v[128:129], 5, v[150:151]
	v_readlane_b32 s15, v251, 40
	s_mov_b32 s0, 0x3727c5ac
	s_mov_b32 s16, 0x3a000000
	v_lshl_add_u64 v[132:133], s[14:15], 0, v[128:129]
	v_mov_b32_e32 v128, 0
	v_mov_b32_e32 v129, 0
	v_mov_b32_e32 v130, 0
	v_mov_b32_e32 v131, 0
	s_nop 0
	v_mov_b32_e32 v132, v240
	v_mov_b32_e32 v133, 0
	v_mov_b32_e32 v134, 0
	v_mov_b32_e32 v135, 0
	s_mov_b32 s9, 0x800000
	s_waitcnt vmcnt(0)
	v_mov_b32_e32 v152, v133
	v_mov_b32_e32 v153, v134
	v_mov_b32_e32 v133, v135
	v_pk_add_f32 v[154:155], v[152:153], v[132:133]
	v_or_b32_e32 v152, 16, v150
	v_mov_b32_e32 v132, v130
	v_mov_b32_e32 v133, v128
	v_mov_b32_e32 v128, v131
	v_ashrrev_i32_e32 v153, 31, v152
	v_pk_add_f32 v[158:159], v[132:133], v[128:129]
	v_lshlrev_b64 v[128:129], 5, v[152:153]
	v_lshl_add_u64 v[132:133], s[14:15], 0, v[128:129]
	v_mov_b32_e32 v128, 0
	v_mov_b32_e32 v129, 0
	v_mov_b32_e32 v130, 0
	v_mov_b32_e32 v131, 0
	s_nop 0
	v_mov_b32_e32 v132, v241
	v_mov_b32_e32 v133, 0
	v_mov_b32_e32 v134, 0
	v_mov_b32_e32 v135, 0
	s_waitcnt vmcnt(0)
	v_mov_b32_e32 v174, v133
	v_mov_b32_e32 v175, v134
	v_mov_b32_e32 v133, v135
	v_pk_add_f32 v[132:133], v[174:175], v[132:133]
	v_mov_b32_e32 v134, v130
	v_mov_b32_e32 v135, v128
	v_mov_b32_e32 v128, v131
	v_pk_add_f32 v[128:129], v[134:135], v[128:129]
	v_mov_b32_e32 v130, v132
	v_mov_b32_e32 v131, v154
	v_mov_b32_e32 v154, v133
	v_pk_add_f32 v[130:131], v[130:131], v[154:155]
	v_mov_b32_e32 v132, v129
	v_mov_b32_e32 v133, v159
	v_pk_add_f32 v[130:131], v[130:131], v[132:133]
	v_mov_b32_e32 v129, v158
	v_pk_add_f32 v[128:129], v[128:129], v[130:131]
	v_mov_b64_e32 v[158:159], s[0:1]
	v_pk_fma_f32 v[128:129], v[128:129], s[16:17], v[158:159] op_sel_hi:[1,0,0]
	v_or_b32_e32 v174, 32, v150
	v_mul_f32_e32 v130, 0x4b800000, v129
	v_cmp_gt_f32_e64 s[0:1], s9, v129
	v_cmp_gt_f32_e32 vcc, s9, v128
	v_ashrrev_i32_e32 v175, 31, v174
	v_cndmask_b32_e64 v129, v129, v130, s[0:1]
	v_rsq_f32_e32 v129, v129
	s_nop 0
	v_mul_f32_e32 v130, 0x45800000, v129
	v_cndmask_b32_e64 v156, v129, v130, s[0:1]
	v_mul_f32_e32 v129, 0x4b800000, v128
	v_cndmask_b32_e32 v128, v128, v129, vcc
	v_rsq_f32_e32 v128, v128
	s_nop 0
	v_mul_f32_e32 v129, 0x45800000, v128
	v_cndmask_b32_e32 v154, v128, v129, vcc
	v_lshlrev_b64 v[128:129], 5, v[174:175]
	v_lshl_add_u64 v[132:133], s[14:15], 0, v[128:129]
	v_mov_b32_e32 v128, 0
	v_mov_b32_e32 v129, 0
	v_mov_b32_e32 v130, 0
	v_mov_b32_e32 v131, 0
	s_nop 0
	v_mov_b32_e32 v132, v242
	v_mov_b32_e32 v133, 0
	v_mov_b32_e32 v134, 0
	v_mov_b32_e32 v135, 0
	s_waitcnt vmcnt(0)
	v_mov_b32_e32 v176, v133
	v_mov_b32_e32 v177, v134
	v_mov_b32_e32 v133, v135
	v_pk_add_f32 v[178:179], v[176:177], v[132:133]
	v_or_b32_e32 v176, 48, v150
	v_mov_b32_e32 v132, v130
	v_mov_b32_e32 v133, v128
	v_mov_b32_e32 v128, v131
	v_ashrrev_i32_e32 v177, 31, v176
	v_pk_add_f32 v[182:183], v[132:133], v[128:129]
	v_lshlrev_b64 v[128:129], 5, v[176:177]
	v_lshl_add_u64 v[132:133], s[14:15], 0, v[128:129]
	v_mov_b32_e32 v128, 0
	v_mov_b32_e32 v129, 0
	v_mov_b32_e32 v130, 0
	v_mov_b32_e32 v131, 0
	s_nop 0
	v_mov_b32_e32 v132, v243
	v_mov_b32_e32 v133, 0
	v_mov_b32_e32 v134, 0
	v_mov_b32_e32 v135, 0
	s_waitcnt vmcnt(0)
	v_mov_b32_e32 v184, v133
	v_mov_b32_e32 v185, v134
	v_mov_b32_e32 v133, v135
	v_pk_add_f32 v[132:133], v[184:185], v[132:133]
	v_mov_b32_e32 v134, v130
	v_mov_b32_e32 v135, v128
	v_mov_b32_e32 v128, v131
	v_pk_add_f32 v[128:129], v[134:135], v[128:129]
	v_mov_b32_e32 v130, v132
	v_mov_b32_e32 v131, v178
	v_mov_b32_e32 v178, v133
	v_pk_add_f32 v[130:131], v[130:131], v[178:179]
	v_mov_b32_e32 v132, v129
	v_mov_b32_e32 v133, v183
	v_pk_add_f32 v[130:131], v[130:131], v[132:133]
	v_mov_b32_e32 v129, v182
	v_pk_add_f32 v[128:129], v[128:129], v[130:131]
	v_add_u32_e32 v182, 0x80, v150
	v_pk_fma_f32 v[128:129], v[128:129], s[16:17], v[158:159] op_sel_hi:[1,0,0]
	v_ashrrev_i32_e32 v183, 31, v182
	v_mul_f32_e32 v130, 0x4b800000, v129
	v_cmp_gt_f32_e64 s[0:1], s9, v129
	v_cmp_gt_f32_e32 vcc, s9, v128
	s_nop 0
	v_cndmask_b32_e64 v129, v129, v130, s[0:1]
	v_rsq_f32_e32 v129, v129
	s_nop 0
	v_mul_f32_e32 v130, 0x45800000, v129
	v_cndmask_b32_e64 v180, v129, v130, s[0:1]
	v_mul_f32_e32 v129, 0x4b800000, v128
	v_cndmask_b32_e32 v128, v128, v129, vcc
	v_rsq_f32_e32 v128, v128
	s_nop 0
	v_mul_f32_e32 v129, 0x45800000, v128
	v_cndmask_b32_e32 v178, v128, v129, vcc
	v_lshlrev_b64 v[128:129], 5, v[182:183]
	v_lshl_add_u64 v[132:133], s[14:15], 0, v[128:129]
	v_mov_b32_e32 v128, 0
	v_mov_b32_e32 v129, 0
	v_mov_b32_e32 v130, 0
	v_mov_b32_e32 v131, 0
	s_nop 0
	v_mov_b32_e32 v132, v244
	v_mov_b32_e32 v133, 0
	v_mov_b32_e32 v134, 0
	v_mov_b32_e32 v135, 0
	s_waitcnt vmcnt(0)
	v_mov_b32_e32 v184, v133
	v_mov_b32_e32 v185, v134
	v_mov_b32_e32 v133, v135
	v_pk_add_f32 v[186:187], v[184:185], v[132:133]
	v_add_u32_e32 v184, 0x90, v150
	v_mov_b32_e32 v132, v130
	v_mov_b32_e32 v133, v128
	v_mov_b32_e32 v128, v131
	v_ashrrev_i32_e32 v185, 31, v184
	v_pk_add_f32 v[188:189], v[132:133], v[128:129]
	v_lshlrev_b64 v[128:129], 5, v[184:185]
	v_lshl_add_u64 v[132:133], s[14:15], 0, v[128:129]
	v_mov_b32_e32 v128, 0
	v_mov_b32_e32 v129, 0
	v_mov_b32_e32 v130, 0
	v_mov_b32_e32 v131, 0
	s_nop 0
	v_mov_b32_e32 v132, v245
	v_mov_b32_e32 v133, 0
	v_mov_b32_e32 v134, 0
	v_mov_b32_e32 v135, 0
	s_waitcnt vmcnt(0)
; DEV bf16x8 pack8(f32x4 a, f32x4 b) { u32x4 w; w.x = cvt_pk_bf16(a[0], a[1]); w.y = cvt_pk_bf16(a[2], a[3]); w.z = cvt_pk_bf16(b[0], b[1]); w.w = cvt_pk_bf16(b[2], b[3]); return __builtin_bit_cast(bf16x8, w); }
; DEV u32x2 pack4(f32x4 a) { u32x2 w; w.x = cvt_pk_bf16(a[0], a[1]); w.y = cvt_pk_bf16(a[2], a[3]); return w; }
; DEV f32x4 gelu4(f32x4 v) { f32x2 a = gelu_pk((f32x2){v[0], v[1]}), b = gelu_pk((f32x2){v[2], v[3]}); return (f32x4){a.x, a.y, b.x, b.y}; }
; DEV float rowscale(const float* ss, int row) { const f32x4 a = *(const f32x4*)(ss + (size_t)row * 8), b = *(const f32x4*)(ss + (size_t)row * 8 + 4);
;     return rsqrtf(((a[0] + a[1]) + (a[2] + a[3]) + (b[0] + b[1]) + (b[2] + b[3])) * (1.0f / 2048.0f) + EPS); }
; template <int ACT, bool PERM>
; DEV void store_bf16_tile(AccRef acc, u16* O, int ld, int row0, int col0, const float* ss) {
;     ...
;         for (int m = 0; m < 4; ++m) rsv[ai][m] = ss ? rowscale(ss, row0 + ai * 128 + m * 16) : 1.0f;
; #pragma unroll
;     for (int ai = 0; ai < 2; ++ai)
; #pragma unroll
;         for (int m = 0; m < 4; ++m) { u16* rowp = O + (size_t)(row0 + ai * 128 + m * 16) * ld + col0; const float rs = rsv[ai][m];
; #pragma unroll
;             for (int bj = 0; bj < 2; ++bj) { f32x4 v0 = acc[ai][bj][m][0] * rs, v1 = acc[ai][bj][m][1] * rs; if (ACT == 1) { v0 = gelu4(v0); v1 = gelu4(v1); }
;                 if (PERM) *(u32x4*)(rowp + bj * 128) = __builtin_bit_cast(u32x4, pack8(v0, v1));
;                 else { *(u32x2*)(rowp + bj * 128) = pack4(v0); *(u32x2*)(rowp + bj * 128 + 16) = pack4(v1); } } }
	v_mov_b32_e32 v190, v133
	v_mov_b32_e32 v191, v134
	v_mov_b32_e32 v133, v135
	v_pk_add_f32 v[132:133], v[190:191], v[132:133]
	v_mov_b32_e32 v134, v130
	v_mov_b32_e32 v135, v128
	v_mov_b32_e32 v128, v131
	v_pk_add_f32 v[128:129], v[134:135], v[128:129]
	v_mov_b32_e32 v130, v132
	v_mov_b32_e32 v131, v186
	v_mov_b32_e32 v186, v133
	v_pk_add_f32 v[130:131], v[130:131], v[186:187]
	v_mov_b32_e32 v132, v129
	v_mov_b32_e32 v133, v189
	v_pk_add_f32 v[130:131], v[130:131], v[132:133]
	v_mov_b32_e32 v129, v188
	v_pk_add_f32 v[128:129], v[128:129], v[130:131]
	v_add_u32_e32 v190, 0xa0, v150
	v_pk_fma_f32 v[128:129], v[128:129], s[16:17], v[158:159] op_sel_hi:[1,0,0]
	v_ashrrev_i32_e32 v191, 31, v190
	v_mul_f32_e32 v130, 0x4b800000, v129
	v_cmp_gt_f32_e64 s[0:1], s9, v129
	v_cmp_gt_f32_e32 vcc, s9, v128
	s_nop 0
	v_cndmask_b32_e64 v129, v129, v130, s[0:1]
	v_rsq_f32_e32 v129, v129
	s_nop 0
	v_mul_f32_e32 v130, 0x45800000, v129
	v_cndmask_b32_e64 v188, v129, v130, s[0:1]
	v_mul_f32_e32 v129, 0x4b800000, v128
	v_cndmask_b32_e32 v128, v128, v129, vcc
	v_rsq_f32_e32 v128, v128
	s_nop 0
	v_mul_f32_e32 v129, 0x45800000, v128
	v_cndmask_b32_e32 v186, v128, v129, vcc
	v_lshlrev_b64 v[128:129], 5, v[190:191]
	v_lshl_add_u64 v[132:133], s[14:15], 0, v[128:129]
	v_mov_b32_e32 v128, 0
	v_mov_b32_e32 v129, 0
	v_mov_b32_e32 v130, 0
	v_mov_b32_e32 v131, 0
	s_nop 0
	v_mov_b32_e32 v132, v246
	v_mov_b32_e32 v133, 0
	v_mov_b32_e32 v134, 0
	v_mov_b32_e32 v135, 0
	s_waitcnt vmcnt(0)
	v_mov_b32_e32 v192, v133
	v_mov_b32_e32 v193, v134
	v_mov_b32_e32 v133, v135
	v_pk_add_f32 v[196:197], v[192:193], v[132:133]
	v_add_u32_e32 v192, 0xb0, v150
	v_mov_b32_e32 v132, v130
	v_mov_b32_e32 v133, v128
	v_mov_b32_e32 v128, v131
	v_ashrrev_i32_e32 v193, 31, v192
	v_pk_add_f32 v[194:195], v[132:133], v[128:129]
	v_lshlrev_b64 v[128:129], 5, v[192:193]
	v_lshl_add_u64 v[132:133], s[14:15], 0, v[128:129]
	v_mov_b32_e32 v128, 0
	v_mov_b32_e32 v129, 0
	v_mov_b32_e32 v130, 0
	v_mov_b32_e32 v131, 0
	s_nop 0
	v_mov_b32_e32 v132, v247
	v_mov_b32_e32 v133, 0
	v_mov_b32_e32 v134, 0
	v_mov_b32_e32 v135, 0
	s_waitcnt vmcnt(0)
	v_mov_b32_e32 v214, v133
	v_mov_b32_e32 v215, v134
	v_mov_b32_e32 v133, v135
	v_pk_add_f32 v[132:133], v[214:215], v[132:133]
	v_mov_b32_e32 v134, v130
	v_mov_b32_e32 v135, v128
	v_mov_b32_e32 v128, v131
	v_pk_add_f32 v[128:129], v[134:135], v[128:129]
	v_mov_b32_e32 v130, v132
	v_mov_b32_e32 v131, v196
	v_mov_b32_e32 v196, v133
	v_pk_add_f32 v[130:131], v[130:131], v[196:197]
	v_mov_b32_e32 v132, v129
	v_mov_b32_e32 v133, v195
	v_pk_add_f32 v[130:131], v[130:131], v[132:133]
	v_mov_b32_e32 v129, v194
	v_pk_add_f32 v[128:129], v[128:129], v[130:131]
	v_pk_mul_f32 v[194:195], v[124:125], v[156:157] op_sel_hi:[1,0]
	v_pk_fma_f32 v[128:129], v[128:129], s[16:17], v[158:159] op_sel_hi:[1,0,0]
	v_pk_mul_f32 v[158:159], v[126:127], v[156:157] op_sel_hi:[1,0]
	v_mul_f32_e32 v130, 0x4b800000, v129
	v_cmp_gt_f32_e64 s[0:1], s9, v129
	v_cmp_gt_f32_e32 vcc, s9, v128
	s_movk_i32 s9, 0x1800
	v_cndmask_b32_e64 v129, v129, v130, s[0:1]
	v_rsq_f32_e32 v129, v129
	v_pk_mul_f32 v[214:215], v[122:123], v[156:157] op_sel_hi:[1,0]
	v_pk_mul_f32 v[196:197], v[120:121], v[156:157] op_sel_hi:[1,0]
	v_cvt_pk_bf16_f32 v194, v194, v195
	v_mul_f32_e32 v130, 0x45800000, v129
	v_cndmask_b32_e64 v130, v129, v130, s[0:1]
	v_readlane_b32 s0, v251, 5
	v_readlane_b32 s1, v251, 6
	v_cvt_pk_bf16_f32 v195, v158, v159
	v_cvt_pk_bf16_f32 v196, v196, v197
	v_lshl_add_u64 v[132:133], v[160:161], 1, s[0:1]
	v_mad_i64_i32 v[134:135], s[0:1], v150, s9, v[132:133]
	v_cvt_pk_bf16_f32 v197, v214, v215
	global_store_dwordx4 v[134:135], v[194:197], off
	v_pk_mul_f32 v[158:159], v[118:119], v[156:157] op_sel_hi:[1,0]
	v_pk_mul_f32 v[214:215], v[114:115], v[156:157] op_sel_hi:[1,0]
	v_pk_mul_f32 v[194:195], v[116:117], v[156:157] op_sel_hi:[1,0]
	v_pk_mul_f32 v[196:197], v[112:113], v[156:157] op_sel_hi:[1,0]
	v_cvt_pk_bf16_f32 v194, v194, v195
	v_cvt_pk_bf16_f32 v195, v158, v159
	v_cvt_pk_bf16_f32 v196, v196, v197
	v_cvt_pk_bf16_f32 v197, v214, v215
	global_store_dwordx4 v[134:135], v[194:197], off offset:256
	v_mad_i64_i32 v[134:135], s[0:1], v152, s9, v[132:133]
	v_pk_mul_f32 v[152:153], v[110:111], v[154:155] op_sel_hi:[1,0]
	v_pk_mul_f32 v[158:159], v[108:109], v[154:155] op_sel_hi:[1,0]
	v_pk_mul_f32 v[214:215], v[106:107], v[154:155] op_sel_hi:[1,0]
	v_pk_mul_f32 v[196:197], v[104:105], v[154:155] op_sel_hi:[1,0]
	v_cvt_pk_bf16_f32 v194, v158, v159
	v_cvt_pk_bf16_f32 v195, v152, v153
	v_cvt_pk_bf16_f32 v196, v196, v197
	v_cvt_pk_bf16_f32 v197, v214, v215
	global_store_dwordx4 v[134:135], v[194:197], off
	v_pk_mul_f32 v[158:159], v[102:103], v[154:155] op_sel_hi:[1,0]
	v_pk_mul_f32 v[152:153], v[100:101], v[154:155] op_sel_hi:[1,0]
	v_pk_mul_f32 v[194:195], v[98:99], v[154:155] op_sel_hi:[1,0]
	v_pk_mul_f32 v[154:155], v[96:97], v[154:155] op_sel_hi:[1,0]
	v_cvt_pk_bf16_f32 v152, v152, v153
	v_cvt_pk_bf16_f32 v153, v158, v159
	v_cvt_pk_bf16_f32 v154, v154, v155
	v_cvt_pk_bf16_f32 v155, v194, v195
	global_store_dwordx4 v[134:135], v[152:155], off offset:256
	v_mad_i64_i32 v[134:135], s[0:1], v174, s9, v[132:133]
	s_nop 0
	v_pk_mul_f32 v[154:155], v[94:95], v[180:181] op_sel_hi:[1,0]
	v_pk_mul_f32 v[152:153], v[92:93], v[180:181] op_sel_hi:[1,0]
	v_pk_mul_f32 v[158:159], v[90:91], v[180:181] op_sel_hi:[1,0]
	v_pk_mul_f32 v[174:175], v[88:89], v[180:181] op_sel_hi:[1,0]
	v_cvt_pk_bf16_f32 v152, v152, v153
	v_cvt_pk_bf16_f32 v153, v154, v155
	v_cvt_pk_bf16_f32 v154, v174, v175
; DEV bf16x8 pack8(f32x4 a, f32x4 b) { u32x4 w; w.x = cvt_pk_bf16(a[0], a[1]); w.y = cvt_pk_bf16(a[2], a[3]); w.z = cvt_pk_bf16(b[0], b[1]); w.w = cvt_pk_bf16(b[2], b[3]); return __builtin_bit_cast(bf16x8, w); }
; DEV u32x2 pack4(f32x4 a) { u32x2 w; w.x = cvt_pk_bf16(a[0], a[1]); w.y = cvt_pk_bf16(a[2], a[3]); return w; }
; DEV f32x4 gelu4(f32x4 v) { f32x2 a = gelu_pk((f32x2){v[0], v[1]}), b = gelu_pk((f32x2){v[2], v[3]}); return (f32x4){a.x, a.y, b.x, b.y}; }
; template <int ACT, bool PERM>
; DEV void store_bf16_tile(AccRef acc, u16* O, int ld, int row0, int col0, const float* ss) {
;     ...
;         for (int m = 0; m < 4; ++m) { u16* rowp = O + (size_t)(row0 + ai * 128 + m * 16) * ld + col0; const float rs = rsv[ai][m];
; #pragma unroll
;             for (int bj = 0; bj < 2; ++bj) { f32x4 v0 = acc[ai][bj][m][0] * rs, v1 = acc[ai][bj][m][1] * rs; if (ACT == 1) { v0 = gelu4(v0); v1 = gelu4(v1); }
;                 if (PERM) *(u32x4*)(rowp + bj * 128) = __builtin_bit_cast(u32x4, pack8(v0, v1));
;                 else { *(u32x2*)(rowp + bj * 128) = pack4(v0); *(u32x2*)(rowp + bj * 128 + 16) = pack4(v1); } } }
	v_cvt_pk_bf16_f32 v155, v158, v159
	global_store_dwordx4 v[134:135], v[152:155], off
	v_pk_mul_f32 v[158:159], v[82:83], v[180:181] op_sel_hi:[1,0]
	v_pk_mul_f32 v[174:175], v[80:81], v[180:181] op_sel_hi:[1,0]
	v_pk_mul_f32 v[154:155], v[86:87], v[180:181] op_sel_hi:[1,0]
	v_pk_mul_f32 v[152:153], v[84:85], v[180:181] op_sel_hi:[1,0]
	v_mul_f32_e32 v129, 0x4b800000, v128
	v_cvt_pk_bf16_f32 v152, v152, v153
	v_cvt_pk_bf16_f32 v153, v154, v155
	v_cvt_pk_bf16_f32 v154, v174, v175
	v_cvt_pk_bf16_f32 v155, v158, v159
	global_store_dwordx4 v[134:135], v[152:155], off offset:256
	v_pk_mul_f32 v[158:159], v[74:75], v[178:179] op_sel_hi:[1,0]
	v_pk_mul_f32 v[174:175], v[72:73], v[178:179] op_sel_hi:[1,0]
	v_pk_mul_f32 v[154:155], v[78:79], v[178:179] op_sel_hi:[1,0]
	v_pk_mul_f32 v[152:153], v[76:77], v[178:179] op_sel_hi:[1,0]
	v_mad_i64_i32 v[134:135], s[0:1], v176, s9, v[132:133]
	v_cvt_pk_bf16_f32 v152, v152, v153
	v_cvt_pk_bf16_f32 v153, v154, v155
	v_cvt_pk_bf16_f32 v154, v174, v175
	v_cvt_pk_bf16_f32 v155, v158, v159
	global_store_dwordx4 v[134:135], v[152:155], off
	v_pk_mul_f32 v[158:159], v[66:67], v[178:179] op_sel_hi:[1,0]
	v_pk_mul_f32 v[174:175], v[64:65], v[178:179] op_sel_hi:[1,0]
	v_pk_mul_f32 v[154:155], v[70:71], v[178:179] op_sel_hi:[1,0]
	v_pk_mul_f32 v[152:153], v[68:69], v[178:179] op_sel_hi:[1,0]
	v_cndmask_b32_e32 v128, v128, v129, vcc
	v_cvt_pk_bf16_f32 v152, v152, v153
	v_cvt_pk_bf16_f32 v153, v154, v155
	v_cvt_pk_bf16_f32 v154, v174, v175
	v_cvt_pk_bf16_f32 v155, v158, v159
	global_store_dwordx4 v[134:135], v[152:155], off offset:256
	v_pk_mul_f32 v[158:159], v[58:59], v[188:189] op_sel_hi:[1,0]
	v_pk_mul_f32 v[174:175], v[56:57], v[188:189] op_sel_hi:[1,0]
	v_pk_mul_f32 v[154:155], v[62:63], v[188:189] op_sel_hi:[1,0]
	v_pk_mul_f32 v[152:153], v[60:61], v[188:189] op_sel_hi:[1,0]
	v_mad_i64_i32 v[134:135], s[0:1], v182, s9, v[132:133]
	v_cvt_pk_bf16_f32 v152, v152, v153
	v_cvt_pk_bf16_f32 v153, v154, v155
	v_cvt_pk_bf16_f32 v154, v174, v175
	v_cvt_pk_bf16_f32 v155, v158, v159
	global_store_dwordx4 v[134:135], v[152:155], off
	v_pk_mul_f32 v[158:159], v[50:51], v[188:189] op_sel_hi:[1,0]
	v_pk_mul_f32 v[174:175], v[48:49], v[188:189] op_sel_hi:[1,0]
	v_pk_mul_f32 v[154:155], v[54:55], v[188:189] op_sel_hi:[1,0]
	v_pk_mul_f32 v[152:153], v[52:53], v[188:189] op_sel_hi:[1,0]
	v_rsq_f32_e32 v128, v128
	v_cvt_pk_bf16_f32 v152, v152, v153
	v_cvt_pk_bf16_f32 v153, v154, v155
	v_cvt_pk_bf16_f32 v154, v174, v175
	v_cvt_pk_bf16_f32 v155, v158, v159
	global_store_dwordx4 v[134:135], v[152:155], off offset:256
	v_pk_mul_f32 v[158:159], v[42:43], v[186:187] op_sel_hi:[1,0]
	v_pk_mul_f32 v[174:175], v[40:41], v[186:187] op_sel_hi:[1,0]
	v_pk_mul_f32 v[154:155], v[46:47], v[186:187] op_sel_hi:[1,0]
	v_pk_mul_f32 v[152:153], v[44:45], v[186:187] op_sel_hi:[1,0]
	v_mad_i64_i32 v[134:135], s[0:1], v184, s9, v[132:133]
	v_cvt_pk_bf16_f32 v152, v152, v153
	v_cvt_pk_bf16_f32 v153, v154, v155
	v_cvt_pk_bf16_f32 v154, v174, v175
	v_cvt_pk_bf16_f32 v155, v158, v159
	global_store_dwordx4 v[134:135], v[152:155], off
	v_pk_mul_f32 v[158:159], v[34:35], v[186:187] op_sel_hi:[1,0]
	v_pk_mul_f32 v[174:175], v[32:33], v[186:187] op_sel_hi:[1,0]
	v_pk_mul_f32 v[154:155], v[38:39], v[186:187] op_sel_hi:[1,0]
	v_pk_mul_f32 v[152:153], v[36:37], v[186:187] op_sel_hi:[1,0]
	v_mul_f32_e32 v129, 0x45800000, v128
	v_cvt_pk_bf16_f32 v152, v152, v153
	v_cvt_pk_bf16_f32 v153, v154, v155
	v_cvt_pk_bf16_f32 v154, v174, v175
	v_cvt_pk_bf16_f32 v155, v158, v159
	global_store_dwordx4 v[134:135], v[152:155], off offset:256
	v_pk_mul_f32 v[158:159], v[26:27], v[130:131] op_sel_hi:[1,0]
	v_pk_mul_f32 v[174:175], v[24:25], v[130:131] op_sel_hi:[1,0]
	v_pk_mul_f32 v[154:155], v[30:31], v[130:131] op_sel_hi:[1,0]
	v_pk_mul_f32 v[152:153], v[28:29], v[130:131] op_sel_hi:[1,0]
	v_mad_i64_i32 v[134:135], s[0:1], v190, s9, v[132:133]
	v_cvt_pk_bf16_f32 v152, v152, v153
	v_cvt_pk_bf16_f32 v153, v154, v155
	v_cvt_pk_bf16_f32 v154, v174, v175
	v_cvt_pk_bf16_f32 v155, v158, v159
	global_store_dwordx4 v[134:135], v[152:155], off
	v_pk_mul_f32 v[158:159], v[18:19], v[130:131] op_sel_hi:[1,0]
	v_cndmask_b32_e32 v128, v128, v129, vcc
	v_pk_mul_f32 v[154:155], v[22:23], v[130:131] op_sel_hi:[1,0]
	v_pk_mul_f32 v[152:153], v[20:21], v[130:131] op_sel_hi:[1,0]
	v_pk_mul_f32 v[130:131], v[16:17], v[130:131] op_sel_hi:[1,0]
	v_cvt_pk_bf16_f32 v152, v152, v153
	v_cvt_pk_bf16_f32 v153, v154, v155
	v_cvt_pk_bf16_f32 v154, v130, v131
	v_cvt_pk_bf16_f32 v155, v158, v159
	global_store_dwordx4 v[134:135], v[152:155], off offset:256
	v_mad_i64_i32 v[134:135], s[0:1], v192, s9, v[132:133]
	v_pk_mul_f32 v[132:133], v[14:15], v[128:129] op_sel_hi:[1,0]
	v_pk_mul_f32 v[130:131], v[12:13], v[128:129] op_sel_hi:[1,0]
	v_pk_mul_f32 v[152:153], v[10:11], v[128:129] op_sel_hi:[1,0]
	v_pk_mul_f32 v[154:155], v[8:9], v[128:129] op_sel_hi:[1,0]
	v_cvt_pk_bf16_f32 v130, v130, v131
	v_cvt_pk_bf16_f32 v131, v132, v133
	v_cvt_pk_bf16_f32 v132, v154, v155
	v_cvt_pk_bf16_f32 v133, v152, v153
	global_store_dwordx4 v[134:135], v[130:133], off
	v_pk_mul_f32 v[152:153], v[2:3], v[128:129] op_sel_hi:[1,0]
	v_pk_mul_f32 v[154:155], v[0:1], v[128:129] op_sel_hi:[1,0]
	v_pk_mul_f32 v[130:131], v[6:7], v[128:129] op_sel_hi:[1,0]
	v_pk_mul_f32 v[132:133], v[4:5], v[128:129] op_sel_hi:[1,0]
	v_cvt_pk_bf16_f32 v129, v130, v131
	v_cvt_pk_bf16_f32 v128, v132, v133
	v_cvt_pk_bf16_f32 v130, v154, v155
	v_cvt_pk_bf16_f32 v131, v152, v153
	global_store_dwordx4 v[134:135], v[128:131], off offset:256

; DEV float rowscale(const float* ss, int row) { const f32x4 a = *(const f32x4*)(ss + (size_t)row * 8), b = *(const f32x4*)(ss + (size_t)row * 8 + 4);
;     return rsqrtf(((a[0] + a[1]) + (a[2] + a[3]) + (b[0] + b[1]) + (b[2] + b[3])) * (1.0f / 2048.0f) + EPS); }
; template <int ACT, bool PERM>
; DEV void store_bf16_tile(AccRef acc, u16* O, int ld, int row0, int col0, const float* ss) {
;     ...
;         for (int m = 0; m < 4; ++m) rsv[ai][m] = ss ? rowscale(ss, row0 + ai * 128 + m * 16) : 1.0f;
.LBB0_598:
	s_andn2_b64 vcc, exec, s[0:1]
	s_cbranch_vccnz .LBB0_600
	v_ashrrev_i32_e32 v151, 31, v150
	v_readlane_b32 s14, v251, 39
	v_lshlrev_b64 v[128:129], 5, v[150:151]
	v_readlane_b32 s15, v251, 40
	s_mov_b32 s0, 0x3727c5ac
	s_mov_b32 s16, 0x3a000000
	v_lshl_add_u64 v[132:133], s[14:15], 0, v[128:129]
	v_mov_b32_e32 v128, 0
	v_mov_b32_e32 v129, 0
	v_mov_b32_e32 v130, 0
	v_mov_b32_e32 v131, 0
	s_nop 0
	v_mov_b32_e32 v132, v240
	v_mov_b32_e32 v133, 0
	v_mov_b32_e32 v134, 0
	v_mov_b32_e32 v135, 0
	s_mov_b32 s9, 0x800000
	v_add_u32_e32 v160, s7, v218
	s_waitcnt vmcnt(0)
	v_mov_b32_e32 v152, v133
	v_mov_b32_e32 v153, v134
	v_mov_b32_e32 v133, v135
	v_pk_add_f32 v[154:155], v[152:153], v[132:133]
	v_or_b32_e32 v152, 16, v150
	v_mov_b32_e32 v132, v130
	v_mov_b32_e32 v133, v128
	v_mov_b32_e32 v128, v131
	v_ashrrev_i32_e32 v153, 31, v152
	v_pk_add_f32 v[158:159], v[132:133], v[128:129]
	v_lshlrev_b64 v[128:129], 5, v[152:153]
	v_lshl_add_u64 v[132:133], s[14:15], 0, v[128:129]
	v_mov_b32_e32 v128, 0
	v_mov_b32_e32 v129, 0
	v_mov_b32_e32 v130, 0
	v_mov_b32_e32 v131, 0
	s_nop 0
	v_mov_b32_e32 v132, v241
	v_mov_b32_e32 v133, 0
	v_mov_b32_e32 v134, 0
	v_mov_b32_e32 v135, 0
	s_waitcnt vmcnt(0)
	v_mov_b32_e32 v174, v133
	v_mov_b32_e32 v175, v134
	v_mov_b32_e32 v133, v135
	v_pk_add_f32 v[132:133], v[174:175], v[132:133]
	v_mov_b32_e32 v134, v130
	v_mov_b32_e32 v135, v128
	v_mov_b32_e32 v128, v131
	v_pk_add_f32 v[128:129], v[134:135], v[128:129]
	v_mov_b32_e32 v130, v132
	v_mov_b32_e32 v131, v154
	v_mov_b32_e32 v154, v133
	v_pk_add_f32 v[130:131], v[130:131], v[154:155]
	v_mov_b32_e32 v132, v129
	v_mov_b32_e32 v133, v159
	v_pk_add_f32 v[130:131], v[130:131], v[132:133]
	v_mov_b32_e32 v129, v158
	v_pk_add_f32 v[128:129], v[128:129], v[130:131]
	v_mov_b64_e32 v[158:159], s[0:1]
	v_pk_fma_f32 v[128:129], v[128:129], s[16:17], v[158:159] op_sel_hi:[1,0,0]
	v_or_b32_e32 v174, 32, v150
	v_mul_f32_e32 v130, 0x4b800000, v129
	v_cmp_gt_f32_e64 s[0:1], s9, v129
	v_cmp_gt_f32_e32 vcc, s9, v128
	v_ashrrev_i32_e32 v175, 31, v174
	v_cndmask_b32_e64 v129, v129, v130, s[0:1]
	v_rsq_f32_e32 v129, v129
	s_nop 0
	v_mul_f32_e32 v130, 0x45800000, v129
	v_cndmask_b32_e64 v156, v129, v130, s[0:1]
	v_mul_f32_e32 v129, 0x4b800000, v128
	v_cndmask_b32_e32 v128, v128, v129, vcc
	v_rsq_f32_e32 v128, v128
	s_nop 0
	v_mul_f32_e32 v129, 0x45800000, v128
	v_cndmask_b32_e32 v154, v128, v129, vcc
	v_lshlrev_b64 v[128:129], 5, v[174:175]
	v_lshl_add_u64 v[132:133], s[14:15], 0, v[128:129]
	v_mov_b32_e32 v128, 0
	v_mov_b32_e32 v129, 0
	v_mov_b32_e32 v130, 0
	v_mov_b32_e32 v131, 0
	s_nop 0
	v_mov_b32_e32 v132, v242
	v_mov_b32_e32 v133, 0
	v_mov_b32_e32 v134, 0
	v_mov_b32_e32 v135, 0
	s_waitcnt vmcnt(0)
	v_mov_b32_e32 v176, v133
	v_mov_b32_e32 v177, v134
	v_mov_b32_e32 v133, v135
	v_pk_add_f32 v[178:179], v[176:177], v[132:133]
	v_or_b32_e32 v176, 48, v150
	v_mov_b32_e32 v132, v130
	v_mov_b32_e32 v133, v128
	v_mov_b32_e32 v128, v131
	v_ashrrev_i32_e32 v177, 31, v176
	v_pk_add_f32 v[182:183], v[132:133], v[128:129]
	v_lshlrev_b64 v[128:129], 5, v[176:177]
	v_lshl_add_u64 v[132:133], s[14:15], 0, v[128:129]
	v_mov_b32_e32 v128, 0
	v_mov_b32_e32 v129, 0
	v_mov_b32_e32 v130, 0
	v_mov_b32_e32 v131, 0
	s_nop 0
	v_mov_b32_e32 v132, v243
	v_mov_b32_e32 v133, 0
	v_mov_b32_e32 v134, 0
	v_mov_b32_e32 v135, 0
	s_waitcnt vmcnt(0)
	v_mov_b32_e32 v184, v133
	v_mov_b32_e32 v185, v134
	v_mov_b32_e32 v133, v135
	v_pk_add_f32 v[132:133], v[184:185], v[132:133]
	v_mov_b32_e32 v134, v130
	v_mov_b32_e32 v135, v128
	v_mov_b32_e32 v128, v131
	v_pk_add_f32 v[128:129], v[134:135], v[128:129]
	v_mov_b32_e32 v130, v132
	v_mov_b32_e32 v131, v178
	v_mov_b32_e32 v178, v133
	v_pk_add_f32 v[130:131], v[130:131], v[178:179]
	v_mov_b32_e32 v132, v129
	v_mov_b32_e32 v133, v183
	v_pk_add_f32 v[130:131], v[130:131], v[132:133]
	v_mov_b32_e32 v129, v182
	v_pk_add_f32 v[128:129], v[128:129], v[130:131]
	v_add_u32_e32 v182, 0x80, v150
	v_pk_fma_f32 v[128:129], v[128:129], s[16:17], v[158:159] op_sel_hi:[1,0,0]
	v_ashrrev_i32_e32 v183, 31, v182
	v_mul_f32_e32 v130, 0x4b800000, v129
	v_cmp_gt_f32_e64 s[0:1], s9, v129
	v_cmp_gt_f32_e32 vcc, s9, v128
	s_nop 0
	v_cndmask_b32_e64 v129, v129, v130, s[0:1]
	v_rsq_f32_e32 v129, v129
	s_nop 0
	v_mul_f32_e32 v130, 0x45800000, v129
	v_cndmask_b32_e64 v180, v129, v130, s[0:1]
	v_mul_f32_e32 v129, 0x4b800000, v128
	v_cndmask_b32_e32 v128, v128, v129, vcc
	v_rsq_f32_e32 v128, v128
	s_nop 0
	v_mul_f32_e32 v129, 0x45800000, v128
	v_cndmask_b32_e32 v178, v128, v129, vcc
	v_lshlrev_b64 v[128:129], 5, v[182:183]
	v_lshl_add_u64 v[132:133], s[14:15], 0, v[128:129]
	v_mov_b32_e32 v128, 0
	v_mov_b32_e32 v129, 0
	v_mov_b32_e32 v130, 0
	v_mov_b32_e32 v131, 0
	s_nop 0
	v_mov_b32_e32 v132, v244
	v_mov_b32_e32 v133, 0
	v_mov_b32_e32 v134, 0
	v_mov_b32_e32 v135, 0
	s_waitcnt vmcnt(0)
	v_mov_b32_e32 v184, v133
	v_mov_b32_e32 v185, v134
	v_mov_b32_e32 v133, v135
	v_pk_add_f32 v[186:187], v[184:185], v[132:133]
	v_add_u32_e32 v184, 0x90, v150
	v_mov_b32_e32 v132, v130
	v_mov_b32_e32 v133, v128
	v_mov_b32_e32 v128, v131
	v_ashrrev_i32_e32 v185, 31, v184
	v_pk_add_f32 v[188:189], v[132:133], v[128:129]
	v_lshlrev_b64 v[128:129], 5, v[184:185]
	v_lshl_add_u64 v[132:133], s[14:15], 0, v[128:129]
	v_mov_b32_e32 v128, 0
	v_mov_b32_e32 v129, 0
	v_mov_b32_e32 v130, 0
	v_mov_b32_e32 v131, 0
	s_nop 0
	v_mov_b32_e32 v132, v245
	v_mov_b32_e32 v133, 0
	v_mov_b32_e32 v134, 0
	v_mov_b32_e32 v135, 0
	s_waitcnt vmcnt(0)
; DEV bf16x8 pack8(f32x4 a, f32x4 b) { u32x4 w; w.x = cvt_pk_bf16(a[0], a[1]); w.y = cvt_pk_bf16(a[2], a[3]); w.z = cvt_pk_bf16(b[0], b[1]); w.w = cvt_pk_bf16(b[2], b[3]); return __builtin_bit_cast(bf16x8, w); }
; DEV u32x2 pack4(f32x4 a) { u32x2 w; w.x = cvt_pk_bf16(a[0], a[1]); w.y = cvt_pk_bf16(a[2], a[3]); return w; }
; DEV f32x4 gelu4(f32x4 v) { f32x2 a = gelu_pk((f32x2){v[0], v[1]}), b = gelu_pk((f32x2){v[2], v[3]}); return (f32x4){a.x, a.y, b.x, b.y}; }
; DEV float rowscale(const float* ss, int row) { const f32x4 a = *(const f32x4*)(ss + (size_t)row * 8), b = *(const f32x4*)(ss + (size_t)row * 8 + 4);
;     return rsqrtf(((a[0] + a[1]) + (a[2] + a[3]) + (b[0] + b[1]) + (b[2] + b[3])) * (1.0f / 2048.0f) + EPS); }
; template <int ACT, bool PERM>
; DEV void store_bf16_tile(AccRef acc, u16* O, int ld, int row0, int col0, const float* ss) {
;     ...
;         for (int m = 0; m < 4; ++m) rsv[ai][m] = ss ? rowscale(ss, row0 + ai * 128 + m * 16) : 1.0f;
; #pragma unroll
;     for (int ai = 0; ai < 2; ++ai)
; #pragma unroll
;         for (int m = 0; m < 4; ++m) { u16* rowp = O + (size_t)(row0 + ai * 128 + m * 16) * ld + col0; const float rs = rsv[ai][m];
; #pragma unroll
;             for (int bj = 0; bj < 2; ++bj) { f32x4 v0 = acc[ai][bj][m][0] * rs, v1 = acc[ai][bj][m][1] * rs; if (ACT == 1) { v0 = gelu4(v0); v1 = gelu4(v1); }
;                 if (PERM) *(u32x4*)(rowp + bj * 128) = __builtin_bit_cast(u32x4, pack8(v0, v1));
;                 else { *(u32x2*)(rowp + bj * 128) = pack4(v0); *(u32x2*)(rowp + bj * 128 + 16) = pack4(v1); } } }
	v_mov_b32_e32 v190, v133
	v_mov_b32_e32 v191, v134
	v_mov_b32_e32 v133, v135
	v_pk_add_f32 v[132:133], v[190:191], v[132:133]
	v_mov_b32_e32 v134, v130
	v_mov_b32_e32 v135, v128
	v_mov_b32_e32 v128, v131
	v_pk_add_f32 v[128:129], v[134:135], v[128:129]
	v_mov_b32_e32 v130, v132
	v_mov_b32_e32 v131, v186
	v_mov_b32_e32 v186, v133
	v_pk_add_f32 v[130:131], v[130:131], v[186:187]
	v_mov_b32_e32 v132, v129
	v_mov_b32_e32 v133, v189
	v_pk_add_f32 v[130:131], v[130:131], v[132:133]
	v_mov_b32_e32 v129, v188
	v_pk_add_f32 v[128:129], v[128:129], v[130:131]
	v_add_u32_e32 v190, 0xa0, v150
	v_pk_fma_f32 v[128:129], v[128:129], s[16:17], v[158:159] op_sel_hi:[1,0,0]
	v_ashrrev_i32_e32 v191, 31, v190
	v_mul_f32_e32 v130, 0x4b800000, v129
	v_cmp_gt_f32_e64 s[0:1], s9, v129
	v_cmp_gt_f32_e32 vcc, s9, v128
	s_nop 0
	v_cndmask_b32_e64 v129, v129, v130, s[0:1]
	v_rsq_f32_e32 v129, v129
	s_nop 0
	v_mul_f32_e32 v130, 0x45800000, v129
	v_cndmask_b32_e64 v188, v129, v130, s[0:1]
	v_mul_f32_e32 v129, 0x4b800000, v128
	v_cndmask_b32_e32 v128, v128, v129, vcc
	v_rsq_f32_e32 v128, v128
	s_nop 0
	v_mul_f32_e32 v129, 0x45800000, v128
	v_cndmask_b32_e32 v186, v128, v129, vcc
	v_lshlrev_b64 v[128:129], 5, v[190:191]
	v_lshl_add_u64 v[132:133], s[14:15], 0, v[128:129]
	v_mov_b32_e32 v128, 0
	v_mov_b32_e32 v129, 0
	v_mov_b32_e32 v130, 0
	v_mov_b32_e32 v131, 0
	s_nop 0
	v_mov_b32_e32 v132, v246
	v_mov_b32_e32 v133, 0
	v_mov_b32_e32 v134, 0
	v_mov_b32_e32 v135, 0
	s_waitcnt vmcnt(0)
	v_mov_b32_e32 v192, v133
	v_mov_b32_e32 v193, v134
	v_mov_b32_e32 v133, v135
	v_pk_add_f32 v[196:197], v[192:193], v[132:133]
	v_add_u32_e32 v192, 0xb0, v150
	v_mov_b32_e32 v132, v130
	v_mov_b32_e32 v133, v128
	v_mov_b32_e32 v128, v131
	v_ashrrev_i32_e32 v193, 31, v192
	v_pk_add_f32 v[194:195], v[132:133], v[128:129]
	v_lshlrev_b64 v[128:129], 5, v[192:193]
	v_lshl_add_u64 v[132:133], s[14:15], 0, v[128:129]
	v_mov_b32_e32 v128, 0
	v_mov_b32_e32 v129, 0
	v_mov_b32_e32 v130, 0
	v_mov_b32_e32 v131, 0
	s_nop 0
	v_mov_b32_e32 v132, v247
	v_mov_b32_e32 v133, 0
	v_mov_b32_e32 v134, 0
	v_mov_b32_e32 v135, 0
	s_waitcnt vmcnt(0)
	v_mov_b32_e32 v214, v133
	v_mov_b32_e32 v215, v134
	v_mov_b32_e32 v133, v135
	v_pk_add_f32 v[132:133], v[214:215], v[132:133]
	v_mov_b32_e32 v134, v130
	v_mov_b32_e32 v135, v128
	v_mov_b32_e32 v128, v131
	v_pk_add_f32 v[128:129], v[134:135], v[128:129]
	v_mov_b32_e32 v130, v132
	v_mov_b32_e32 v131, v196
	v_mov_b32_e32 v196, v133
	v_pk_add_f32 v[130:131], v[130:131], v[196:197]
	v_mov_b32_e32 v132, v129
	v_mov_b32_e32 v133, v195
	v_pk_add_f32 v[130:131], v[130:131], v[132:133]
	v_mov_b32_e32 v129, v194
	v_pk_add_f32 v[128:129], v[128:129], v[130:131]
	v_lshlrev_b64 v[134:135], 12, v[150:151]
	v_pk_fma_f32 v[128:129], v[128:129], s[16:17], v[158:159] op_sel_hi:[1,0,0]
	v_pk_mul_f32 v[158:159], v[126:127], v[156:157] op_sel_hi:[1,0]
	v_mul_f32_e32 v130, 0x4b800000, v129
	v_cmp_gt_f32_e64 s[0:1], s9, v129
	v_pk_mul_f32 v[194:195], v[124:125], v[156:157] op_sel_hi:[1,0]
	v_pk_mul_f32 v[214:215], v[122:123], v[156:157] op_sel_hi:[1,0]
	v_cndmask_b32_e64 v129, v129, v130, s[0:1]
	v_rsq_f32_e32 v129, v129
	v_pk_mul_f32 v[196:197], v[120:121], v[156:157] op_sel_hi:[1,0]
	v_cvt_pk_bf16_f32 v194, v194, v195
	v_cvt_pk_bf16_f32 v195, v158, v159
	v_mul_f32_e32 v130, 0x45800000, v129
	v_cndmask_b32_e64 v130, v129, v130, s[0:1]
	v_readlane_b32 s0, v251, 3
	v_readlane_b32 s1, v251, 4
	v_cvt_pk_bf16_f32 v196, v196, v197
	v_cvt_pk_bf16_f32 v197, v214, v215
	v_lshl_add_u64 v[132:133], v[160:161], 1, s[0:1]
	v_lshl_add_u64 v[134:135], v[132:133], 0, v[134:135]
	global_store_dwordx4 v[134:135], v[194:197], off
	v_pk_mul_f32 v[158:159], v[118:119], v[156:157] op_sel_hi:[1,0]
	v_pk_mul_f32 v[214:215], v[114:115], v[156:157] op_sel_hi:[1,0]
	v_pk_mul_f32 v[194:195], v[116:117], v[156:157] op_sel_hi:[1,0]
	v_pk_mul_f32 v[196:197], v[112:113], v[156:157] op_sel_hi:[1,0]
	v_cvt_pk_bf16_f32 v194, v194, v195
	v_cvt_pk_bf16_f32 v195, v158, v159
	v_cvt_pk_bf16_f32 v196, v196, v197
	v_cvt_pk_bf16_f32 v197, v214, v215
	global_store_dwordx4 v[134:135], v[194:197], off offset:256
	v_lshlrev_b64 v[134:135], 12, v[152:153]
	v_pk_mul_f32 v[152:153], v[110:111], v[154:155] op_sel_hi:[1,0]
	v_pk_mul_f32 v[158:159], v[108:109], v[154:155] op_sel_hi:[1,0]
	v_pk_mul_f32 v[214:215], v[106:107], v[154:155] op_sel_hi:[1,0]
	v_pk_mul_f32 v[196:197], v[104:105], v[154:155] op_sel_hi:[1,0]
	v_lshl_add_u64 v[134:135], v[132:133], 0, v[134:135]
	v_cvt_pk_bf16_f32 v194, v158, v159
	v_cvt_pk_bf16_f32 v195, v152, v153
	v_cvt_pk_bf16_f32 v196, v196, v197
	v_cvt_pk_bf16_f32 v197, v214, v215
	global_store_dwordx4 v[134:135], v[194:197], off
	v_pk_mul_f32 v[158:159], v[102:103], v[154:155] op_sel_hi:[1,0]
	v_pk_mul_f32 v[152:153], v[100:101], v[154:155] op_sel_hi:[1,0]
	v_pk_mul_f32 v[194:195], v[98:99], v[154:155] op_sel_hi:[1,0]
	v_pk_mul_f32 v[154:155], v[96:97], v[154:155] op_sel_hi:[1,0]
	v_cvt_pk_bf16_f32 v152, v152, v153
	v_cvt_pk_bf16_f32 v153, v158, v159
	v_cvt_pk_bf16_f32 v154, v154, v155
	v_cvt_pk_bf16_f32 v155, v194, v195
	global_store_dwordx4 v[134:135], v[152:155], off offset:256
	v_lshlrev_b64 v[134:135], 12, v[174:175]
	v_pk_mul_f32 v[158:159], v[90:91], v[180:181] op_sel_hi:[1,0]
	v_pk_mul_f32 v[154:155], v[94:95], v[180:181] op_sel_hi:[1,0]
	v_pk_mul_f32 v[152:153], v[92:93], v[180:181] op_sel_hi:[1,0]
	v_pk_mul_f32 v[174:175], v[88:89], v[180:181] op_sel_hi:[1,0]
	v_lshl_add_u64 v[134:135], v[132:133], 0, v[134:135]
	v_cvt_pk_bf16_f32 v152, v152, v153
	v_cvt_pk_bf16_f32 v153, v154, v155
	v_cvt_pk_bf16_f32 v154, v174, v175
	v_cvt_pk_bf16_f32 v155, v158, v159
	global_store_dwordx4 v[134:135], v[152:155], off
; DEV bf16x8 pack8(f32x4 a, f32x4 b) { u32x4 w; w.x = cvt_pk_bf16(a[0], a[1]); w.y = cvt_pk_bf16(a[2], a[3]); w.z = cvt_pk_bf16(b[0], b[1]); w.w = cvt_pk_bf16(b[2], b[3]); return __builtin_bit_cast(bf16x8, w); }
; DEV u32x2 pack4(f32x4 a) { u32x2 w; w.x = cvt_pk_bf16(a[0], a[1]); w.y = cvt_pk_bf16(a[2], a[3]); return w; }
; DEV f32x4 gelu4(f32x4 v) { f32x2 a = gelu_pk((f32x2){v[0], v[1]}), b = gelu_pk((f32x2){v[2], v[3]}); return (f32x4){a.x, a.y, b.x, b.y}; }
; template <int ACT, bool PERM>
; DEV void store_bf16_tile(AccRef acc, u16* O, int ld, int row0, int col0, const float* ss) {
;     ...
;         for (int m = 0; m < 4; ++m) { u16* rowp = O + (size_t)(row0 + ai * 128 + m * 16) * ld + col0; const float rs = rsv[ai][m];
; #pragma unroll
;             for (int bj = 0; bj < 2; ++bj) { f32x4 v0 = acc[ai][bj][m][0] * rs, v1 = acc[ai][bj][m][1] * rs; if (ACT == 1) { v0 = gelu4(v0); v1 = gelu4(v1); }
;                 if (PERM) *(u32x4*)(rowp + bj * 128) = __builtin_bit_cast(u32x4, pack8(v0, v1));
;                 else { *(u32x2*)(rowp + bj * 128) = pack4(v0); *(u32x2*)(rowp + bj * 128 + 16) = pack4(v1); } } }
	v_pk_mul_f32 v[158:159], v[82:83], v[180:181] op_sel_hi:[1,0]
	v_pk_mul_f32 v[174:175], v[80:81], v[180:181] op_sel_hi:[1,0]
	v_pk_mul_f32 v[154:155], v[86:87], v[180:181] op_sel_hi:[1,0]
	v_pk_mul_f32 v[152:153], v[84:85], v[180:181] op_sel_hi:[1,0]
	v_cmp_gt_f32_e32 vcc, s9, v128
	v_cvt_pk_bf16_f32 v152, v152, v153
	v_cvt_pk_bf16_f32 v153, v154, v155
	v_cvt_pk_bf16_f32 v154, v174, v175
	v_cvt_pk_bf16_f32 v155, v158, v159
	global_store_dwordx4 v[134:135], v[152:155], off offset:256
	v_lshlrev_b64 v[134:135], 12, v[176:177]
	v_pk_mul_f32 v[158:159], v[74:75], v[178:179] op_sel_hi:[1,0]
	v_pk_mul_f32 v[154:155], v[78:79], v[178:179] op_sel_hi:[1,0]
	v_pk_mul_f32 v[152:153], v[76:77], v[178:179] op_sel_hi:[1,0]
	v_pk_mul_f32 v[174:175], v[72:73], v[178:179] op_sel_hi:[1,0]
	v_lshl_add_u64 v[134:135], v[132:133], 0, v[134:135]
	v_cvt_pk_bf16_f32 v152, v152, v153
	v_cvt_pk_bf16_f32 v153, v154, v155
	v_cvt_pk_bf16_f32 v154, v174, v175
	v_cvt_pk_bf16_f32 v155, v158, v159
	global_store_dwordx4 v[134:135], v[152:155], off
	v_pk_mul_f32 v[158:159], v[66:67], v[178:179] op_sel_hi:[1,0]
	v_pk_mul_f32 v[174:175], v[64:65], v[178:179] op_sel_hi:[1,0]
	v_pk_mul_f32 v[154:155], v[70:71], v[178:179] op_sel_hi:[1,0]
	v_pk_mul_f32 v[152:153], v[68:69], v[178:179] op_sel_hi:[1,0]
	v_mul_f32_e32 v129, 0x4b800000, v128
	v_cvt_pk_bf16_f32 v152, v152, v153
	v_cvt_pk_bf16_f32 v153, v154, v155
	v_cvt_pk_bf16_f32 v154, v174, v175
	v_cvt_pk_bf16_f32 v155, v158, v159
	global_store_dwordx4 v[134:135], v[152:155], off offset:256
	v_lshlrev_b64 v[134:135], 12, v[182:183]
	v_pk_mul_f32 v[158:159], v[58:59], v[188:189] op_sel_hi:[1,0]
	v_pk_mul_f32 v[154:155], v[62:63], v[188:189] op_sel_hi:[1,0]
	v_pk_mul_f32 v[152:153], v[60:61], v[188:189] op_sel_hi:[1,0]
	v_pk_mul_f32 v[174:175], v[56:57], v[188:189] op_sel_hi:[1,0]
	v_lshl_add_u64 v[134:135], v[132:133], 0, v[134:135]
	v_cvt_pk_bf16_f32 v152, v152, v153
	v_cvt_pk_bf16_f32 v153, v154, v155
	v_cvt_pk_bf16_f32 v154, v174, v175
	v_cvt_pk_bf16_f32 v155, v158, v159
	global_store_dwordx4 v[134:135], v[152:155], off
	v_pk_mul_f32 v[158:159], v[50:51], v[188:189] op_sel_hi:[1,0]
	v_pk_mul_f32 v[174:175], v[48:49], v[188:189] op_sel_hi:[1,0]
	v_pk_mul_f32 v[154:155], v[54:55], v[188:189] op_sel_hi:[1,0]
	v_pk_mul_f32 v[152:153], v[52:53], v[188:189] op_sel_hi:[1,0]
	v_cndmask_b32_e32 v128, v128, v129, vcc
	v_cvt_pk_bf16_f32 v152, v152, v153
	v_cvt_pk_bf16_f32 v153, v154, v155
	v_cvt_pk_bf16_f32 v154, v174, v175
	v_cvt_pk_bf16_f32 v155, v158, v159
	global_store_dwordx4 v[134:135], v[152:155], off offset:256
	v_lshlrev_b64 v[134:135], 12, v[184:185]
	v_pk_mul_f32 v[158:159], v[42:43], v[186:187] op_sel_hi:[1,0]
	v_pk_mul_f32 v[154:155], v[46:47], v[186:187] op_sel_hi:[1,0]
	v_pk_mul_f32 v[152:153], v[44:45], v[186:187] op_sel_hi:[1,0]
	v_pk_mul_f32 v[174:175], v[40:41], v[186:187] op_sel_hi:[1,0]
	v_lshl_add_u64 v[134:135], v[132:133], 0, v[134:135]
	v_cvt_pk_bf16_f32 v152, v152, v153
	v_cvt_pk_bf16_f32 v153, v154, v155
	v_cvt_pk_bf16_f32 v154, v174, v175
	v_cvt_pk_bf16_f32 v155, v158, v159
	v_rsq_f32_e32 v128, v128
	global_store_dwordx4 v[134:135], v[152:155], off
	v_pk_mul_f32 v[158:159], v[34:35], v[186:187] op_sel_hi:[1,0]
	v_pk_mul_f32 v[174:175], v[32:33], v[186:187] op_sel_hi:[1,0]
	v_pk_mul_f32 v[154:155], v[38:39], v[186:187] op_sel_hi:[1,0]
	v_pk_mul_f32 v[152:153], v[36:37], v[186:187] op_sel_hi:[1,0]
	v_mul_f32_e32 v129, 0x45800000, v128
	v_cvt_pk_bf16_f32 v152, v152, v153
	v_cvt_pk_bf16_f32 v153, v154, v155
	v_cvt_pk_bf16_f32 v154, v174, v175
	v_cvt_pk_bf16_f32 v155, v158, v159
	global_store_dwordx4 v[134:135], v[152:155], off offset:256
	v_lshlrev_b64 v[134:135], 12, v[190:191]
	v_pk_mul_f32 v[158:159], v[26:27], v[130:131] op_sel_hi:[1,0]
	v_pk_mul_f32 v[154:155], v[30:31], v[130:131] op_sel_hi:[1,0]
	v_pk_mul_f32 v[152:153], v[28:29], v[130:131] op_sel_hi:[1,0]
	v_pk_mul_f32 v[174:175], v[24:25], v[130:131] op_sel_hi:[1,0]
	v_lshl_add_u64 v[134:135], v[132:133], 0, v[134:135]
	v_cvt_pk_bf16_f32 v152, v152, v153
	v_cvt_pk_bf16_f32 v153, v154, v155
	v_cvt_pk_bf16_f32 v154, v174, v175
	v_cvt_pk_bf16_f32 v155, v158, v159
	global_store_dwordx4 v[134:135], v[152:155], off
	v_pk_mul_f32 v[158:159], v[18:19], v[130:131] op_sel_hi:[1,0]
	v_cndmask_b32_e32 v128, v128, v129, vcc
	v_pk_mul_f32 v[154:155], v[22:23], v[130:131] op_sel_hi:[1,0]
	v_pk_mul_f32 v[152:153], v[20:21], v[130:131] op_sel_hi:[1,0]
	v_pk_mul_f32 v[130:131], v[16:17], v[130:131] op_sel_hi:[1,0]
	v_cvt_pk_bf16_f32 v152, v152, v153
	v_cvt_pk_bf16_f32 v153, v154, v155
	v_cvt_pk_bf16_f32 v154, v130, v131
	v_cvt_pk_bf16_f32 v155, v158, v159
	v_lshlrev_b64 v[130:131], 12, v[192:193]
	global_store_dwordx4 v[134:135], v[152:155], off offset:256
	v_lshl_add_u64 v[134:135], v[132:133], 0, v[130:131]
	v_pk_mul_f32 v[132:133], v[14:15], v[128:129] op_sel_hi:[1,0]
	v_pk_mul_f32 v[130:131], v[12:13], v[128:129] op_sel_hi:[1,0]
	v_pk_mul_f32 v[152:153], v[10:11], v[128:129] op_sel_hi:[1,0]
	v_pk_mul_f32 v[154:155], v[8:9], v[128:129] op_sel_hi:[1,0]
	v_cvt_pk_bf16_f32 v130, v130, v131
	v_cvt_pk_bf16_f32 v131, v132, v133
	v_cvt_pk_bf16_f32 v132, v154, v155
	v_cvt_pk_bf16_f32 v133, v152, v153
	global_store_dwordx4 v[134:135], v[130:133], off
	v_pk_mul_f32 v[152:153], v[2:3], v[128:129] op_sel_hi:[1,0]
	v_pk_mul_f32 v[154:155], v[0:1], v[128:129] op_sel_hi:[1,0]
	v_pk_mul_f32 v[130:131], v[6:7], v[128:129] op_sel_hi:[1,0]
	v_pk_mul_f32 v[132:133], v[4:5], v[128:129] op_sel_hi:[1,0]
	v_cvt_pk_bf16_f32 v129, v130, v131
	v_cvt_pk_bf16_f32 v128, v132, v133
	v_cvt_pk_bf16_f32 v130, v154, v155
	v_cvt_pk_bf16_f32 v131, v152, v153
	global_store_dwordx4 v[134:135], v[128:131], off offset:256

; DEV f32x4 gelu4(f32x4 v) { f32x2 a = gelu_pk((f32x2){v[0], v[1]}), b = gelu_pk((f32x2){v[2], v[3]}); return (f32x4){a.x, a.y, b.x, b.y}; }
; DEV float rowscale(const float* ss, int row) { const f32x4 a = *(const f32x4*)(ss + (size_t)row * 8), b = *(const f32x4*)(ss + (size_t)row * 8 + 4);
;     return rsqrtf(((a[0] + a[1]) + (a[2] + a[3]) + (b[0] + b[1]) + (b[2] + b[3])) * (1.0f / 2048.0f) + EPS); }
; template <int ACT, bool PERM>
; DEV void store_bf16_tile(AccRef acc, u16* O, int ld, int row0, int col0, const float* ss) {
;     ...
;         for (int m = 0; m < 4; ++m) rsv[ai][m] = ss ? rowscale(ss, row0 + ai * 128 + m * 16) : 1.0f;
;     ...
;             for (int bj = 0; bj < 2; ++bj) { f32x4 v0 = acc[ai][bj][m][0] * rs, v1 = acc[ai][bj][m][1] * rs; if (ACT == 1) { v0 = gelu4(v0); v1 = gelu4(v1); }
.LBB0_601:
	s_andn2_b64 vcc, exec, s[0:1]
	s_cbranch_vccnz .LBB0_584
	v_ashrrev_i32_e32 v151, 31, v150
	v_readlane_b32 s14, v251, 39
	v_lshlrev_b64 v[128:129], 5, v[150:151]
	v_readlane_b32 s15, v251, 40
	v_or_b32_e32 v186, 16, v150
	v_ashrrev_i32_e32 v187, 31, v186
	v_lshl_add_u64 v[132:133], s[14:15], 0, v[128:129]
	v_mov_b32_e32 v128, 0
	v_mov_b32_e32 v129, 0
	v_mov_b32_e32 v130, 0
	v_mov_b32_e32 v131, 0
	s_nop 0
	v_mov_b32_e32 v132, v240
	v_mov_b32_e32 v133, 0
	v_mov_b32_e32 v134, 0
	v_mov_b32_e32 v135, 0
	s_mov_b32 s0, 0x3727c5ac
	v_mov_b64_e32 v[192:193], s[0:1]
	s_mov_b32 s16, 0x3a000000
	v_or_b32_e32 v190, s7, v181
	s_mov_b32 s7, 0x800000
	v_or_b32_e32 v182, 32, v150
	v_ashrrev_i32_e32 v183, 31, v182
	v_or_b32_e32 v178, 48, v150
	v_ashrrev_i32_e32 v179, 31, v178
	v_add_u32_e32 v174, 0x80, v150
	v_ashrrev_i32_e32 v175, 31, v174
	v_ashrrev_i32_e32 v191, 31, v190
	s_mov_b32 s36, 0xbf38aa3b
	s_mov_b32 s18, 0xbe11a98e
	s_mov_b32 s34, 0x3e027906
	s_waitcnt vmcnt(0)
	v_mov_b32_e32 v152, v133
	v_mov_b32_e32 v153, v134
	v_mov_b32_e32 v133, v135
	v_pk_add_f32 v[152:153], v[152:153], v[132:133]
	v_mov_b32_e32 v132, v130
	v_mov_b32_e32 v133, v128
	v_mov_b32_e32 v128, v131
	v_pk_add_f32 v[154:155], v[132:133], v[128:129]
	v_lshlrev_b64 v[128:129], 5, v[186:187]
	v_lshl_add_u64 v[132:133], s[14:15], 0, v[128:129]
	v_mov_b32_e32 v128, 0
	v_mov_b32_e32 v129, 0
	v_mov_b32_e32 v130, 0
	v_mov_b32_e32 v131, 0
	s_nop 0
	v_mov_b32_e32 v132, v241
	v_mov_b32_e32 v133, 0
	v_mov_b32_e32 v134, 0
	v_mov_b32_e32 v135, 0
	s_waitcnt vmcnt(0)
	v_mov_b32_e32 v158, v133
	v_mov_b32_e32 v159, v134
	v_mov_b32_e32 v133, v135
	v_pk_add_f32 v[132:133], v[158:159], v[132:133]
	v_mov_b32_e32 v134, v130
	v_mov_b32_e32 v135, v128
	v_mov_b32_e32 v128, v131
	v_pk_add_f32 v[128:129], v[134:135], v[128:129]
	v_mov_b32_e32 v130, v132
	v_mov_b32_e32 v131, v152
	v_mov_b32_e32 v152, v133
	v_pk_add_f32 v[130:131], v[130:131], v[152:153]
	v_mov_b32_e32 v132, v129
	v_mov_b32_e32 v133, v155
	v_pk_add_f32 v[130:131], v[130:131], v[132:133]
	v_mov_b32_e32 v129, v154
	v_pk_add_f32 v[128:129], v[128:129], v[130:131]
	s_nop 0
	v_pk_fma_f32 v[128:129], v[128:129], s[16:17], v[192:193] op_sel_hi:[1,0,0]
	s_nop 0
	v_mul_f32_e32 v130, 0x4b800000, v129
	v_cmp_gt_f32_e64 s[0:1], s7, v129
	v_cmp_gt_f32_e32 vcc, s7, v128
	s_nop 0
	v_cndmask_b32_e64 v129, v129, v130, s[0:1]
	v_rsq_f32_e32 v129, v129
	s_nop 0
	v_mul_f32_e32 v130, 0x45800000, v129
	v_cndmask_b32_e64 v188, v129, v130, s[0:1]
	v_mul_f32_e32 v129, 0x4b800000, v128
	v_cndmask_b32_e32 v128, v128, v129, vcc
	v_rsq_f32_e32 v128, v128
	v_pk_mul_f32 v[124:125], v[124:125], v[188:189] op_sel_hi:[1,0]
	v_pk_mul_f32 v[126:127], v[126:127], v[188:189] op_sel_hi:[1,0]
	v_pk_mul_f32 v[122:123], v[122:123], v[188:189] op_sel_hi:[1,0]
	v_mul_f32_e32 v129, 0x45800000, v128
	v_cndmask_b32_e32 v184, v128, v129, vcc
	v_lshlrev_b64 v[128:129], 5, v[182:183]
	v_lshl_add_u64 v[132:133], s[14:15], 0, v[128:129]
	v_mov_b32_e32 v128, 0
	v_mov_b32_e32 v129, 0
	v_mov_b32_e32 v130, 0
	v_mov_b32_e32 v131, 0
	s_nop 0
	v_mov_b32_e32 v132, v242
	v_mov_b32_e32 v133, 0
	v_mov_b32_e32 v134, 0
	v_mov_b32_e32 v135, 0
	s_waitcnt vmcnt(0)
	v_mov_b32_e32 v152, v133
	v_mov_b32_e32 v153, v134
	v_mov_b32_e32 v133, v135
	v_pk_add_f32 v[152:153], v[152:153], v[132:133]
	v_mov_b32_e32 v132, v130
	v_mov_b32_e32 v133, v128
	v_mov_b32_e32 v128, v131
	v_pk_add_f32 v[154:155], v[132:133], v[128:129]
	v_lshlrev_b64 v[128:129], 5, v[178:179]
	v_lshl_add_u64 v[132:133], s[14:15], 0, v[128:129]
	v_mov_b32_e32 v128, 0
	v_mov_b32_e32 v129, 0
	v_mov_b32_e32 v130, 0
	v_mov_b32_e32 v131, 0
	s_nop 0
	v_mov_b32_e32 v132, v243
	v_mov_b32_e32 v133, 0
	v_mov_b32_e32 v134, 0
	v_mov_b32_e32 v135, 0
	s_waitcnt vmcnt(0)
	v_mov_b32_e32 v158, v133
	v_mov_b32_e32 v159, v134
	v_mov_b32_e32 v133, v135
	v_pk_add_f32 v[132:133], v[158:159], v[132:133]
	v_mov_b32_e32 v134, v130
	v_mov_b32_e32 v135, v128
	v_mov_b32_e32 v128, v131
	v_pk_add_f32 v[128:129], v[134:135], v[128:129]
	v_mov_b32_e32 v130, v132
	v_mov_b32_e32 v131, v152
	v_mov_b32_e32 v152, v133
	v_pk_add_f32 v[130:131], v[130:131], v[152:153]
	v_mov_b32_e32 v132, v129
	v_mov_b32_e32 v133, v155
	v_pk_add_f32 v[130:131], v[130:131], v[132:133]
	v_mov_b32_e32 v129, v154
	v_pk_add_f32 v[128:129], v[128:129], v[130:131]
	v_add_u32_e32 v158, 0x90, v150
	v_pk_fma_f32 v[128:129], v[128:129], s[16:17], v[192:193] op_sel_hi:[1,0,0]
	v_ashrrev_i32_e32 v159, 31, v158
	v_mul_f32_e32 v130, 0x4b800000, v129
	v_cmp_gt_f32_e64 s[0:1], s7, v129
	v_cmp_gt_f32_e32 vcc, s7, v128
	s_nop 0
	v_cndmask_b32_e64 v129, v129, v130, s[0:1]
	v_rsq_f32_e32 v129, v129
	s_nop 0
	v_mul_f32_e32 v130, 0x45800000, v129
	v_cndmask_b32_e64 v180, v129, v130, s[0:1]
	v_mul_f32_e32 v129, 0x4b800000, v128
	v_cndmask_b32_e32 v128, v128, v129, vcc
	v_rsq_f32_e32 v128, v128
	v_pk_mul_f32 v[92:93], v[92:93], v[180:181] op_sel_hi:[1,0]
	v_pk_mul_f32 v[94:95], v[94:95], v[180:181] op_sel_hi:[1,0]
	v_pk_mul_f32 v[88:89], v[88:89], v[180:181] op_sel_hi:[1,0]
	v_mul_f32_e32 v129, 0x45800000, v128
	v_cndmask_b32_e32 v176, v128, v129, vcc
	v_lshlrev_b64 v[128:129], 5, v[174:175]
	v_lshl_add_u64 v[132:133], s[14:15], 0, v[128:129]
	v_mov_b32_e32 v128, 0
	v_mov_b32_e32 v129, 0
	v_mov_b32_e32 v130, 0
	v_mov_b32_e32 v131, 0
	s_nop 0
	v_mov_b32_e32 v132, v244
	v_mov_b32_e32 v133, 0
	v_mov_b32_e32 v134, 0
	v_mov_b32_e32 v135, 0
	v_pk_mul_f32 v[90:91], v[90:91], v[180:181] op_sel_hi:[1,0]
	v_pk_mul_f32 v[84:85], v[84:85], v[180:181] op_sel_hi:[1,0]
	v_pk_mul_f32 v[86:87], v[86:87], v[180:181] op_sel_hi:[1,0]
	v_pk_mul_f32 v[80:81], v[80:81], v[180:181] op_sel_hi:[1,0]
	v_pk_mul_f32 v[82:83], v[82:83], v[180:181] op_sel_hi:[1,0]
	s_waitcnt vmcnt(0)
; DEV f32x4 gelu4(f32x4 v) { f32x2 a = gelu_pk((f32x2){v[0], v[1]}), b = gelu_pk((f32x2){v[2], v[3]}); return (f32x4){a.x, a.y, b.x, b.y}; }
; DEV f32x2 gelu_pk(f32x2 v) {
;     const f32x2 av = __builtin_elementwise_abs(v), d = av * 0.2316418882f + 1.0f;
;     f32x2 t; t.x = __builtin_amdgcn_rcpf(d.x); t.y = __builtin_amdgcn_rcpf(d.y);
;     f32x2 q = t * 0.5307027145f + (-0.7265760135f); q = q * t + 0.7107068705f; q = q * t + (-0.142248368f); q = q * t + 0.127414796f; q = q * t;
;     const f32x2 s = (v * v) * (-0.72134752044f);
;     f32x2 e; e.x = __builtin_amdgcn_exp2f(s.x); e.y = __builtin_amdgcn_exp2f(s.y);
; template <int ACT, bool PERM>
; DEV void store_bf16_tile(AccRef acc, u16* O, int ld, int row0, int col0, const float* ss) {
;     ...
;         for (int m = 0; m < 4; ++m) rsv[ai][m] = ss ? rowscale(ss, row0 + ai * 128 + m * 16) : 1.0f;
;     ...
;             for (int bj = 0; bj < 2; ++bj) { f32x4 v0 = acc[ai][bj][m][0] * rs, v1 = acc[ai][bj][m][1] * rs; if (ACT == 1) { v0 = gelu4(v0); v1 = gelu4(v1); }
	v_mov_b32_e32 v152, v133
	v_mov_b32_e32 v153, v134
	v_mov_b32_e32 v133, v135
	v_pk_add_f32 v[152:153], v[152:153], v[132:133]
	v_mov_b32_e32 v132, v130
	v_mov_b32_e32 v133, v128
	v_mov_b32_e32 v128, v131
	v_pk_add_f32 v[154:155], v[132:133], v[128:129]
	v_lshlrev_b64 v[128:129], 5, v[158:159]
	v_lshl_add_u64 v[132:133], s[14:15], 0, v[128:129]
	v_mov_b32_e32 v128, 0
	v_mov_b32_e32 v129, 0
	v_mov_b32_e32 v130, 0
	v_mov_b32_e32 v131, 0
	s_nop 0
	v_mov_b32_e32 v132, v245
	v_mov_b32_e32 v133, 0
	v_mov_b32_e32 v134, 0
	v_mov_b32_e32 v135, 0
	s_waitcnt vmcnt(0)
	v_mov_b32_e32 v194, v133
	v_mov_b32_e32 v195, v134
	v_mov_b32_e32 v133, v135
	v_pk_add_f32 v[132:133], v[194:195], v[132:133]
	v_mov_b32_e32 v134, v130
	v_mov_b32_e32 v135, v128
	v_mov_b32_e32 v128, v131
	v_pk_add_f32 v[128:129], v[134:135], v[128:129]
	v_mov_b32_e32 v130, v132
	v_mov_b32_e32 v131, v152
	v_mov_b32_e32 v152, v133
	v_pk_add_f32 v[130:131], v[130:131], v[152:153]
	v_mov_b32_e32 v132, v129
	v_mov_b32_e32 v133, v155
	v_pk_add_f32 v[130:131], v[130:131], v[132:133]
	v_mov_b32_e32 v129, v154
	v_pk_add_f32 v[128:129], v[128:129], v[130:131]
	v_add_u32_e32 v154, 0xa0, v150
	v_pk_fma_f32 v[128:129], v[128:129], s[16:17], v[192:193] op_sel_hi:[1,0,0]
	v_ashrrev_i32_e32 v155, 31, v154
	v_mul_f32_e32 v130, 0x4b800000, v129
	v_cmp_gt_f32_e64 s[0:1], s7, v129
	v_cmp_gt_f32_e32 vcc, s7, v128
	s_nop 0
	v_cndmask_b32_e64 v129, v129, v130, s[0:1]
	v_rsq_f32_e32 v129, v129
	s_nop 0
	v_mul_f32_e32 v130, 0x45800000, v129
	v_cndmask_b32_e64 v160, v129, v130, s[0:1]
	v_mul_f32_e32 v129, 0x4b800000, v128
	v_cndmask_b32_e32 v128, v128, v129, vcc
	v_rsq_f32_e32 v128, v128
	v_pk_mul_f32 v[60:61], v[60:61], v[160:161] op_sel_hi:[1,0]
	v_pk_mul_f32 v[62:63], v[62:63], v[160:161] op_sel_hi:[1,0]
	v_pk_mul_f32 v[56:57], v[56:57], v[160:161] op_sel_hi:[1,0]
	v_mul_f32_e32 v129, 0x45800000, v128
	v_cndmask_b32_e32 v156, v128, v129, vcc
	v_lshlrev_b64 v[128:129], 5, v[154:155]
	v_lshl_add_u64 v[132:133], s[14:15], 0, v[128:129]
	v_mov_b32_e32 v128, 0
	v_mov_b32_e32 v129, 0
	v_mov_b32_e32 v130, 0
	v_mov_b32_e32 v131, 0
	s_nop 0
	v_mov_b32_e32 v132, v246
	v_mov_b32_e32 v133, 0
	v_mov_b32_e32 v134, 0
	v_mov_b32_e32 v135, 0
	v_pk_mul_f32 v[58:59], v[58:59], v[160:161] op_sel_hi:[1,0]
	v_pk_mul_f32 v[52:53], v[52:53], v[160:161] op_sel_hi:[1,0]
	v_pk_mul_f32 v[54:55], v[54:55], v[160:161] op_sel_hi:[1,0]
	v_pk_mul_f32 v[48:49], v[48:49], v[160:161] op_sel_hi:[1,0]
	v_pk_mul_f32 v[50:51], v[50:51], v[160:161] op_sel_hi:[1,0]
	v_pk_mul_f32 v[44:45], v[44:45], v[156:157] op_sel_hi:[1,0]
	v_pk_mul_f32 v[46:47], v[46:47], v[156:157] op_sel_hi:[1,0]
	v_pk_mul_f32 v[40:41], v[40:41], v[156:157] op_sel_hi:[1,0]
	v_pk_mul_f32 v[42:43], v[42:43], v[156:157] op_sel_hi:[1,0]
	v_pk_mul_f32 v[36:37], v[36:37], v[156:157] op_sel_hi:[1,0]
	v_pk_mul_f32 v[38:39], v[38:39], v[156:157] op_sel_hi:[1,0]
	v_pk_mul_f32 v[32:33], v[32:33], v[156:157] op_sel_hi:[1,0]
	v_pk_mul_f32 v[34:35], v[34:35], v[156:157] op_sel_hi:[1,0]
	s_waitcnt vmcnt(0)
	v_mov_b32_e32 v152, v133
	v_mov_b32_e32 v153, v134
	v_mov_b32_e32 v133, v135
	v_pk_add_f32 v[196:197], v[152:153], v[132:133]
	v_add_u32_e32 v152, 0xb0, v150
	v_mov_b32_e32 v132, v130
	v_mov_b32_e32 v133, v128
	v_mov_b32_e32 v128, v131
	v_ashrrev_i32_e32 v153, 31, v152
	v_pk_add_f32 v[194:195], v[132:133], v[128:129]
	v_lshlrev_b64 v[128:129], 5, v[152:153]
	v_lshl_add_u64 v[132:133], s[14:15], 0, v[128:129]
	v_mov_b32_e32 v128, 0
	v_mov_b32_e32 v129, 0
	v_mov_b32_e32 v130, 0
	v_mov_b32_e32 v131, 0
	s_nop 0
	v_mov_b32_e32 v132, v247
	v_mov_b32_e32 v133, 0
	v_mov_b32_e32 v134, 0
	v_mov_b32_e32 v135, 0
	s_mov_b32 s14, 0x3e6d3388
	s_waitcnt vmcnt(0)
	v_mov_b32_e32 v214, v133
	v_mov_b32_e32 v215, v134
	v_mov_b32_e32 v133, v135
	v_pk_add_f32 v[132:133], v[214:215], v[132:133]
	v_mov_b32_e32 v134, v130
	v_mov_b32_e32 v135, v128
	v_mov_b32_e32 v128, v131
	v_pk_add_f32 v[128:129], v[134:135], v[128:129]
	v_mov_b32_e32 v130, v132
	v_mov_b32_e32 v131, v196
	v_mov_b32_e32 v196, v133
	v_pk_add_f32 v[130:131], v[130:131], v[196:197]
	v_mov_b32_e32 v132, v129
	v_mov_b32_e32 v133, v195
	v_pk_add_f32 v[130:131], v[130:131], v[132:133]
	v_mov_b32_e32 v129, v194
	v_pk_add_f32 v[128:129], v[128:129], v[130:131]
	v_lshlrev_b64 v[134:135], 13, v[150:151]
	v_pk_fma_f32 v[128:129], v[128:129], s[16:17], v[192:193] op_sel_hi:[1,0,0]
	v_pk_mul_f32 v[150:151], v[120:121], v[188:189] op_sel_hi:[1,0]
	v_mul_f32_e32 v130, 0x4b800000, v129
	v_cmp_gt_f32_e64 s[0:1], s7, v129
	v_and_b32_e32 v121, 0x7fffffff, v125
	v_and_b32_e32 v120, 0x7fffffff, v124
	v_cndmask_b32_e64 v129, v129, v130, s[0:1]
	v_rsq_f32_e32 v129, v129
	v_pk_fma_f32 v[120:121], v[120:121], s[14:15], 1.0 op_sel_hi:[1,0,0]
	v_cmp_gt_f32_e32 vcc, s7, v128
	v_pk_mul_f32 v[194:195], v[124:125], v[124:125]
	v_mul_f32_e32 v130, 0x45800000, v129
	v_cndmask_b32_e64 v132, v129, v130, s[0:1]
	v_readlane_b32 s0, v250, 11
	v_readlane_b32 s1, v250, 12
	v_mul_f32_e32 v129, 0x4b800000, v128
	v_cndmask_b32_e32 v128, v128, v129, vcc
	v_lshl_add_u64 v[130:131], v[190:191], 1, s[0:1]
	v_rcp_f32_e32 v190, v120
	v_rcp_f32_e32 v191, v121
	s_mov_b32 s0, 0xbf3a00e3
	v_mov_b64_e32 v[120:121], s[0:1]
	s_mov_b32 s0, 0x3f07dc22
	v_pk_fma_f32 v[192:193], v[190:191], s[0:1], v[120:121] op_sel_hi:[1,0,0]
	s_mov_b32 s16, 0x3f35f0e3
	v_pk_mul_f32 v[194:195], v[194:195], s[36:37] op_sel_hi:[1,0]
	v_rsq_f32_e32 v128, v128
	v_pk_fma_f32 v[192:193], v[190:191], v[192:193], s[16:17] op_sel_hi:[1,1,0]
	v_exp_f32_e32 v194, v194
	v_exp_f32_e32 v195, v195
	v_pk_fma_f32 v[192:193], v[190:191], v[192:193], s[18:19] op_sel_hi:[1,1,0]
	v_mul_f32_e32 v129, 0x45800000, v128
; DEV bf16x8 pack8(f32x4 a, f32x4 b) { u32x4 w; w.x = cvt_pk_bf16(a[0], a[1]); w.y = cvt_pk_bf16(a[2], a[3]); w.z = cvt_pk_bf16(b[0], b[1]); w.w = cvt_pk_bf16(b[2], b[3]); return __builtin_bit_cast(bf16x8, w); }
; DEV f32x2 gelu_pk(f32x2 v) {
;     const f32x2 av = __builtin_elementwise_abs(v), d = av * 0.2316418882f + 1.0f;
;     f32x2 t; t.x = __builtin_amdgcn_rcpf(d.x); t.y = __builtin_amdgcn_rcpf(d.y);
;     f32x2 q = t * 0.5307027145f + (-0.7265760135f); q = q * t + 0.7107068705f; q = q * t + (-0.142248368f); q = q * t + 0.127414796f; q = q * t;
;     const f32x2 s = (v * v) * (-0.72134752044f);
;     f32x2 e; e.x = __builtin_amdgcn_exp2f(s.x); e.y = __builtin_amdgcn_exp2f(s.y);
;     const f32x2 m = v * (q * e), r = v - m;
;     f32x2 o; o.x = v.x < 0.f ? m.x : r.x; o.y = v.y < 0.f ? m.y : r.y; return o;
; }
; DEV f32x4 gelu4(f32x4 v) { f32x2 a = gelu_pk((f32x2){v[0], v[1]}), b = gelu_pk((f32x2){v[2], v[3]}); return (f32x4){a.x, a.y, b.x, b.y}; }
; template <int ACT, bool PERM>
; DEV void store_bf16_tile(AccRef acc, u16* O, int ld, int row0, int col0, const float* ss) {
;     ...
;             for (int bj = 0; bj < 2; ++bj) { f32x4 v0 = acc[ai][bj][m][0] * rs, v1 = acc[ai][bj][m][1] * rs; if (ACT == 1) { v0 = gelu4(v0); v1 = gelu4(v1); }
;                 if (PERM) *(u32x4*)(rowp + bj * 128) = __builtin_bit_cast(u32x4, pack8(v0, v1));
	v_pk_fma_f32 v[192:193], v[190:191], v[192:193], s[34:35] op_sel_hi:[1,1,0]
	v_cndmask_b32_e32 v128, v128, v129, vcc
	v_pk_mul_f32 v[190:191], v[190:191], v[192:193]
	v_cmp_gt_f32_e32 vcc, 0, v124
	v_pk_mul_f32 v[190:191], v[194:195], v[190:191]
	v_pk_mul_f32 v[192:193], v[126:127], v[126:127]
	v_pk_mul_f32 v[194:195], v[124:125], v[190:191]
	v_pk_fma_f32 v[190:191], v[124:125], v[190:191], v[124:125] neg_lo:[1,0,0] neg_hi:[1,0,0]
	v_and_b32_e32 v124, 0x7fffffff, v126
	v_cndmask_b32_e32 v129, v190, v194, vcc
	v_cmp_gt_f32_e32 vcc, 0, v125
	v_and_b32_e32 v125, 0x7fffffff, v127
	v_pk_fma_f32 v[124:125], v[124:125], s[14:15], 1.0 op_sel_hi:[1,0,0]
	v_cndmask_b32_e32 v133, v191, v195, vcc
	v_rcp_f32_e32 v124, v124
	v_rcp_f32_e32 v125, v125
	v_cmp_gt_f32_e32 vcc, 0, v126
	v_lshl_add_u64 v[134:135], v[130:131], 0, v[134:135]
	v_pk_mul_f32 v[28:29], v[28:29], v[132:133] op_sel_hi:[1,0]
	v_pk_fma_f32 v[190:191], v[124:125], s[0:1], v[120:121] op_sel_hi:[1,0,0]
	v_pk_mul_f32 v[30:31], v[30:31], v[132:133] op_sel_hi:[1,0]
	v_pk_fma_f32 v[190:191], v[124:125], v[190:191], s[16:17] op_sel_hi:[1,1,0]
	v_pk_mul_f32 v[24:25], v[24:25], v[132:133] op_sel_hi:[1,0]
	v_pk_fma_f32 v[190:191], v[124:125], v[190:191], s[18:19] op_sel_hi:[1,1,0]
	v_pk_mul_f32 v[26:27], v[26:27], v[132:133] op_sel_hi:[1,0]
	v_pk_fma_f32 v[190:191], v[124:125], v[190:191], s[34:35] op_sel_hi:[1,1,0]
	v_pk_mul_f32 v[20:21], v[20:21], v[132:133] op_sel_hi:[1,0]
	v_pk_mul_f32 v[124:125], v[124:125], v[190:191]
	v_pk_mul_f32 v[190:191], v[192:193], s[36:37] op_sel_hi:[1,0]
	v_pk_mul_f32 v[22:23], v[22:23], v[132:133] op_sel_hi:[1,0]
	v_exp_f32_e32 v190, v190
	v_exp_f32_e32 v191, v191
	v_pk_mul_f32 v[16:17], v[16:17], v[132:133] op_sel_hi:[1,0]
	v_pk_mul_f32 v[18:19], v[18:19], v[132:133] op_sel_hi:[1,0]
	v_pk_mul_f32 v[12:13], v[12:13], v[128:129] op_sel_hi:[1,0]
	v_pk_mul_f32 v[124:125], v[190:191], v[124:125]
	v_pk_mul_f32 v[14:15], v[14:15], v[128:129] op_sel_hi:[1,0]
	v_pk_mul_f32 v[190:191], v[126:127], v[124:125]
	v_pk_fma_f32 v[124:125], v[126:127], v[124:125], v[126:127] neg_lo:[1,0,0] neg_hi:[1,0,0]
	v_pk_mul_f32 v[8:9], v[8:9], v[128:129] op_sel_hi:[1,0]
	v_cndmask_b32_e32 v177, v124, v190, vcc
	v_cmp_gt_f32_e32 vcc, 0, v127
	v_and_b32_e32 v124, 0x7fffffff, v150
	v_pk_mul_f32 v[76:77], v[76:77], v[176:177] op_sel_hi:[1,0]
	v_cndmask_b32_e32 v185, v125, v191, vcc
	v_and_b32_e32 v125, 0x7fffffff, v151
	v_pk_fma_f32 v[124:125], v[124:125], s[14:15], 1.0 op_sel_hi:[1,0,0]
	v_pk_mul_f32 v[190:191], v[150:151], v[150:151]
	v_rcp_f32_e32 v124, v124
	v_rcp_f32_e32 v125, v125
	v_pk_mul_f32 v[190:191], v[190:191], s[36:37] op_sel_hi:[1,0]
	v_cmp_gt_f32_e32 vcc, 0, v150
	v_exp_f32_e32 v190, v190
	v_pk_fma_f32 v[126:127], v[124:125], s[0:1], v[120:121] op_sel_hi:[1,0,0]
	v_exp_f32_e32 v191, v191
	v_pk_fma_f32 v[126:127], v[124:125], v[126:127], s[16:17] op_sel_hi:[1,1,0]
	v_pk_mul_f32 v[108:109], v[108:109], v[184:185] op_sel_hi:[1,0]
	v_pk_fma_f32 v[126:127], v[124:125], v[126:127], s[18:19] op_sel_hi:[1,1,0]
	v_pk_mul_f32 v[110:111], v[110:111], v[184:185] op_sel_hi:[1,0]
	v_pk_fma_f32 v[126:127], v[124:125], v[126:127], s[34:35] op_sel_hi:[1,1,0]
	v_pk_mul_f32 v[104:105], v[104:105], v[184:185] op_sel_hi:[1,0]
	v_pk_mul_f32 v[124:125], v[124:125], v[126:127]
	v_pk_mul_f32 v[126:127], v[122:123], v[122:123]
	v_pk_mul_f32 v[124:125], v[190:191], v[124:125]
	v_pk_mul_f32 v[126:127], v[126:127], s[36:37] op_sel_hi:[1,0]
	v_pk_mul_f32 v[190:191], v[150:151], v[124:125]
	v_pk_fma_f32 v[124:125], v[150:151], v[124:125], v[150:151] neg_lo:[1,0,0] neg_hi:[1,0,0]
	v_exp_f32_e32 v126, v126
	v_cndmask_b32_e32 v189, v124, v190, vcc
	v_cmp_gt_f32_e32 vcc, 0, v151
	v_and_b32_e32 v124, 0x7fffffff, v122
	v_exp_f32_e32 v127, v127
	v_cndmask_b32_e32 v190, v125, v191, vcc
	v_and_b32_e32 v125, 0x7fffffff, v123
	v_pk_fma_f32 v[124:125], v[124:125], s[14:15], 1.0 op_sel_hi:[1,0,0]
	v_cmp_gt_f32_e32 vcc, 0, v122
	v_rcp_f32_e32 v124, v124
	v_rcp_f32_e32 v125, v125
	v_pk_mul_f32 v[116:117], v[116:117], v[188:189] op_sel_hi:[1,0]
	v_pk_mul_f32 v[118:119], v[118:119], v[188:189] op_sel_hi:[1,0]
	v_pk_mul_f32 v[112:113], v[112:113], v[188:189] op_sel_hi:[1,0]
	v_pk_fma_f32 v[150:151], v[124:125], s[0:1], v[120:121] op_sel_hi:[1,0,0]
	v_pk_mul_f32 v[114:115], v[114:115], v[188:189] op_sel_hi:[1,0]
	v_pk_fma_f32 v[150:151], v[124:125], v[150:151], s[16:17] op_sel_hi:[1,1,0]
	v_pk_mul_f32 v[106:107], v[106:107], v[184:185] op_sel_hi:[1,0]
	v_pk_fma_f32 v[150:151], v[124:125], v[150:151], s[18:19] op_sel_hi:[1,1,0]
	v_pk_mul_f32 v[100:101], v[100:101], v[184:185] op_sel_hi:[1,0]
	v_pk_fma_f32 v[150:151], v[124:125], v[150:151], s[34:35] op_sel_hi:[1,1,0]
	v_pk_mul_f32 v[102:103], v[102:103], v[184:185] op_sel_hi:[1,0]
	v_pk_mul_f32 v[124:125], v[124:125], v[150:151]
	v_pk_mul_f32 v[96:97], v[96:97], v[184:185] op_sel_hi:[1,0]
	v_pk_mul_f32 v[124:125], v[126:127], v[124:125]
	v_pk_mul_f32 v[98:99], v[98:99], v[184:185] op_sel_hi:[1,0]
	v_pk_mul_f32 v[126:127], v[122:123], v[124:125]
	v_pk_fma_f32 v[124:125], v[122:123], v[124:125], v[122:123] neg_lo:[1,0,0] neg_hi:[1,0,0]
	v_cvt_pk_bf16_f32 v122, v129, v133
	v_cndmask_b32_e32 v126, v124, v126, vcc
	v_cmp_gt_f32_e32 vcc, 0, v123
	v_cvt_pk_bf16_f32 v123, v177, v185
	v_cvt_pk_bf16_f32 v124, v189, v190
	v_cndmask_b32_e32 v125, v125, v127, vcc
	v_cvt_pk_bf16_f32 v125, v126, v125
	global_store_dwordx4 v[134:135], v[122:125], off
	v_pk_mul_f32 v[126:127], v[116:117], v[116:117]
	v_cmp_gt_f32_e32 vcc, 0, v116
	v_and_b32_e32 v123, 0x7fffffff, v117
	v_and_b32_e32 v122, 0x7fffffff, v116
	v_pk_fma_f32 v[122:123], v[122:123], s[14:15], 1.0 op_sel_hi:[1,0,0]
; DEV bf16x8 pack8(f32x4 a, f32x4 b) { u32x4 w; w.x = cvt_pk_bf16(a[0], a[1]); w.y = cvt_pk_bf16(a[2], a[3]); w.z = cvt_pk_bf16(b[0], b[1]); w.w = cvt_pk_bf16(b[2], b[3]); return __builtin_bit_cast(bf16x8, w); }
; DEV f32x2 gelu_pk(f32x2 v) {
;     const f32x2 av = __builtin_elementwise_abs(v), d = av * 0.2316418882f + 1.0f;
;     f32x2 t; t.x = __builtin_amdgcn_rcpf(d.x); t.y = __builtin_amdgcn_rcpf(d.y);
;     f32x2 q = t * 0.5307027145f + (-0.7265760135f); q = q * t + 0.7107068705f; q = q * t + (-0.142248368f); q = q * t + 0.127414796f; q = q * t;
;     const f32x2 s = (v * v) * (-0.72134752044f);
;     f32x2 e; e.x = __builtin_amdgcn_exp2f(s.x); e.y = __builtin_amdgcn_exp2f(s.y);
;     const f32x2 m = v * (q * e), r = v - m;
;     f32x2 o; o.x = v.x < 0.f ? m.x : r.x; o.y = v.y < 0.f ? m.y : r.y; return o;
; }
; DEV f32x4 gelu4(f32x4 v) { f32x2 a = gelu_pk((f32x2){v[0], v[1]}), b = gelu_pk((f32x2){v[2], v[3]}); return (f32x4){a.x, a.y, b.x, b.y}; }
; template <int ACT, bool PERM>
; DEV void store_bf16_tile(AccRef acc, u16* O, int ld, int row0, int col0, const float* ss) {
;     ...
;             for (int bj = 0; bj < 2; ++bj) { f32x4 v0 = acc[ai][bj][m][0] * rs, v1 = acc[ai][bj][m][1] * rs; if (ACT == 1) { v0 = gelu4(v0); v1 = gelu4(v1); }
;                 if (PERM) *(u32x4*)(rowp + bj * 128) = __builtin_bit_cast(u32x4, pack8(v0, v1));
	v_pk_mul_f32 v[126:127], v[126:127], s[36:37] op_sel_hi:[1,0]
	v_rcp_f32_e32 v122, v122
	v_rcp_f32_e32 v123, v123
	v_exp_f32_e32 v126, v126
	v_exp_f32_e32 v127, v127
	v_pk_mul_f32 v[78:79], v[78:79], v[176:177] op_sel_hi:[1,0]
	v_pk_fma_f32 v[124:125], v[122:123], s[0:1], v[120:121] op_sel_hi:[1,0,0]
	v_pk_mul_f32 v[72:73], v[72:73], v[176:177] op_sel_hi:[1,0]
	v_pk_fma_f32 v[124:125], v[122:123], v[124:125], s[16:17] op_sel_hi:[1,1,0]
	v_pk_mul_f32 v[74:75], v[74:75], v[176:177] op_sel_hi:[1,0]
	v_pk_fma_f32 v[124:125], v[122:123], v[124:125], s[18:19] op_sel_hi:[1,1,0]
	v_pk_mul_f32 v[68:69], v[68:69], v[176:177] op_sel_hi:[1,0]
	v_pk_fma_f32 v[124:125], v[122:123], v[124:125], s[34:35] op_sel_hi:[1,1,0]
	v_pk_mul_f32 v[70:71], v[70:71], v[176:177] op_sel_hi:[1,0]
	v_pk_mul_f32 v[122:123], v[122:123], v[124:125]
	v_pk_mul_f32 v[124:125], v[118:119], v[118:119]
	v_pk_mul_f32 v[122:123], v[126:127], v[122:123]
	v_pk_mul_f32 v[64:65], v[64:65], v[176:177] op_sel_hi:[1,0]
	v_pk_mul_f32 v[126:127], v[116:117], v[122:123]
	v_pk_fma_f32 v[122:123], v[116:117], v[122:123], v[116:117] neg_lo:[1,0,0] neg_hi:[1,0,0]
	v_and_b32_e32 v116, 0x7fffffff, v118
	v_cndmask_b32_e32 v126, v122, v126, vcc
	v_cmp_gt_f32_e32 vcc, 0, v117
	v_and_b32_e32 v117, 0x7fffffff, v119
	v_pk_fma_f32 v[116:117], v[116:117], s[14:15], 1.0 op_sel_hi:[1,0,0]
	v_cndmask_b32_e32 v127, v123, v127, vcc
	v_rcp_f32_e32 v116, v116
	v_rcp_f32_e32 v117, v117
	v_cmp_gt_f32_e32 vcc, 0, v118
	v_pk_mul_f32 v[66:67], v[66:67], v[176:177] op_sel_hi:[1,0]
	v_pk_mul_f32 v[10:11], v[10:11], v[128:129] op_sel_hi:[1,0]
	v_pk_fma_f32 v[122:123], v[116:117], s[0:1], v[120:121] op_sel_hi:[1,0,0]
	v_pk_mul_f32 v[4:5], v[4:5], v[128:129] op_sel_hi:[1,0]
	v_pk_fma_f32 v[122:123], v[116:117], v[122:123], s[16:17] op_sel_hi:[1,1,0]
	v_pk_mul_f32 v[6:7], v[6:7], v[128:129] op_sel_hi:[1,0]
	v_pk_fma_f32 v[122:123], v[116:117], v[122:123], s[18:19] op_sel_hi:[1,1,0]
	v_pk_mul_f32 v[0:1], v[0:1], v[128:129] op_sel_hi:[1,0]
	v_pk_fma_f32 v[122:123], v[116:117], v[122:123], s[34:35] op_sel_hi:[1,1,0]
	v_pk_mul_f32 v[2:3], v[2:3], v[128:129] op_sel_hi:[1,0]
	v_pk_mul_f32 v[116:117], v[116:117], v[122:123]
	v_pk_mul_f32 v[122:123], v[124:125], s[36:37] op_sel_hi:[1,0]
	s_nop 0
	v_exp_f32_e32 v122, v122
	v_exp_f32_e32 v123, v123
	s_nop 0
	v_pk_mul_f32 v[116:117], v[122:123], v[116:117]
	s_nop 0
	v_pk_mul_f32 v[122:123], v[118:119], v[116:117]
	v_pk_fma_f32 v[116:117], v[118:119], v[116:117], v[118:119] neg_lo:[1,0,0] neg_hi:[1,0,0]
	s_nop 0
	v_cndmask_b32_e32 v124, v116, v122, vcc
	v_cmp_gt_f32_e32 vcc, 0, v119
	v_and_b32_e32 v116, 0x7fffffff, v112
	s_nop 0
	v_cndmask_b32_e32 v125, v117, v123, vcc
	v_and_b32_e32 v117, 0x7fffffff, v113
	v_pk_fma_f32 v[116:117], v[116:117], s[14:15], 1.0 op_sel_hi:[1,0,0]
	v_pk_mul_f32 v[122:123], v[112:113], v[112:113]
	v_rcp_f32_e32 v116, v116
	v_rcp_f32_e32 v117, v117
	v_pk_mul_f32 v[122:123], v[122:123], s[36:37] op_sel_hi:[1,0]
	v_cmp_gt_f32_e32 vcc, 0, v112
	v_exp_f32_e32 v122, v122
	v_pk_fma_f32 v[118:119], v[116:117], s[0:1], v[120:121] op_sel_hi:[1,0,0]
	v_exp_f32_e32 v123, v123
	v_pk_fma_f32 v[118:119], v[116:117], v[118:119], s[16:17] op_sel_hi:[1,1,0]
	s_nop 0
	v_pk_fma_f32 v[118:119], v[116:117], v[118:119], s[18:19] op_sel_hi:[1,1,0]
	s_nop 0
	v_pk_fma_f32 v[118:119], v[116:117], v[118:119], s[34:35] op_sel_hi:[1,1,0]
	s_nop 0
	v_pk_mul_f32 v[116:117], v[116:117], v[118:119]
	v_pk_mul_f32 v[118:119], v[114:115], v[114:115]
	v_pk_mul_f32 v[116:117], v[122:123], v[116:117]
	s_nop 0
	v_pk_mul_f32 v[122:123], v[112:113], v[116:117]
	v_pk_fma_f32 v[116:117], v[112:113], v[116:117], v[112:113] neg_lo:[1,0,0] neg_hi:[1,0,0]
	v_and_b32_e32 v112, 0x7fffffff, v114
	v_cndmask_b32_e32 v122, v116, v122, vcc
	v_cmp_gt_f32_e32 vcc, 0, v113
	v_and_b32_e32 v113, 0x7fffffff, v115
	v_pk_fma_f32 v[112:113], v[112:113], s[14:15], 1.0 op_sel_hi:[1,0,0]
	v_cndmask_b32_e32 v123, v117, v123, vcc
	v_rcp_f32_e32 v112, v112
	v_rcp_f32_e32 v113, v113
	v_cmp_gt_f32_e32 vcc, 0, v114
	v_pk_fma_f32 v[116:117], v[112:113], s[0:1], v[120:121] op_sel_hi:[1,0,0]
	s_nop 0
	v_pk_fma_f32 v[116:117], v[112:113], v[116:117], s[16:17] op_sel_hi:[1,1,0]
	s_nop 0
	v_pk_fma_f32 v[116:117], v[112:113], v[116:117], s[18:19] op_sel_hi:[1,1,0]
	s_nop 0
	v_pk_fma_f32 v[116:117], v[112:113], v[116:117], s[34:35] op_sel_hi:[1,1,0]
	s_nop 0
	v_pk_mul_f32 v[112:113], v[112:113], v[116:117]
	v_pk_mul_f32 v[116:117], v[118:119], s[36:37] op_sel_hi:[1,0]
	v_pk_mul_f32 v[118:119], v[108:109], v[108:109]
	v_exp_f32_e32 v116, v116
	v_exp_f32_e32 v117, v117
	v_pk_mul_f32 v[118:119], v[118:119], s[36:37] op_sel_hi:[1,0]
	v_pk_mul_f32 v[112:113], v[116:117], v[112:113]
	s_nop 0
	v_pk_mul_f32 v[116:117], v[114:115], v[112:113]
	v_pk_fma_f32 v[112:113], v[114:115], v[112:113], v[114:115] neg_lo:[1,0,0] neg_hi:[1,0,0]
	v_cvt_pk_bf16_f32 v114, v122, v123
	v_cndmask_b32_e32 v116, v112, v116, vcc
	v_cmp_gt_f32_e32 vcc, 0, v115
	v_cvt_pk_bf16_f32 v112, v126, v127
	v_exp_f32_e32 v118, v118
	v_cndmask_b32_e32 v115, v113, v117, vcc
	v_cvt_pk_bf16_f32 v113, v124, v125
	v_cvt_pk_bf16_f32 v115, v116, v115
	global_store_dwordx4 v[134:135], v[112:115], off offset:256
	v_exp_f32_e32 v119, v119
	v_cmp_gt_f32_e32 vcc, 0, v108
	v_and_b32_e32 v115, 0x7fffffff, v109
	v_and_b32_e32 v114, 0x7fffffff, v108
	v_pk_fma_f32 v[114:115], v[114:115], s[14:15], 1.0 op_sel_hi:[1,0,0]
	v_lshlrev_b64 v[112:113], 13, v[186:187]
	v_rcp_f32_e32 v114, v114
	v_rcp_f32_e32 v115, v115
	v_lshl_add_u64 v[112:113], v[130:131], 0, v[112:113]
	v_pk_fma_f32 v[116:117], v[114:115], s[0:1], v[120:121] op_sel_hi:[1,0,0]
	s_nop 0
	v_pk_fma_f32 v[116:117], v[114:115], v[116:117], s[16:17] op_sel_hi:[1,1,0]
; DEV bf16x8 pack8(f32x4 a, f32x4 b) { u32x4 w; w.x = cvt_pk_bf16(a[0], a[1]); w.y = cvt_pk_bf16(a[2], a[3]); w.z = cvt_pk_bf16(b[0], b[1]); w.w = cvt_pk_bf16(b[2], b[3]); return __builtin_bit_cast(bf16x8, w); }
; DEV f32x2 gelu_pk(f32x2 v) {
;     const f32x2 av = __builtin_elementwise_abs(v), d = av * 0.2316418882f + 1.0f;
;     f32x2 t; t.x = __builtin_amdgcn_rcpf(d.x); t.y = __builtin_amdgcn_rcpf(d.y);
;     f32x2 q = t * 0.5307027145f + (-0.7265760135f); q = q * t + 0.7107068705f; q = q * t + (-0.142248368f); q = q * t + 0.127414796f; q = q * t;
;     const f32x2 s = (v * v) * (-0.72134752044f);
;     f32x2 e; e.x = __builtin_amdgcn_exp2f(s.x); e.y = __builtin_amdgcn_exp2f(s.y);
;     const f32x2 m = v * (q * e), r = v - m;
;     f32x2 o; o.x = v.x < 0.f ? m.x : r.x; o.y = v.y < 0.f ? m.y : r.y; return o;
; }
; DEV f32x4 gelu4(f32x4 v) { f32x2 a = gelu_pk((f32x2){v[0], v[1]}), b = gelu_pk((f32x2){v[2], v[3]}); return (f32x4){a.x, a.y, b.x, b.y}; }
; template <int ACT, bool PERM>
; DEV void store_bf16_tile(AccRef acc, u16* O, int ld, int row0, int col0, const float* ss) {
;     ...
;             for (int bj = 0; bj < 2; ++bj) { f32x4 v0 = acc[ai][bj][m][0] * rs, v1 = acc[ai][bj][m][1] * rs; if (ACT == 1) { v0 = gelu4(v0); v1 = gelu4(v1); }
;                 if (PERM) *(u32x4*)(rowp + bj * 128) = __builtin_bit_cast(u32x4, pack8(v0, v1));
	s_nop 0
	v_pk_fma_f32 v[116:117], v[114:115], v[116:117], s[18:19] op_sel_hi:[1,1,0]
	s_nop 0
	v_pk_fma_f32 v[116:117], v[114:115], v[116:117], s[34:35] op_sel_hi:[1,1,0]
	s_nop 0
	v_pk_mul_f32 v[114:115], v[114:115], v[116:117]
	v_pk_mul_f32 v[116:117], v[110:111], v[110:111]
	v_pk_mul_f32 v[114:115], v[118:119], v[114:115]
	s_nop 0
	v_pk_mul_f32 v[118:119], v[108:109], v[114:115]
	v_pk_fma_f32 v[114:115], v[108:109], v[114:115], v[108:109] neg_lo:[1,0,0] neg_hi:[1,0,0]
	v_and_b32_e32 v108, 0x7fffffff, v110
	v_cndmask_b32_e32 v118, v114, v118, vcc
	v_cmp_gt_f32_e32 vcc, 0, v109
	v_and_b32_e32 v109, 0x7fffffff, v111
	v_pk_fma_f32 v[108:109], v[108:109], s[14:15], 1.0 op_sel_hi:[1,0,0]
	v_cndmask_b32_e32 v119, v115, v119, vcc
	v_rcp_f32_e32 v108, v108
	v_rcp_f32_e32 v109, v109
	v_cmp_gt_f32_e32 vcc, 0, v110
	v_pk_fma_f32 v[114:115], v[108:109], s[0:1], v[120:121] op_sel_hi:[1,0,0]
	s_nop 0
	v_pk_fma_f32 v[114:115], v[108:109], v[114:115], s[16:17] op_sel_hi:[1,1,0]
	s_nop 0
	v_pk_fma_f32 v[114:115], v[108:109], v[114:115], s[18:19] op_sel_hi:[1,1,0]
	s_nop 0
	v_pk_fma_f32 v[114:115], v[108:109], v[114:115], s[34:35] op_sel_hi:[1,1,0]
	s_nop 0
	v_pk_mul_f32 v[108:109], v[108:109], v[114:115]
	v_pk_mul_f32 v[114:115], v[116:117], s[36:37] op_sel_hi:[1,0]
	s_nop 0
	v_exp_f32_e32 v114, v114
	v_exp_f32_e32 v115, v115
	s_nop 0
	v_pk_mul_f32 v[108:109], v[114:115], v[108:109]
	s_nop 0
	v_pk_mul_f32 v[114:115], v[110:111], v[108:109]
	v_pk_fma_f32 v[108:109], v[110:111], v[108:109], v[110:111] neg_lo:[1,0,0] neg_hi:[1,0,0]
	s_nop 0
	v_cndmask_b32_e32 v116, v108, v114, vcc
	v_cmp_gt_f32_e32 vcc, 0, v111
	v_and_b32_e32 v108, 0x7fffffff, v104
	s_nop 0
	v_cndmask_b32_e32 v117, v109, v115, vcc
	v_and_b32_e32 v109, 0x7fffffff, v105
	v_pk_fma_f32 v[108:109], v[108:109], s[14:15], 1.0 op_sel_hi:[1,0,0]
	v_pk_mul_f32 v[114:115], v[104:105], v[104:105]
	v_rcp_f32_e32 v108, v108
	v_rcp_f32_e32 v109, v109
	v_pk_mul_f32 v[114:115], v[114:115], s[36:37] op_sel_hi:[1,0]
	v_cmp_gt_f32_e32 vcc, 0, v104
	v_exp_f32_e32 v114, v114
	v_pk_fma_f32 v[110:111], v[108:109], s[0:1], v[120:121] op_sel_hi:[1,0,0]
	v_exp_f32_e32 v115, v115
	v_pk_fma_f32 v[110:111], v[108:109], v[110:111], s[16:17] op_sel_hi:[1,1,0]
	s_nop 0
	v_pk_fma_f32 v[110:111], v[108:109], v[110:111], s[18:19] op_sel_hi:[1,1,0]
	s_nop 0
	v_pk_fma_f32 v[110:111], v[108:109], v[110:111], s[34:35] op_sel_hi:[1,1,0]
	s_nop 0
	v_pk_mul_f32 v[108:109], v[108:109], v[110:111]
	v_pk_mul_f32 v[110:111], v[106:107], v[106:107]
	v_pk_mul_f32 v[108:109], v[114:115], v[108:109]
	s_nop 0
	v_pk_mul_f32 v[114:115], v[104:105], v[108:109]
	v_pk_fma_f32 v[108:109], v[104:105], v[108:109], v[104:105] neg_lo:[1,0,0] neg_hi:[1,0,0]
	v_and_b32_e32 v104, 0x7fffffff, v106
	v_cndmask_b32_e32 v114, v108, v114, vcc
	v_cmp_gt_f32_e32 vcc, 0, v105
	v_and_b32_e32 v105, 0x7fffffff, v107
	v_pk_fma_f32 v[104:105], v[104:105], s[14:15], 1.0 op_sel_hi:[1,0,0]
	v_cndmask_b32_e32 v115, v109, v115, vcc
	v_rcp_f32_e32 v104, v104
	v_rcp_f32_e32 v105, v105
	v_cmp_gt_f32_e32 vcc, 0, v106
	v_pk_fma_f32 v[108:109], v[104:105], s[0:1], v[120:121] op_sel_hi:[1,0,0]
	s_nop 0
	v_pk_fma_f32 v[108:109], v[104:105], v[108:109], s[16:17] op_sel_hi:[1,1,0]
	s_nop 0
	v_pk_fma_f32 v[108:109], v[104:105], v[108:109], s[18:19] op_sel_hi:[1,1,0]
	s_nop 0
	v_pk_fma_f32 v[108:109], v[104:105], v[108:109], s[34:35] op_sel_hi:[1,1,0]
	s_nop 0
	v_pk_mul_f32 v[104:105], v[104:105], v[108:109]
	v_pk_mul_f32 v[108:109], v[110:111], s[36:37] op_sel_hi:[1,0]
	s_nop 0
	v_exp_f32_e32 v108, v108
	v_exp_f32_e32 v109, v109
	s_nop 0
	v_pk_mul_f32 v[104:105], v[108:109], v[104:105]
	s_nop 0
	v_pk_mul_f32 v[108:109], v[106:107], v[104:105]
	v_pk_fma_f32 v[104:105], v[106:107], v[104:105], v[106:107] neg_lo:[1,0,0] neg_hi:[1,0,0]
	v_cvt_pk_bf16_f32 v106, v114, v115
	v_cndmask_b32_e32 v108, v104, v108, vcc
	v_cmp_gt_f32_e32 vcc, 0, v107
	v_cvt_pk_bf16_f32 v104, v118, v119
	s_nop 0
	v_cndmask_b32_e32 v107, v105, v109, vcc
	v_cvt_pk_bf16_f32 v105, v116, v117
	v_cvt_pk_bf16_f32 v107, v108, v107
	global_store_dwordx4 v[112:113], v[104:107], off
	v_pk_mul_f32 v[108:109], v[100:101], v[100:101]
	v_cmp_gt_f32_e32 vcc, 0, v100
	v_and_b32_e32 v105, 0x7fffffff, v101
	v_and_b32_e32 v104, 0x7fffffff, v100
	v_pk_fma_f32 v[104:105], v[104:105], s[14:15], 1.0 op_sel_hi:[1,0,0]
	v_pk_mul_f32 v[108:109], v[108:109], s[36:37] op_sel_hi:[1,0]
	v_rcp_f32_e32 v104, v104
	v_rcp_f32_e32 v105, v105
	v_exp_f32_e32 v108, v108
	v_exp_f32_e32 v109, v109
	v_pk_fma_f32 v[106:107], v[104:105], s[0:1], v[120:121] op_sel_hi:[1,0,0]
	s_nop 0
	v_pk_fma_f32 v[106:107], v[104:105], v[106:107], s[16:17] op_sel_hi:[1,1,0]
	s_nop 0
	v_pk_fma_f32 v[106:107], v[104:105], v[106:107], s[18:19] op_sel_hi:[1,1,0]
	s_nop 0
	v_pk_fma_f32 v[106:107], v[104:105], v[106:107], s[34:35] op_sel_hi:[1,1,0]
	s_nop 0
	v_pk_mul_f32 v[104:105], v[104:105], v[106:107]
	v_pk_mul_f32 v[106:107], v[102:103], v[102:103]
	v_pk_mul_f32 v[104:105], v[108:109], v[104:105]
	s_nop 0
	v_pk_mul_f32 v[108:109], v[100:101], v[104:105]
	v_pk_fma_f32 v[104:105], v[100:101], v[104:105], v[100:101] neg_lo:[1,0,0] neg_hi:[1,0,0]
	v_and_b32_e32 v100, 0x7fffffff, v102
	v_cndmask_b32_e32 v108, v104, v108, vcc
	v_cmp_gt_f32_e32 vcc, 0, v101
	v_and_b32_e32 v101, 0x7fffffff, v103
	v_pk_fma_f32 v[100:101], v[100:101], s[14:15], 1.0 op_sel_hi:[1,0,0]
	v_cndmask_b32_e32 v109, v105, v109, vcc
	v_rcp_f32_e32 v100, v100
	v_rcp_f32_e32 v101, v101
	v_cmp_gt_f32_e32 vcc, 0, v102
	v_pk_fma_f32 v[104:105], v[100:101], s[0:1], v[120:121] op_sel_hi:[1,0,0]
	s_nop 0
	v_pk_fma_f32 v[104:105], v[100:101], v[104:105], s[16:17] op_sel_hi:[1,1,0]
	s_nop 0
; DEV bf16x8 pack8(f32x4 a, f32x4 b) { u32x4 w; w.x = cvt_pk_bf16(a[0], a[1]); w.y = cvt_pk_bf16(a[2], a[3]); w.z = cvt_pk_bf16(b[0], b[1]); w.w = cvt_pk_bf16(b[2], b[3]); return __builtin_bit_cast(bf16x8, w); }
; DEV f32x2 gelu_pk(f32x2 v) {
;     const f32x2 av = __builtin_elementwise_abs(v), d = av * 0.2316418882f + 1.0f;
;     f32x2 t; t.x = __builtin_amdgcn_rcpf(d.x); t.y = __builtin_amdgcn_rcpf(d.y);
;     f32x2 q = t * 0.5307027145f + (-0.7265760135f); q = q * t + 0.7107068705f; q = q * t + (-0.142248368f); q = q * t + 0.127414796f; q = q * t;
;     const f32x2 s = (v * v) * (-0.72134752044f);
;     f32x2 e; e.x = __builtin_amdgcn_exp2f(s.x); e.y = __builtin_amdgcn_exp2f(s.y);
;     const f32x2 m = v * (q * e), r = v - m;
;     f32x2 o; o.x = v.x < 0.f ? m.x : r.x; o.y = v.y < 0.f ? m.y : r.y; return o;
; }
; DEV f32x4 gelu4(f32x4 v) { f32x2 a = gelu_pk((f32x2){v[0], v[1]}), b = gelu_pk((f32x2){v[2], v[3]}); return (f32x4){a.x, a.y, b.x, b.y}; }
; template <int ACT, bool PERM>
; DEV void store_bf16_tile(AccRef acc, u16* O, int ld, int row0, int col0, const float* ss) {
;     ...
;             for (int bj = 0; bj < 2; ++bj) { f32x4 v0 = acc[ai][bj][m][0] * rs, v1 = acc[ai][bj][m][1] * rs; if (ACT == 1) { v0 = gelu4(v0); v1 = gelu4(v1); }
;                 if (PERM) *(u32x4*)(rowp + bj * 128) = __builtin_bit_cast(u32x4, pack8(v0, v1));
	v_pk_fma_f32 v[104:105], v[100:101], v[104:105], s[18:19] op_sel_hi:[1,1,0]
	s_nop 0
	v_pk_fma_f32 v[104:105], v[100:101], v[104:105], s[34:35] op_sel_hi:[1,1,0]
	s_nop 0
	v_pk_mul_f32 v[100:101], v[100:101], v[104:105]
	v_pk_mul_f32 v[104:105], v[106:107], s[36:37] op_sel_hi:[1,0]
	s_nop 0
	v_exp_f32_e32 v104, v104
	v_exp_f32_e32 v105, v105
	s_nop 0
	v_pk_mul_f32 v[100:101], v[104:105], v[100:101]
	s_nop 0
	v_pk_mul_f32 v[104:105], v[102:103], v[100:101]
	v_pk_fma_f32 v[100:101], v[102:103], v[100:101], v[102:103] neg_lo:[1,0,0] neg_hi:[1,0,0]
	s_nop 0
	v_cndmask_b32_e32 v106, v100, v104, vcc
	v_cmp_gt_f32_e32 vcc, 0, v103
	v_and_b32_e32 v100, 0x7fffffff, v96
	s_nop 0
	v_cndmask_b32_e32 v107, v101, v105, vcc
	v_and_b32_e32 v101, 0x7fffffff, v97
	v_pk_fma_f32 v[100:101], v[100:101], s[14:15], 1.0 op_sel_hi:[1,0,0]
	v_pk_mul_f32 v[104:105], v[96:97], v[96:97]
	v_rcp_f32_e32 v100, v100
	v_rcp_f32_e32 v101, v101
	v_pk_mul_f32 v[104:105], v[104:105], s[36:37] op_sel_hi:[1,0]
	v_cmp_gt_f32_e32 vcc, 0, v96
	v_exp_f32_e32 v104, v104
	v_pk_fma_f32 v[102:103], v[100:101], s[0:1], v[120:121] op_sel_hi:[1,0,0]
	v_exp_f32_e32 v105, v105
	v_pk_fma_f32 v[102:103], v[100:101], v[102:103], s[16:17] op_sel_hi:[1,1,0]
	s_nop 0
	v_pk_fma_f32 v[102:103], v[100:101], v[102:103], s[18:19] op_sel_hi:[1,1,0]
	s_nop 0
	v_pk_fma_f32 v[102:103], v[100:101], v[102:103], s[34:35] op_sel_hi:[1,1,0]
	s_nop 0
	v_pk_mul_f32 v[100:101], v[100:101], v[102:103]
	v_pk_mul_f32 v[102:103], v[98:99], v[98:99]
	v_pk_mul_f32 v[100:101], v[104:105], v[100:101]
	s_nop 0
	v_pk_mul_f32 v[104:105], v[96:97], v[100:101]
	v_pk_fma_f32 v[100:101], v[96:97], v[100:101], v[96:97] neg_lo:[1,0,0] neg_hi:[1,0,0]
	v_and_b32_e32 v96, 0x7fffffff, v98
	v_cndmask_b32_e32 v104, v100, v104, vcc
	v_cmp_gt_f32_e32 vcc, 0, v97
	v_and_b32_e32 v97, 0x7fffffff, v99
	v_pk_fma_f32 v[96:97], v[96:97], s[14:15], 1.0 op_sel_hi:[1,0,0]
	v_cndmask_b32_e32 v105, v101, v105, vcc
	v_rcp_f32_e32 v96, v96
	v_rcp_f32_e32 v97, v97
	v_cmp_gt_f32_e32 vcc, 0, v98
	v_pk_fma_f32 v[100:101], v[96:97], s[0:1], v[120:121] op_sel_hi:[1,0,0]
	s_nop 0
	v_pk_fma_f32 v[100:101], v[96:97], v[100:101], s[16:17] op_sel_hi:[1,1,0]
	s_nop 0
	v_pk_fma_f32 v[100:101], v[96:97], v[100:101], s[18:19] op_sel_hi:[1,1,0]
	s_nop 0
	v_pk_fma_f32 v[100:101], v[96:97], v[100:101], s[34:35] op_sel_hi:[1,1,0]
	s_nop 0
	v_pk_mul_f32 v[96:97], v[96:97], v[100:101]
	v_pk_mul_f32 v[100:101], v[102:103], s[36:37] op_sel_hi:[1,0]
	v_pk_mul_f32 v[102:103], v[92:93], v[92:93]
	v_exp_f32_e32 v100, v100
	v_exp_f32_e32 v101, v101
	v_pk_mul_f32 v[102:103], v[102:103], s[36:37] op_sel_hi:[1,0]
	v_pk_mul_f32 v[96:97], v[100:101], v[96:97]
	s_nop 0
	v_pk_mul_f32 v[100:101], v[98:99], v[96:97]
	v_pk_fma_f32 v[96:97], v[98:99], v[96:97], v[98:99] neg_lo:[1,0,0] neg_hi:[1,0,0]
	v_cvt_pk_bf16_f32 v98, v104, v105
	v_cndmask_b32_e32 v100, v96, v100, vcc
	v_cmp_gt_f32_e32 vcc, 0, v99
	v_cvt_pk_bf16_f32 v96, v108, v109
	v_exp_f32_e32 v102, v102
	v_cndmask_b32_e32 v99, v97, v101, vcc
	v_cvt_pk_bf16_f32 v97, v106, v107
	v_cvt_pk_bf16_f32 v99, v100, v99
	global_store_dwordx4 v[112:113], v[96:99], off offset:256
	v_exp_f32_e32 v103, v103
	v_cmp_gt_f32_e32 vcc, 0, v92
	v_and_b32_e32 v99, 0x7fffffff, v93
	v_and_b32_e32 v98, 0x7fffffff, v92
	v_pk_fma_f32 v[98:99], v[98:99], s[14:15], 1.0 op_sel_hi:[1,0,0]
	v_lshlrev_b64 v[96:97], 13, v[182:183]
	v_rcp_f32_e32 v98, v98
	v_rcp_f32_e32 v99, v99
	v_lshl_add_u64 v[96:97], v[130:131], 0, v[96:97]
	v_pk_fma_f32 v[100:101], v[98:99], s[0:1], v[120:121] op_sel_hi:[1,0,0]
	s_nop 0
	v_pk_fma_f32 v[100:101], v[98:99], v[100:101], s[16:17] op_sel_hi:[1,1,0]
	s_nop 0
	v_pk_fma_f32 v[100:101], v[98:99], v[100:101], s[18:19] op_sel_hi:[1,1,0]
	s_nop 0
	v_pk_fma_f32 v[100:101], v[98:99], v[100:101], s[34:35] op_sel_hi:[1,1,0]
	s_nop 0
	v_pk_mul_f32 v[98:99], v[98:99], v[100:101]
	v_pk_mul_f32 v[100:101], v[94:95], v[94:95]
	v_pk_mul_f32 v[98:99], v[102:103], v[98:99]
	s_nop 0
	v_pk_mul_f32 v[102:103], v[92:93], v[98:99]
	v_pk_fma_f32 v[98:99], v[92:93], v[98:99], v[92:93] neg_lo:[1,0,0] neg_hi:[1,0,0]
	v_and_b32_e32 v92, 0x7fffffff, v94
	v_cndmask_b32_e32 v102, v98, v102, vcc
	v_cmp_gt_f32_e32 vcc, 0, v93
	v_and_b32_e32 v93, 0x7fffffff, v95
	v_pk_fma_f32 v[92:93], v[92:93], s[14:15], 1.0 op_sel_hi:[1,0,0]
	v_cndmask_b32_e32 v103, v99, v103, vcc
	v_rcp_f32_e32 v92, v92
	v_rcp_f32_e32 v93, v93
	v_cmp_gt_f32_e32 vcc, 0, v94
	v_pk_fma_f32 v[98:99], v[92:93], s[0:1], v[120:121] op_sel_hi:[1,0,0]
	s_nop 0
	v_pk_fma_f32 v[98:99], v[92:93], v[98:99], s[16:17] op_sel_hi:[1,1,0]
	s_nop 0
	v_pk_fma_f32 v[98:99], v[92:93], v[98:99], s[18:19] op_sel_hi:[1,1,0]
	s_nop 0
	v_pk_fma_f32 v[98:99], v[92:93], v[98:99], s[34:35] op_sel_hi:[1,1,0]
	s_nop 0
	v_pk_mul_f32 v[92:93], v[92:93], v[98:99]
	v_pk_mul_f32 v[98:99], v[100:101], s[36:37] op_sel_hi:[1,0]
	s_nop 0
	v_exp_f32_e32 v98, v98
	v_exp_f32_e32 v99, v99
	s_nop 0
	v_pk_mul_f32 v[92:93], v[98:99], v[92:93]
	s_nop 0
	v_pk_mul_f32 v[98:99], v[94:95], v[92:93]
	v_pk_fma_f32 v[92:93], v[94:95], v[92:93], v[94:95] neg_lo:[1,0,0] neg_hi:[1,0,0]
	s_nop 0
	v_cndmask_b32_e32 v100, v92, v98, vcc
	v_cmp_gt_f32_e32 vcc, 0, v95
	v_and_b32_e32 v92, 0x7fffffff, v88
	s_nop 0
	v_cndmask_b32_e32 v101, v93, v99, vcc
	v_and_b32_e32 v93, 0x7fffffff, v89
	v_pk_fma_f32 v[92:93], v[92:93], s[14:15], 1.0 op_sel_hi:[1,0,0]
	v_pk_mul_f32 v[98:99], v[88:89], v[88:89]
	v_rcp_f32_e32 v92, v92
	v_rcp_f32_e32 v93, v93
	v_pk_mul_f32 v[98:99], v[98:99], s[36:37] op_sel_hi:[1,0]
	v_cmp_gt_f32_e32 vcc, 0, v88
	v_exp_f32_e32 v98, v98
	v_pk_fma_f32 v[94:95], v[92:93], s[0:1], v[120:121] op_sel_hi:[1,0,0]
	v_exp_f32_e32 v99, v99
; DEV bf16x8 pack8(f32x4 a, f32x4 b) { u32x4 w; w.x = cvt_pk_bf16(a[0], a[1]); w.y = cvt_pk_bf16(a[2], a[3]); w.z = cvt_pk_bf16(b[0], b[1]); w.w = cvt_pk_bf16(b[2], b[3]); return __builtin_bit_cast(bf16x8, w); }
; DEV f32x2 gelu_pk(f32x2 v) {
;     const f32x2 av = __builtin_elementwise_abs(v), d = av * 0.2316418882f + 1.0f;
;     f32x2 t; t.x = __builtin_amdgcn_rcpf(d.x); t.y = __builtin_amdgcn_rcpf(d.y);
;     f32x2 q = t * 0.5307027145f + (-0.7265760135f); q = q * t + 0.7107068705f; q = q * t + (-0.142248368f); q = q * t + 0.127414796f; q = q * t;
;     const f32x2 s = (v * v) * (-0.72134752044f);
;     f32x2 e; e.x = __builtin_amdgcn_exp2f(s.x); e.y = __builtin_amdgcn_exp2f(s.y);
;     const f32x2 m = v * (q * e), r = v - m;
;     f32x2 o; o.x = v.x < 0.f ? m.x : r.x; o.y = v.y < 0.f ? m.y : r.y; return o;
; }
; DEV f32x4 gelu4(f32x4 v) { f32x2 a = gelu_pk((f32x2){v[0], v[1]}), b = gelu_pk((f32x2){v[2], v[3]}); return (f32x4){a.x, a.y, b.x, b.y}; }
; template <int ACT, bool PERM>
; DEV void store_bf16_tile(AccRef acc, u16* O, int ld, int row0, int col0, const float* ss) {
;     ...
;             for (int bj = 0; bj < 2; ++bj) { f32x4 v0 = acc[ai][bj][m][0] * rs, v1 = acc[ai][bj][m][1] * rs; if (ACT == 1) { v0 = gelu4(v0); v1 = gelu4(v1); }
;                 if (PERM) *(u32x4*)(rowp + bj * 128) = __builtin_bit_cast(u32x4, pack8(v0, v1));
	v_pk_fma_f32 v[94:95], v[92:93], v[94:95], s[16:17] op_sel_hi:[1,1,0]
	s_nop 0
	v_pk_fma_f32 v[94:95], v[92:93], v[94:95], s[18:19] op_sel_hi:[1,1,0]
	s_nop 0
	v_pk_fma_f32 v[94:95], v[92:93], v[94:95], s[34:35] op_sel_hi:[1,1,0]
	s_nop 0
	v_pk_mul_f32 v[92:93], v[92:93], v[94:95]
	v_pk_mul_f32 v[94:95], v[90:91], v[90:91]
	v_pk_mul_f32 v[92:93], v[98:99], v[92:93]
	s_nop 0
	v_pk_mul_f32 v[98:99], v[88:89], v[92:93]
	v_pk_fma_f32 v[92:93], v[88:89], v[92:93], v[88:89] neg_lo:[1,0,0] neg_hi:[1,0,0]
	v_and_b32_e32 v88, 0x7fffffff, v90
	v_cndmask_b32_e32 v98, v92, v98, vcc
	v_cmp_gt_f32_e32 vcc, 0, v89
	v_and_b32_e32 v89, 0x7fffffff, v91
	v_pk_fma_f32 v[88:89], v[88:89], s[14:15], 1.0 op_sel_hi:[1,0,0]
	v_cndmask_b32_e32 v99, v93, v99, vcc
	v_rcp_f32_e32 v88, v88
	v_rcp_f32_e32 v89, v89
	v_cmp_gt_f32_e32 vcc, 0, v90
	v_pk_fma_f32 v[92:93], v[88:89], s[0:1], v[120:121] op_sel_hi:[1,0,0]
	s_nop 0
	v_pk_fma_f32 v[92:93], v[88:89], v[92:93], s[16:17] op_sel_hi:[1,1,0]
	s_nop 0
	v_pk_fma_f32 v[92:93], v[88:89], v[92:93], s[18:19] op_sel_hi:[1,1,0]
	s_nop 0
	v_pk_fma_f32 v[92:93], v[88:89], v[92:93], s[34:35] op_sel_hi:[1,1,0]
	s_nop 0
	v_pk_mul_f32 v[88:89], v[88:89], v[92:93]
	v_pk_mul_f32 v[92:93], v[94:95], s[36:37] op_sel_hi:[1,0]
	s_nop 0
	v_exp_f32_e32 v92, v92
	v_exp_f32_e32 v93, v93
	s_nop 0
	v_pk_mul_f32 v[88:89], v[92:93], v[88:89]
	s_nop 0
	v_pk_mul_f32 v[92:93], v[90:91], v[88:89]
	v_pk_fma_f32 v[88:89], v[90:91], v[88:89], v[90:91] neg_lo:[1,0,0] neg_hi:[1,0,0]
	v_cvt_pk_bf16_f32 v90, v98, v99
	v_cndmask_b32_e32 v92, v88, v92, vcc
	v_cmp_gt_f32_e32 vcc, 0, v91
	v_cvt_pk_bf16_f32 v88, v102, v103
	s_nop 0
	v_cndmask_b32_e32 v91, v89, v93, vcc
	v_cvt_pk_bf16_f32 v89, v100, v101
	v_cvt_pk_bf16_f32 v91, v92, v91
	global_store_dwordx4 v[96:97], v[88:91], off
	v_pk_mul_f32 v[92:93], v[84:85], v[84:85]
	v_cmp_gt_f32_e32 vcc, 0, v84
	v_and_b32_e32 v89, 0x7fffffff, v85
	v_and_b32_e32 v88, 0x7fffffff, v84
	v_pk_fma_f32 v[88:89], v[88:89], s[14:15], 1.0 op_sel_hi:[1,0,0]
	v_pk_mul_f32 v[92:93], v[92:93], s[36:37] op_sel_hi:[1,0]
	v_rcp_f32_e32 v88, v88
	v_rcp_f32_e32 v89, v89
	v_exp_f32_e32 v92, v92
	v_exp_f32_e32 v93, v93
	v_pk_fma_f32 v[90:91], v[88:89], s[0:1], v[120:121] op_sel_hi:[1,0,0]
	s_nop 0
	v_pk_fma_f32 v[90:91], v[88:89], v[90:91], s[16:17] op_sel_hi:[1,1,0]
	s_nop 0
	v_pk_fma_f32 v[90:91], v[88:89], v[90:91], s[18:19] op_sel_hi:[1,1,0]
	s_nop 0
	v_pk_fma_f32 v[90:91], v[88:89], v[90:91], s[34:35] op_sel_hi:[1,1,0]
	s_nop 0
	v_pk_mul_f32 v[88:89], v[88:89], v[90:91]
	v_pk_mul_f32 v[90:91], v[86:87], v[86:87]
	v_pk_mul_f32 v[88:89], v[92:93], v[88:89]
	s_nop 0
	v_pk_mul_f32 v[92:93], v[84:85], v[88:89]
	v_pk_fma_f32 v[88:89], v[84:85], v[88:89], v[84:85] neg_lo:[1,0,0] neg_hi:[1,0,0]
	v_and_b32_e32 v84, 0x7fffffff, v86
	v_cndmask_b32_e32 v92, v88, v92, vcc
	v_cmp_gt_f32_e32 vcc, 0, v85
	v_and_b32_e32 v85, 0x7fffffff, v87
	v_pk_fma_f32 v[84:85], v[84:85], s[14:15], 1.0 op_sel_hi:[1,0,0]
	v_cndmask_b32_e32 v93, v89, v93, vcc
	v_rcp_f32_e32 v84, v84
	v_rcp_f32_e32 v85, v85
	v_cmp_gt_f32_e32 vcc, 0, v86
	v_pk_fma_f32 v[88:89], v[84:85], s[0:1], v[120:121] op_sel_hi:[1,0,0]
	s_nop 0
	v_pk_fma_f32 v[88:89], v[84:85], v[88:89], s[16:17] op_sel_hi:[1,1,0]
	s_nop 0
	v_pk_fma_f32 v[88:89], v[84:85], v[88:89], s[18:19] op_sel_hi:[1,1,0]
	s_nop 0
	v_pk_fma_f32 v[88:89], v[84:85], v[88:89], s[34:35] op_sel_hi:[1,1,0]
	s_nop 0
	v_pk_mul_f32 v[84:85], v[84:85], v[88:89]
	v_pk_mul_f32 v[88:89], v[90:91], s[36:37] op_sel_hi:[1,0]
	s_nop 0
	v_exp_f32_e32 v88, v88
	v_exp_f32_e32 v89, v89
	s_nop 0
	v_pk_mul_f32 v[84:85], v[88:89], v[84:85]
	s_nop 0
	v_pk_mul_f32 v[88:89], v[86:87], v[84:85]
	v_pk_fma_f32 v[84:85], v[86:87], v[84:85], v[86:87] neg_lo:[1,0,0] neg_hi:[1,0,0]
	s_nop 0
	v_cndmask_b32_e32 v90, v84, v88, vcc
	v_cmp_gt_f32_e32 vcc, 0, v87
	v_and_b32_e32 v84, 0x7fffffff, v80
	s_nop 0
	v_cndmask_b32_e32 v91, v85, v89, vcc
	v_and_b32_e32 v85, 0x7fffffff, v81
	v_pk_fma_f32 v[84:85], v[84:85], s[14:15], 1.0 op_sel_hi:[1,0,0]
	v_pk_mul_f32 v[88:89], v[80:81], v[80:81]
	v_rcp_f32_e32 v84, v84
	v_rcp_f32_e32 v85, v85
	v_pk_mul_f32 v[88:89], v[88:89], s[36:37] op_sel_hi:[1,0]
	v_cmp_gt_f32_e32 vcc, 0, v80
	v_exp_f32_e32 v88, v88
	v_pk_fma_f32 v[86:87], v[84:85], s[0:1], v[120:121] op_sel_hi:[1,0,0]
	v_exp_f32_e32 v89, v89
	v_pk_fma_f32 v[86:87], v[84:85], v[86:87], s[16:17] op_sel_hi:[1,1,0]
	s_nop 0
	v_pk_fma_f32 v[86:87], v[84:85], v[86:87], s[18:19] op_sel_hi:[1,1,0]
	s_nop 0
	v_pk_fma_f32 v[86:87], v[84:85], v[86:87], s[34:35] op_sel_hi:[1,1,0]
	s_nop 0
	v_pk_mul_f32 v[84:85], v[84:85], v[86:87]
	v_pk_mul_f32 v[86:87], v[82:83], v[82:83]
	v_pk_mul_f32 v[84:85], v[88:89], v[84:85]
	s_nop 0
	v_pk_mul_f32 v[88:89], v[80:81], v[84:85]
	v_pk_fma_f32 v[84:85], v[80:81], v[84:85], v[80:81] neg_lo:[1,0,0] neg_hi:[1,0,0]
	v_and_b32_e32 v80, 0x7fffffff, v82
	v_cndmask_b32_e32 v88, v84, v88, vcc
	v_cmp_gt_f32_e32 vcc, 0, v81
	v_and_b32_e32 v81, 0x7fffffff, v83
	v_pk_fma_f32 v[80:81], v[80:81], s[14:15], 1.0 op_sel_hi:[1,0,0]
	v_cndmask_b32_e32 v89, v85, v89, vcc
	v_rcp_f32_e32 v80, v80
	v_rcp_f32_e32 v81, v81
	v_cmp_gt_f32_e32 vcc, 0, v82
	v_pk_fma_f32 v[84:85], v[80:81], s[0:1], v[120:121] op_sel_hi:[1,0,0]
	s_nop 0
	v_pk_fma_f32 v[84:85], v[80:81], v[84:85], s[16:17] op_sel_hi:[1,1,0]
	s_nop 0
	v_pk_fma_f32 v[84:85], v[80:81], v[84:85], s[18:19] op_sel_hi:[1,1,0]
	s_nop 0
	v_pk_fma_f32 v[84:85], v[80:81], v[84:85], s[34:35] op_sel_hi:[1,1,0]
	s_nop 0
	v_pk_mul_f32 v[80:81], v[80:81], v[84:85]
	v_pk_mul_f32 v[84:85], v[86:87], s[36:37] op_sel_hi:[1,0]
	v_pk_mul_f32 v[86:87], v[76:77], v[76:77]
	v_exp_f32_e32 v84, v84
	v_exp_f32_e32 v85, v85
; DEV bf16x8 pack8(f32x4 a, f32x4 b) { u32x4 w; w.x = cvt_pk_bf16(a[0], a[1]); w.y = cvt_pk_bf16(a[2], a[3]); w.z = cvt_pk_bf16(b[0], b[1]); w.w = cvt_pk_bf16(b[2], b[3]); return __builtin_bit_cast(bf16x8, w); }
; DEV f32x2 gelu_pk(f32x2 v) {
;     const f32x2 av = __builtin_elementwise_abs(v), d = av * 0.2316418882f + 1.0f;
;     f32x2 t; t.x = __builtin_amdgcn_rcpf(d.x); t.y = __builtin_amdgcn_rcpf(d.y);
;     f32x2 q = t * 0.5307027145f + (-0.7265760135f); q = q * t + 0.7107068705f; q = q * t + (-0.142248368f); q = q * t + 0.127414796f; q = q * t;
;     const f32x2 s = (v * v) * (-0.72134752044f);
;     f32x2 e; e.x = __builtin_amdgcn_exp2f(s.x); e.y = __builtin_amdgcn_exp2f(s.y);
;     const f32x2 m = v * (q * e), r = v - m;
;     f32x2 o; o.x = v.x < 0.f ? m.x : r.x; o.y = v.y < 0.f ? m.y : r.y; return o;
; }
; DEV f32x4 gelu4(f32x4 v) { f32x2 a = gelu_pk((f32x2){v[0], v[1]}), b = gelu_pk((f32x2){v[2], v[3]}); return (f32x4){a.x, a.y, b.x, b.y}; }
; template <int ACT, bool PERM>
; DEV void store_bf16_tile(AccRef acc, u16* O, int ld, int row0, int col0, const float* ss) {
;     ...
;             for (int bj = 0; bj < 2; ++bj) { f32x4 v0 = acc[ai][bj][m][0] * rs, v1 = acc[ai][bj][m][1] * rs; if (ACT == 1) { v0 = gelu4(v0); v1 = gelu4(v1); }
;                 if (PERM) *(u32x4*)(rowp + bj * 128) = __builtin_bit_cast(u32x4, pack8(v0, v1));
	v_pk_mul_f32 v[86:87], v[86:87], s[36:37] op_sel_hi:[1,0]
	v_pk_mul_f32 v[80:81], v[84:85], v[80:81]
	s_nop 0
	v_pk_mul_f32 v[84:85], v[82:83], v[80:81]
	v_pk_fma_f32 v[80:81], v[82:83], v[80:81], v[82:83] neg_lo:[1,0,0] neg_hi:[1,0,0]
	v_cvt_pk_bf16_f32 v82, v88, v89
	v_cndmask_b32_e32 v84, v80, v84, vcc
	v_cmp_gt_f32_e32 vcc, 0, v83
	v_cvt_pk_bf16_f32 v80, v92, v93
	v_exp_f32_e32 v86, v86
	v_cndmask_b32_e32 v83, v81, v85, vcc
	v_cvt_pk_bf16_f32 v81, v90, v91
	v_cvt_pk_bf16_f32 v83, v84, v83
	global_store_dwordx4 v[96:97], v[80:83], off offset:256
	v_exp_f32_e32 v87, v87
	v_cmp_gt_f32_e32 vcc, 0, v76
	v_and_b32_e32 v83, 0x7fffffff, v77
	v_and_b32_e32 v82, 0x7fffffff, v76
	v_pk_fma_f32 v[82:83], v[82:83], s[14:15], 1.0 op_sel_hi:[1,0,0]
	v_lshlrev_b64 v[80:81], 13, v[178:179]
	v_rcp_f32_e32 v82, v82
	v_rcp_f32_e32 v83, v83
	v_lshl_add_u64 v[80:81], v[130:131], 0, v[80:81]
	v_pk_fma_f32 v[84:85], v[82:83], s[0:1], v[120:121] op_sel_hi:[1,0,0]
	s_nop 0
	v_pk_fma_f32 v[84:85], v[82:83], v[84:85], s[16:17] op_sel_hi:[1,1,0]
	s_nop 0
	v_pk_fma_f32 v[84:85], v[82:83], v[84:85], s[18:19] op_sel_hi:[1,1,0]
	s_nop 0
	v_pk_fma_f32 v[84:85], v[82:83], v[84:85], s[34:35] op_sel_hi:[1,1,0]
	s_nop 0
	v_pk_mul_f32 v[82:83], v[82:83], v[84:85]
	v_pk_mul_f32 v[84:85], v[78:79], v[78:79]
	v_pk_mul_f32 v[82:83], v[86:87], v[82:83]
	s_nop 0
	v_pk_mul_f32 v[86:87], v[76:77], v[82:83]
	v_pk_fma_f32 v[82:83], v[76:77], v[82:83], v[76:77] neg_lo:[1,0,0] neg_hi:[1,0,0]
	v_and_b32_e32 v76, 0x7fffffff, v78
	v_cndmask_b32_e32 v86, v82, v86, vcc
	v_cmp_gt_f32_e32 vcc, 0, v77
	v_and_b32_e32 v77, 0x7fffffff, v79
	v_pk_fma_f32 v[76:77], v[76:77], s[14:15], 1.0 op_sel_hi:[1,0,0]
	v_cndmask_b32_e32 v87, v83, v87, vcc
	v_rcp_f32_e32 v76, v76
	v_rcp_f32_e32 v77, v77
	v_cmp_gt_f32_e32 vcc, 0, v78
	v_pk_fma_f32 v[82:83], v[76:77], s[0:1], v[120:121] op_sel_hi:[1,0,0]
	s_nop 0
	v_pk_fma_f32 v[82:83], v[76:77], v[82:83], s[16:17] op_sel_hi:[1,1,0]
	s_nop 0
	v_pk_fma_f32 v[82:83], v[76:77], v[82:83], s[18:19] op_sel_hi:[1,1,0]
	s_nop 0
	v_pk_fma_f32 v[82:83], v[76:77], v[82:83], s[34:35] op_sel_hi:[1,1,0]
	s_nop 0
	v_pk_mul_f32 v[76:77], v[76:77], v[82:83]
	v_pk_mul_f32 v[82:83], v[84:85], s[36:37] op_sel_hi:[1,0]
	s_nop 0
	v_exp_f32_e32 v82, v82
	v_exp_f32_e32 v83, v83
	s_nop 0
	v_pk_mul_f32 v[76:77], v[82:83], v[76:77]
	s_nop 0
	v_pk_mul_f32 v[82:83], v[78:79], v[76:77]
	v_pk_fma_f32 v[76:77], v[78:79], v[76:77], v[78:79] neg_lo:[1,0,0] neg_hi:[1,0,0]
	s_nop 0
	v_cndmask_b32_e32 v84, v76, v82, vcc
	v_cmp_gt_f32_e32 vcc, 0, v79
	v_and_b32_e32 v76, 0x7fffffff, v72
	s_nop 0
	v_cndmask_b32_e32 v85, v77, v83, vcc
	v_and_b32_e32 v77, 0x7fffffff, v73
	v_pk_fma_f32 v[76:77], v[76:77], s[14:15], 1.0 op_sel_hi:[1,0,0]
	v_pk_mul_f32 v[82:83], v[72:73], v[72:73]
	v_rcp_f32_e32 v76, v76
	v_rcp_f32_e32 v77, v77
	v_pk_mul_f32 v[82:83], v[82:83], s[36:37] op_sel_hi:[1,0]
	v_cmp_gt_f32_e32 vcc, 0, v72
	v_exp_f32_e32 v82, v82
	v_pk_fma_f32 v[78:79], v[76:77], s[0:1], v[120:121] op_sel_hi:[1,0,0]
	v_exp_f32_e32 v83, v83
	v_pk_fma_f32 v[78:79], v[76:77], v[78:79], s[16:17] op_sel_hi:[1,1,0]
	s_nop 0
	v_pk_fma_f32 v[78:79], v[76:77], v[78:79], s[18:19] op_sel_hi:[1,1,0]
	s_nop 0
	v_pk_fma_f32 v[78:79], v[76:77], v[78:79], s[34:35] op_sel_hi:[1,1,0]
	s_nop 0
	v_pk_mul_f32 v[76:77], v[76:77], v[78:79]
	v_pk_mul_f32 v[78:79], v[74:75], v[74:75]
	v_pk_mul_f32 v[76:77], v[82:83], v[76:77]
	s_nop 0
	v_pk_mul_f32 v[82:83], v[72:73], v[76:77]
	v_pk_fma_f32 v[76:77], v[72:73], v[76:77], v[72:73] neg_lo:[1,0,0] neg_hi:[1,0,0]
	v_and_b32_e32 v72, 0x7fffffff, v74
	v_cndmask_b32_e32 v82, v76, v82, vcc
	v_cmp_gt_f32_e32 vcc, 0, v73
	v_and_b32_e32 v73, 0x7fffffff, v75
	v_pk_fma_f32 v[72:73], v[72:73], s[14:15], 1.0 op_sel_hi:[1,0,0]
	v_cndmask_b32_e32 v83, v77, v83, vcc
	v_rcp_f32_e32 v72, v72
	v_rcp_f32_e32 v73, v73
	v_cmp_gt_f32_e32 vcc, 0, v74
	v_pk_fma_f32 v[76:77], v[72:73], s[0:1], v[120:121] op_sel_hi:[1,0,0]
	s_nop 0
	v_pk_fma_f32 v[76:77], v[72:73], v[76:77], s[16:17] op_sel_hi:[1,1,0]
	s_nop 0
	v_pk_fma_f32 v[76:77], v[72:73], v[76:77], s[18:19] op_sel_hi:[1,1,0]
	s_nop 0
	v_pk_fma_f32 v[76:77], v[72:73], v[76:77], s[34:35] op_sel_hi:[1,1,0]
	s_nop 0
	v_pk_mul_f32 v[72:73], v[72:73], v[76:77]
	v_pk_mul_f32 v[76:77], v[78:79], s[36:37] op_sel_hi:[1,0]
	s_nop 0
	v_exp_f32_e32 v76, v76
	v_exp_f32_e32 v77, v77
	s_nop 0
	v_pk_mul_f32 v[72:73], v[76:77], v[72:73]
	s_nop 0
	v_pk_mul_f32 v[76:77], v[74:75], v[72:73]
	v_pk_fma_f32 v[72:73], v[74:75], v[72:73], v[74:75] neg_lo:[1,0,0] neg_hi:[1,0,0]
	v_cvt_pk_bf16_f32 v74, v82, v83
	v_cndmask_b32_e32 v76, v72, v76, vcc
	v_cmp_gt_f32_e32 vcc, 0, v75
	v_cvt_pk_bf16_f32 v72, v86, v87
	s_nop 0
	v_cndmask_b32_e32 v75, v73, v77, vcc
	v_cvt_pk_bf16_f32 v73, v84, v85
	v_cvt_pk_bf16_f32 v75, v76, v75
	global_store_dwordx4 v[80:81], v[72:75], off
	v_pk_mul_f32 v[76:77], v[68:69], v[68:69]
	v_cmp_gt_f32_e32 vcc, 0, v68
	v_and_b32_e32 v73, 0x7fffffff, v69
	v_and_b32_e32 v72, 0x7fffffff, v68
	v_pk_fma_f32 v[72:73], v[72:73], s[14:15], 1.0 op_sel_hi:[1,0,0]
	v_pk_mul_f32 v[76:77], v[76:77], s[36:37] op_sel_hi:[1,0]
	v_rcp_f32_e32 v72, v72
	v_rcp_f32_e32 v73, v73
	v_exp_f32_e32 v76, v76
	v_exp_f32_e32 v77, v77
	v_pk_fma_f32 v[74:75], v[72:73], s[0:1], v[120:121] op_sel_hi:[1,0,0]
	s_nop 0
	v_pk_fma_f32 v[74:75], v[72:73], v[74:75], s[16:17] op_sel_hi:[1,1,0]
	s_nop 0
	v_pk_fma_f32 v[74:75], v[72:73], v[74:75], s[18:19] op_sel_hi:[1,1,0]
	s_nop 0
	v_pk_fma_f32 v[74:75], v[72:73], v[74:75], s[34:35] op_sel_hi:[1,1,0]
	s_nop 0
	v_pk_mul_f32 v[72:73], v[72:73], v[74:75]
	v_pk_mul_f32 v[74:75], v[70:71], v[70:71]
	v_pk_mul_f32 v[72:73], v[76:77], v[72:73]
	s_nop 0
; DEV bf16x8 pack8(f32x4 a, f32x4 b) { u32x4 w; w.x = cvt_pk_bf16(a[0], a[1]); w.y = cvt_pk_bf16(a[2], a[3]); w.z = cvt_pk_bf16(b[0], b[1]); w.w = cvt_pk_bf16(b[2], b[3]); return __builtin_bit_cast(bf16x8, w); }
; DEV f32x2 gelu_pk(f32x2 v) {
;     const f32x2 av = __builtin_elementwise_abs(v), d = av * 0.2316418882f + 1.0f;
;     f32x2 t; t.x = __builtin_amdgcn_rcpf(d.x); t.y = __builtin_amdgcn_rcpf(d.y);
;     f32x2 q = t * 0.5307027145f + (-0.7265760135f); q = q * t + 0.7107068705f; q = q * t + (-0.142248368f); q = q * t + 0.127414796f; q = q * t;
;     const f32x2 s = (v * v) * (-0.72134752044f);
;     f32x2 e; e.x = __builtin_amdgcn_exp2f(s.x); e.y = __builtin_amdgcn_exp2f(s.y);
;     const f32x2 m = v * (q * e), r = v - m;
;     f32x2 o; o.x = v.x < 0.f ? m.x : r.x; o.y = v.y < 0.f ? m.y : r.y; return o;
; }
; DEV f32x4 gelu4(f32x4 v) { f32x2 a = gelu_pk((f32x2){v[0], v[1]}), b = gelu_pk((f32x2){v[2], v[3]}); return (f32x4){a.x, a.y, b.x, b.y}; }
; template <int ACT, bool PERM>
; DEV void store_bf16_tile(AccRef acc, u16* O, int ld, int row0, int col0, const float* ss) {
;     ...
;             for (int bj = 0; bj < 2; ++bj) { f32x4 v0 = acc[ai][bj][m][0] * rs, v1 = acc[ai][bj][m][1] * rs; if (ACT == 1) { v0 = gelu4(v0); v1 = gelu4(v1); }
;                 if (PERM) *(u32x4*)(rowp + bj * 128) = __builtin_bit_cast(u32x4, pack8(v0, v1));
	v_pk_mul_f32 v[76:77], v[68:69], v[72:73]
	v_pk_fma_f32 v[72:73], v[68:69], v[72:73], v[68:69] neg_lo:[1,0,0] neg_hi:[1,0,0]
	v_and_b32_e32 v68, 0x7fffffff, v70
	v_cndmask_b32_e32 v76, v72, v76, vcc
	v_cmp_gt_f32_e32 vcc, 0, v69
	v_and_b32_e32 v69, 0x7fffffff, v71
	v_pk_fma_f32 v[68:69], v[68:69], s[14:15], 1.0 op_sel_hi:[1,0,0]
	v_cndmask_b32_e32 v77, v73, v77, vcc
	v_rcp_f32_e32 v68, v68
	v_rcp_f32_e32 v69, v69
	v_cmp_gt_f32_e32 vcc, 0, v70
	v_pk_fma_f32 v[72:73], v[68:69], s[0:1], v[120:121] op_sel_hi:[1,0,0]
	s_nop 0
	v_pk_fma_f32 v[72:73], v[68:69], v[72:73], s[16:17] op_sel_hi:[1,1,0]
	s_nop 0
	v_pk_fma_f32 v[72:73], v[68:69], v[72:73], s[18:19] op_sel_hi:[1,1,0]
	s_nop 0
	v_pk_fma_f32 v[72:73], v[68:69], v[72:73], s[34:35] op_sel_hi:[1,1,0]
	s_nop 0
	v_pk_mul_f32 v[68:69], v[68:69], v[72:73]
	v_pk_mul_f32 v[72:73], v[74:75], s[36:37] op_sel_hi:[1,0]
	s_nop 0
	v_exp_f32_e32 v72, v72
	v_exp_f32_e32 v73, v73
	s_nop 0
	v_pk_mul_f32 v[68:69], v[72:73], v[68:69]
	s_nop 0
	v_pk_mul_f32 v[72:73], v[70:71], v[68:69]
	v_pk_fma_f32 v[68:69], v[70:71], v[68:69], v[70:71] neg_lo:[1,0,0] neg_hi:[1,0,0]
	s_nop 0
	v_cndmask_b32_e32 v74, v68, v72, vcc
	v_cmp_gt_f32_e32 vcc, 0, v71
	v_and_b32_e32 v68, 0x7fffffff, v64
	s_nop 0
	v_cndmask_b32_e32 v75, v69, v73, vcc
	v_and_b32_e32 v69, 0x7fffffff, v65
	v_pk_fma_f32 v[68:69], v[68:69], s[14:15], 1.0 op_sel_hi:[1,0,0]
	v_pk_mul_f32 v[72:73], v[64:65], v[64:65]
	v_rcp_f32_e32 v68, v68
	v_rcp_f32_e32 v69, v69
	v_pk_mul_f32 v[72:73], v[72:73], s[36:37] op_sel_hi:[1,0]
	v_cmp_gt_f32_e32 vcc, 0, v64
	v_exp_f32_e32 v72, v72
	v_pk_fma_f32 v[70:71], v[68:69], s[0:1], v[120:121] op_sel_hi:[1,0,0]
	v_exp_f32_e32 v73, v73
	v_pk_fma_f32 v[70:71], v[68:69], v[70:71], s[16:17] op_sel_hi:[1,1,0]
	s_nop 0
	v_pk_fma_f32 v[70:71], v[68:69], v[70:71], s[18:19] op_sel_hi:[1,1,0]
	s_nop 0
	v_pk_fma_f32 v[70:71], v[68:69], v[70:71], s[34:35] op_sel_hi:[1,1,0]
	s_nop 0
	v_pk_mul_f32 v[68:69], v[68:69], v[70:71]
	v_pk_mul_f32 v[70:71], v[66:67], v[66:67]
	v_pk_mul_f32 v[68:69], v[72:73], v[68:69]
	s_nop 0
	v_pk_mul_f32 v[72:73], v[64:65], v[68:69]
	v_pk_fma_f32 v[68:69], v[64:65], v[68:69], v[64:65] neg_lo:[1,0,0] neg_hi:[1,0,0]
	v_and_b32_e32 v64, 0x7fffffff, v66
	v_cndmask_b32_e32 v72, v68, v72, vcc
	v_cmp_gt_f32_e32 vcc, 0, v65
	v_and_b32_e32 v65, 0x7fffffff, v67
	v_pk_fma_f32 v[64:65], v[64:65], s[14:15], 1.0 op_sel_hi:[1,0,0]
	v_cndmask_b32_e32 v73, v69, v73, vcc
	v_rcp_f32_e32 v64, v64
	v_rcp_f32_e32 v65, v65
	v_cmp_gt_f32_e32 vcc, 0, v66
	v_pk_fma_f32 v[68:69], v[64:65], s[0:1], v[120:121] op_sel_hi:[1,0,0]
	s_nop 0
	v_pk_fma_f32 v[68:69], v[64:65], v[68:69], s[16:17] op_sel_hi:[1,1,0]
	s_nop 0
	v_pk_fma_f32 v[68:69], v[64:65], v[68:69], s[18:19] op_sel_hi:[1,1,0]
	s_nop 0
	v_pk_fma_f32 v[68:69], v[64:65], v[68:69], s[34:35] op_sel_hi:[1,1,0]
	s_nop 0
	v_pk_mul_f32 v[64:65], v[64:65], v[68:69]
	v_pk_mul_f32 v[68:69], v[70:71], s[36:37] op_sel_hi:[1,0]
	v_pk_mul_f32 v[70:71], v[60:61], v[60:61]
	v_exp_f32_e32 v68, v68
	v_exp_f32_e32 v69, v69
	v_pk_mul_f32 v[70:71], v[70:71], s[36:37] op_sel_hi:[1,0]
	v_pk_mul_f32 v[64:65], v[68:69], v[64:65]
	s_nop 0
	v_pk_mul_f32 v[68:69], v[66:67], v[64:65]
	v_pk_fma_f32 v[64:65], v[66:67], v[64:65], v[66:67] neg_lo:[1,0,0] neg_hi:[1,0,0]
	v_cvt_pk_bf16_f32 v66, v72, v73
	v_cndmask_b32_e32 v68, v64, v68, vcc
	v_cmp_gt_f32_e32 vcc, 0, v67
	v_cvt_pk_bf16_f32 v64, v76, v77
	v_exp_f32_e32 v70, v70
	v_cndmask_b32_e32 v67, v65, v69, vcc
	v_cvt_pk_bf16_f32 v65, v74, v75
	v_cvt_pk_bf16_f32 v67, v68, v67
	global_store_dwordx4 v[80:81], v[64:67], off offset:256
	v_exp_f32_e32 v71, v71
	v_cmp_gt_f32_e32 vcc, 0, v60
	v_and_b32_e32 v67, 0x7fffffff, v61
	v_and_b32_e32 v66, 0x7fffffff, v60
	v_pk_fma_f32 v[66:67], v[66:67], s[14:15], 1.0 op_sel_hi:[1,0,0]
	v_lshlrev_b64 v[64:65], 13, v[174:175]
	v_rcp_f32_e32 v66, v66
	v_rcp_f32_e32 v67, v67
	v_lshl_add_u64 v[64:65], v[130:131], 0, v[64:65]
	v_pk_fma_f32 v[68:69], v[66:67], s[0:1], v[120:121] op_sel_hi:[1,0,0]
	s_nop 0
	v_pk_fma_f32 v[68:69], v[66:67], v[68:69], s[16:17] op_sel_hi:[1,1,0]
	s_nop 0
	v_pk_fma_f32 v[68:69], v[66:67], v[68:69], s[18:19] op_sel_hi:[1,1,0]
	s_nop 0
	v_pk_fma_f32 v[68:69], v[66:67], v[68:69], s[34:35] op_sel_hi:[1,1,0]
	s_nop 0
	v_pk_mul_f32 v[66:67], v[66:67], v[68:69]
	v_pk_mul_f32 v[68:69], v[62:63], v[62:63]
	v_pk_mul_f32 v[66:67], v[70:71], v[66:67]
	s_nop 0
	v_pk_mul_f32 v[70:71], v[60:61], v[66:67]
	v_pk_fma_f32 v[66:67], v[60:61], v[66:67], v[60:61] neg_lo:[1,0,0] neg_hi:[1,0,0]
	v_and_b32_e32 v60, 0x7fffffff, v62
	v_cndmask_b32_e32 v70, v66, v70, vcc
	v_cmp_gt_f32_e32 vcc, 0, v61
	v_and_b32_e32 v61, 0x7fffffff, v63
	v_pk_fma_f32 v[60:61], v[60:61], s[14:15], 1.0 op_sel_hi:[1,0,0]
	v_cndmask_b32_e32 v71, v67, v71, vcc
	v_rcp_f32_e32 v60, v60
	v_rcp_f32_e32 v61, v61
	v_cmp_gt_f32_e32 vcc, 0, v62
	v_pk_fma_f32 v[66:67], v[60:61], s[0:1], v[120:121] op_sel_hi:[1,0,0]
	s_nop 0
	v_pk_fma_f32 v[66:67], v[60:61], v[66:67], s[16:17] op_sel_hi:[1,1,0]
	s_nop 0
	v_pk_fma_f32 v[66:67], v[60:61], v[66:67], s[18:19] op_sel_hi:[1,1,0]
	s_nop 0
	v_pk_fma_f32 v[66:67], v[60:61], v[66:67], s[34:35] op_sel_hi:[1,1,0]
	s_nop 0
	v_pk_mul_f32 v[60:61], v[60:61], v[66:67]
	v_pk_mul_f32 v[66:67], v[68:69], s[36:37] op_sel_hi:[1,0]
	s_nop 0
	v_exp_f32_e32 v66, v66
	v_exp_f32_e32 v67, v67
	s_nop 0
	v_pk_mul_f32 v[60:61], v[66:67], v[60:61]
	s_nop 0
	v_pk_mul_f32 v[66:67], v[62:63], v[60:61]
	v_pk_fma_f32 v[60:61], v[62:63], v[60:61], v[62:63] neg_lo:[1,0,0] neg_hi:[1,0,0]
	s_nop 0
	v_cndmask_b32_e32 v68, v60, v66, vcc
	v_cmp_gt_f32_e32 vcc, 0, v63
	v_and_b32_e32 v60, 0x7fffffff, v56
	s_nop 0
	v_cndmask_b32_e32 v69, v61, v67, vcc
; DEV bf16x8 pack8(f32x4 a, f32x4 b) { u32x4 w; w.x = cvt_pk_bf16(a[0], a[1]); w.y = cvt_pk_bf16(a[2], a[3]); w.z = cvt_pk_bf16(b[0], b[1]); w.w = cvt_pk_bf16(b[2], b[3]); return __builtin_bit_cast(bf16x8, w); }
; DEV f32x2 gelu_pk(f32x2 v) {
;     const f32x2 av = __builtin_elementwise_abs(v), d = av * 0.2316418882f + 1.0f;
;     f32x2 t; t.x = __builtin_amdgcn_rcpf(d.x); t.y = __builtin_amdgcn_rcpf(d.y);
;     f32x2 q = t * 0.5307027145f + (-0.7265760135f); q = q * t + 0.7107068705f; q = q * t + (-0.142248368f); q = q * t + 0.127414796f; q = q * t;
;     const f32x2 s = (v * v) * (-0.72134752044f);
;     f32x2 e; e.x = __builtin_amdgcn_exp2f(s.x); e.y = __builtin_amdgcn_exp2f(s.y);
;     const f32x2 m = v * (q * e), r = v - m;
;     f32x2 o; o.x = v.x < 0.f ? m.x : r.x; o.y = v.y < 0.f ? m.y : r.y; return o;
; }
; DEV f32x4 gelu4(f32x4 v) { f32x2 a = gelu_pk((f32x2){v[0], v[1]}), b = gelu_pk((f32x2){v[2], v[3]}); return (f32x4){a.x, a.y, b.x, b.y}; }
; template <int ACT, bool PERM>
; DEV void store_bf16_tile(AccRef acc, u16* O, int ld, int row0, int col0, const float* ss) {
;     ...
;             for (int bj = 0; bj < 2; ++bj) { f32x4 v0 = acc[ai][bj][m][0] * rs, v1 = acc[ai][bj][m][1] * rs; if (ACT == 1) { v0 = gelu4(v0); v1 = gelu4(v1); }
;                 if (PERM) *(u32x4*)(rowp + bj * 128) = __builtin_bit_cast(u32x4, pack8(v0, v1));
	v_and_b32_e32 v61, 0x7fffffff, v57
	v_pk_fma_f32 v[60:61], v[60:61], s[14:15], 1.0 op_sel_hi:[1,0,0]
	v_pk_mul_f32 v[66:67], v[56:57], v[56:57]
	v_rcp_f32_e32 v60, v60
	v_rcp_f32_e32 v61, v61
	v_pk_mul_f32 v[66:67], v[66:67], s[36:37] op_sel_hi:[1,0]
	v_cmp_gt_f32_e32 vcc, 0, v56
	v_exp_f32_e32 v66, v66
	v_pk_fma_f32 v[62:63], v[60:61], s[0:1], v[120:121] op_sel_hi:[1,0,0]
	v_exp_f32_e32 v67, v67
	v_pk_fma_f32 v[62:63], v[60:61], v[62:63], s[16:17] op_sel_hi:[1,1,0]
	s_nop 0
	v_pk_fma_f32 v[62:63], v[60:61], v[62:63], s[18:19] op_sel_hi:[1,1,0]
	s_nop 0
	v_pk_fma_f32 v[62:63], v[60:61], v[62:63], s[34:35] op_sel_hi:[1,1,0]
	s_nop 0
	v_pk_mul_f32 v[60:61], v[60:61], v[62:63]
	v_pk_mul_f32 v[62:63], v[58:59], v[58:59]
	v_pk_mul_f32 v[60:61], v[66:67], v[60:61]
	s_nop 0
	v_pk_mul_f32 v[66:67], v[56:57], v[60:61]
	v_pk_fma_f32 v[60:61], v[56:57], v[60:61], v[56:57] neg_lo:[1,0,0] neg_hi:[1,0,0]
	v_and_b32_e32 v56, 0x7fffffff, v58
	v_cndmask_b32_e32 v66, v60, v66, vcc
	v_cmp_gt_f32_e32 vcc, 0, v57
	v_and_b32_e32 v57, 0x7fffffff, v59
	v_pk_fma_f32 v[56:57], v[56:57], s[14:15], 1.0 op_sel_hi:[1,0,0]
	v_cndmask_b32_e32 v67, v61, v67, vcc
	v_rcp_f32_e32 v56, v56
	v_rcp_f32_e32 v57, v57
	v_cmp_gt_f32_e32 vcc, 0, v58
	v_pk_fma_f32 v[60:61], v[56:57], s[0:1], v[120:121] op_sel_hi:[1,0,0]
	s_nop 0
	v_pk_fma_f32 v[60:61], v[56:57], v[60:61], s[16:17] op_sel_hi:[1,1,0]
	s_nop 0
	v_pk_fma_f32 v[60:61], v[56:57], v[60:61], s[18:19] op_sel_hi:[1,1,0]
	s_nop 0
	v_pk_fma_f32 v[60:61], v[56:57], v[60:61], s[34:35] op_sel_hi:[1,1,0]
	s_nop 0
	v_pk_mul_f32 v[56:57], v[56:57], v[60:61]
	v_pk_mul_f32 v[60:61], v[62:63], s[36:37] op_sel_hi:[1,0]
	s_nop 0
	v_exp_f32_e32 v60, v60
	v_exp_f32_e32 v61, v61
	s_nop 0
	v_pk_mul_f32 v[56:57], v[60:61], v[56:57]
	s_nop 0
	v_pk_mul_f32 v[60:61], v[58:59], v[56:57]
	v_pk_fma_f32 v[56:57], v[58:59], v[56:57], v[58:59] neg_lo:[1,0,0] neg_hi:[1,0,0]
	v_cvt_pk_bf16_f32 v58, v66, v67
	v_cndmask_b32_e32 v60, v56, v60, vcc
	v_cmp_gt_f32_e32 vcc, 0, v59
	v_cvt_pk_bf16_f32 v56, v70, v71
	s_nop 0
	v_cndmask_b32_e32 v59, v57, v61, vcc
	v_cvt_pk_bf16_f32 v57, v68, v69
	v_cvt_pk_bf16_f32 v59, v60, v59
	global_store_dwordx4 v[64:65], v[56:59], off
	v_pk_mul_f32 v[60:61], v[52:53], v[52:53]
	v_cmp_gt_f32_e32 vcc, 0, v52
	v_and_b32_e32 v57, 0x7fffffff, v53
	v_and_b32_e32 v56, 0x7fffffff, v52
	v_pk_fma_f32 v[56:57], v[56:57], s[14:15], 1.0 op_sel_hi:[1,0,0]
	v_pk_mul_f32 v[60:61], v[60:61], s[36:37] op_sel_hi:[1,0]
	v_rcp_f32_e32 v56, v56
	v_rcp_f32_e32 v57, v57
	v_exp_f32_e32 v60, v60
	v_exp_f32_e32 v61, v61
	v_pk_fma_f32 v[58:59], v[56:57], s[0:1], v[120:121] op_sel_hi:[1,0,0]
	s_nop 0
	v_pk_fma_f32 v[58:59], v[56:57], v[58:59], s[16:17] op_sel_hi:[1,1,0]
	s_nop 0
	v_pk_fma_f32 v[58:59], v[56:57], v[58:59], s[18:19] op_sel_hi:[1,1,0]
	s_nop 0
	v_pk_fma_f32 v[58:59], v[56:57], v[58:59], s[34:35] op_sel_hi:[1,1,0]
	s_nop 0
	v_pk_mul_f32 v[56:57], v[56:57], v[58:59]
	v_pk_mul_f32 v[58:59], v[54:55], v[54:55]
	v_pk_mul_f32 v[56:57], v[60:61], v[56:57]
	s_nop 0
	v_pk_mul_f32 v[60:61], v[52:53], v[56:57]
	v_pk_fma_f32 v[56:57], v[52:53], v[56:57], v[52:53] neg_lo:[1,0,0] neg_hi:[1,0,0]
	v_and_b32_e32 v52, 0x7fffffff, v54
	v_cndmask_b32_e32 v60, v56, v60, vcc
	v_cmp_gt_f32_e32 vcc, 0, v53
	v_and_b32_e32 v53, 0x7fffffff, v55
	v_pk_fma_f32 v[52:53], v[52:53], s[14:15], 1.0 op_sel_hi:[1,0,0]
	v_cndmask_b32_e32 v61, v57, v61, vcc
	v_rcp_f32_e32 v52, v52
	v_rcp_f32_e32 v53, v53
	v_cmp_gt_f32_e32 vcc, 0, v54
	v_pk_fma_f32 v[56:57], v[52:53], s[0:1], v[120:121] op_sel_hi:[1,0,0]
	s_nop 0
	v_pk_fma_f32 v[56:57], v[52:53], v[56:57], s[16:17] op_sel_hi:[1,1,0]
	s_nop 0
	v_pk_fma_f32 v[56:57], v[52:53], v[56:57], s[18:19] op_sel_hi:[1,1,0]
	s_nop 0
	v_pk_fma_f32 v[56:57], v[52:53], v[56:57], s[34:35] op_sel_hi:[1,1,0]
	s_nop 0
	v_pk_mul_f32 v[52:53], v[52:53], v[56:57]
	v_pk_mul_f32 v[56:57], v[58:59], s[36:37] op_sel_hi:[1,0]
	s_nop 0
	v_exp_f32_e32 v56, v56
	v_exp_f32_e32 v57, v57
	s_nop 0
	v_pk_mul_f32 v[52:53], v[56:57], v[52:53]
	s_nop 0
	v_pk_mul_f32 v[56:57], v[54:55], v[52:53]
	v_pk_fma_f32 v[52:53], v[54:55], v[52:53], v[54:55] neg_lo:[1,0,0] neg_hi:[1,0,0]
	s_nop 0
	v_cndmask_b32_e32 v58, v52, v56, vcc
	v_cmp_gt_f32_e32 vcc, 0, v55
	v_and_b32_e32 v52, 0x7fffffff, v48
	s_nop 0
	v_cndmask_b32_e32 v59, v53, v57, vcc
	v_and_b32_e32 v53, 0x7fffffff, v49
	v_pk_fma_f32 v[52:53], v[52:53], s[14:15], 1.0 op_sel_hi:[1,0,0]
	v_pk_mul_f32 v[56:57], v[48:49], v[48:49]
	v_rcp_f32_e32 v52, v52
	v_rcp_f32_e32 v53, v53
	v_pk_mul_f32 v[56:57], v[56:57], s[36:37] op_sel_hi:[1,0]
	v_cmp_gt_f32_e32 vcc, 0, v48
	v_exp_f32_e32 v56, v56
	v_pk_fma_f32 v[54:55], v[52:53], s[0:1], v[120:121] op_sel_hi:[1,0,0]
	v_exp_f32_e32 v57, v57
	v_pk_fma_f32 v[54:55], v[52:53], v[54:55], s[16:17] op_sel_hi:[1,1,0]
	s_nop 0
	v_pk_fma_f32 v[54:55], v[52:53], v[54:55], s[18:19] op_sel_hi:[1,1,0]
	s_nop 0
	v_pk_fma_f32 v[54:55], v[52:53], v[54:55], s[34:35] op_sel_hi:[1,1,0]
	s_nop 0
	v_pk_mul_f32 v[52:53], v[52:53], v[54:55]
	v_pk_mul_f32 v[54:55], v[50:51], v[50:51]
	v_pk_mul_f32 v[52:53], v[56:57], v[52:53]
	s_nop 0
	v_pk_mul_f32 v[56:57], v[48:49], v[52:53]
	v_pk_fma_f32 v[52:53], v[48:49], v[52:53], v[48:49] neg_lo:[1,0,0] neg_hi:[1,0,0]
	v_and_b32_e32 v48, 0x7fffffff, v50
	v_cndmask_b32_e32 v56, v52, v56, vcc
	v_cmp_gt_f32_e32 vcc, 0, v49
	v_and_b32_e32 v49, 0x7fffffff, v51
	v_pk_fma_f32 v[48:49], v[48:49], s[14:15], 1.0 op_sel_hi:[1,0,0]
	v_cndmask_b32_e32 v57, v53, v57, vcc
	v_rcp_f32_e32 v48, v48
	v_rcp_f32_e32 v49, v49
	v_cmp_gt_f32_e32 vcc, 0, v50
	v_pk_fma_f32 v[52:53], v[48:49], s[0:1], v[120:121] op_sel_hi:[1,0,0]
	s_nop 0
	v_pk_fma_f32 v[52:53], v[48:49], v[52:53], s[16:17] op_sel_hi:[1,1,0]
; DEV bf16x8 pack8(f32x4 a, f32x4 b) { u32x4 w; w.x = cvt_pk_bf16(a[0], a[1]); w.y = cvt_pk_bf16(a[2], a[3]); w.z = cvt_pk_bf16(b[0], b[1]); w.w = cvt_pk_bf16(b[2], b[3]); return __builtin_bit_cast(bf16x8, w); }
; DEV f32x2 gelu_pk(f32x2 v) {
;     const f32x2 av = __builtin_elementwise_abs(v), d = av * 0.2316418882f + 1.0f;
;     f32x2 t; t.x = __builtin_amdgcn_rcpf(d.x); t.y = __builtin_amdgcn_rcpf(d.y);
;     f32x2 q = t * 0.5307027145f + (-0.7265760135f); q = q * t + 0.7107068705f; q = q * t + (-0.142248368f); q = q * t + 0.127414796f; q = q * t;
;     const f32x2 s = (v * v) * (-0.72134752044f);
;     f32x2 e; e.x = __builtin_amdgcn_exp2f(s.x); e.y = __builtin_amdgcn_exp2f(s.y);
;     const f32x2 m = v * (q * e), r = v - m;
;     f32x2 o; o.x = v.x < 0.f ? m.x : r.x; o.y = v.y < 0.f ? m.y : r.y; return o;
; }
; DEV f32x4 gelu4(f32x4 v) { f32x2 a = gelu_pk((f32x2){v[0], v[1]}), b = gelu_pk((f32x2){v[2], v[3]}); return (f32x4){a.x, a.y, b.x, b.y}; }
; template <int ACT, bool PERM>
; DEV void store_bf16_tile(AccRef acc, u16* O, int ld, int row0, int col0, const float* ss) {
;     ...
;             for (int bj = 0; bj < 2; ++bj) { f32x4 v0 = acc[ai][bj][m][0] * rs, v1 = acc[ai][bj][m][1] * rs; if (ACT == 1) { v0 = gelu4(v0); v1 = gelu4(v1); }
;                 if (PERM) *(u32x4*)(rowp + bj * 128) = __builtin_bit_cast(u32x4, pack8(v0, v1));
	s_nop 0
	v_pk_fma_f32 v[52:53], v[48:49], v[52:53], s[18:19] op_sel_hi:[1,1,0]
	s_nop 0
	v_pk_fma_f32 v[52:53], v[48:49], v[52:53], s[34:35] op_sel_hi:[1,1,0]
	s_nop 0
	v_pk_mul_f32 v[48:49], v[48:49], v[52:53]
	v_pk_mul_f32 v[52:53], v[54:55], s[36:37] op_sel_hi:[1,0]
	v_pk_mul_f32 v[54:55], v[44:45], v[44:45]
	v_exp_f32_e32 v52, v52
	v_exp_f32_e32 v53, v53
	v_pk_mul_f32 v[54:55], v[54:55], s[36:37] op_sel_hi:[1,0]
	v_pk_mul_f32 v[48:49], v[52:53], v[48:49]
	s_nop 0
	v_pk_mul_f32 v[52:53], v[50:51], v[48:49]
	v_pk_fma_f32 v[48:49], v[50:51], v[48:49], v[50:51] neg_lo:[1,0,0] neg_hi:[1,0,0]
	v_cvt_pk_bf16_f32 v50, v56, v57
	v_cndmask_b32_e32 v52, v48, v52, vcc
	v_cmp_gt_f32_e32 vcc, 0, v51
	v_cvt_pk_bf16_f32 v48, v60, v61
	v_exp_f32_e32 v54, v54
	v_cndmask_b32_e32 v51, v49, v53, vcc
	v_cvt_pk_bf16_f32 v49, v58, v59
	v_cvt_pk_bf16_f32 v51, v52, v51
	global_store_dwordx4 v[64:65], v[48:51], off offset:256
	v_exp_f32_e32 v55, v55
	v_cmp_gt_f32_e32 vcc, 0, v44
	v_and_b32_e32 v51, 0x7fffffff, v45
	v_and_b32_e32 v50, 0x7fffffff, v44
	v_pk_fma_f32 v[50:51], v[50:51], s[14:15], 1.0 op_sel_hi:[1,0,0]
	v_lshlrev_b64 v[48:49], 13, v[158:159]
	v_rcp_f32_e32 v50, v50
	v_rcp_f32_e32 v51, v51
	v_lshl_add_u64 v[48:49], v[130:131], 0, v[48:49]
	v_pk_fma_f32 v[52:53], v[50:51], s[0:1], v[120:121] op_sel_hi:[1,0,0]
	s_nop 0
	v_pk_fma_f32 v[52:53], v[50:51], v[52:53], s[16:17] op_sel_hi:[1,1,0]
	s_nop 0
	v_pk_fma_f32 v[52:53], v[50:51], v[52:53], s[18:19] op_sel_hi:[1,1,0]
	s_nop 0
	v_pk_fma_f32 v[52:53], v[50:51], v[52:53], s[34:35] op_sel_hi:[1,1,0]
	s_nop 0
	v_pk_mul_f32 v[50:51], v[50:51], v[52:53]
	v_pk_mul_f32 v[52:53], v[46:47], v[46:47]
	v_pk_mul_f32 v[50:51], v[54:55], v[50:51]
	s_nop 0
	v_pk_mul_f32 v[54:55], v[44:45], v[50:51]
	v_pk_fma_f32 v[50:51], v[44:45], v[50:51], v[44:45] neg_lo:[1,0,0] neg_hi:[1,0,0]
	v_and_b32_e32 v44, 0x7fffffff, v46
	v_cndmask_b32_e32 v54, v50, v54, vcc
	v_cmp_gt_f32_e32 vcc, 0, v45
	v_and_b32_e32 v45, 0x7fffffff, v47
	v_pk_fma_f32 v[44:45], v[44:45], s[14:15], 1.0 op_sel_hi:[1,0,0]
	v_cndmask_b32_e32 v55, v51, v55, vcc
	v_rcp_f32_e32 v44, v44
	v_rcp_f32_e32 v45, v45
	v_cmp_gt_f32_e32 vcc, 0, v46
	v_pk_fma_f32 v[50:51], v[44:45], s[0:1], v[120:121] op_sel_hi:[1,0,0]
	s_nop 0
	v_pk_fma_f32 v[50:51], v[44:45], v[50:51], s[16:17] op_sel_hi:[1,1,0]
	s_nop 0
	v_pk_fma_f32 v[50:51], v[44:45], v[50:51], s[18:19] op_sel_hi:[1,1,0]
	s_nop 0
	v_pk_fma_f32 v[50:51], v[44:45], v[50:51], s[34:35] op_sel_hi:[1,1,0]
	s_nop 0
	v_pk_mul_f32 v[44:45], v[44:45], v[50:51]
	v_pk_mul_f32 v[50:51], v[52:53], s[36:37] op_sel_hi:[1,0]
	s_nop 0
	v_exp_f32_e32 v50, v50
	v_exp_f32_e32 v51, v51
	s_nop 0
	v_pk_mul_f32 v[44:45], v[50:51], v[44:45]
	s_nop 0
	v_pk_mul_f32 v[50:51], v[46:47], v[44:45]
	v_pk_fma_f32 v[44:45], v[46:47], v[44:45], v[46:47] neg_lo:[1,0,0] neg_hi:[1,0,0]
	s_nop 0
	v_cndmask_b32_e32 v52, v44, v50, vcc
	v_cmp_gt_f32_e32 vcc, 0, v47
	v_and_b32_e32 v44, 0x7fffffff, v40
	s_nop 0
	v_cndmask_b32_e32 v53, v45, v51, vcc
	v_and_b32_e32 v45, 0x7fffffff, v41
	v_pk_fma_f32 v[44:45], v[44:45], s[14:15], 1.0 op_sel_hi:[1,0,0]
	v_pk_mul_f32 v[50:51], v[40:41], v[40:41]
	v_rcp_f32_e32 v44, v44
	v_rcp_f32_e32 v45, v45
	v_pk_mul_f32 v[50:51], v[50:51], s[36:37] op_sel_hi:[1,0]
	v_cmp_gt_f32_e32 vcc, 0, v40
	v_exp_f32_e32 v50, v50
	v_pk_fma_f32 v[46:47], v[44:45], s[0:1], v[120:121] op_sel_hi:[1,0,0]
	v_exp_f32_e32 v51, v51
	v_pk_fma_f32 v[46:47], v[44:45], v[46:47], s[16:17] op_sel_hi:[1,1,0]
	s_nop 0
	v_pk_fma_f32 v[46:47], v[44:45], v[46:47], s[18:19] op_sel_hi:[1,1,0]
	s_nop 0
	v_pk_fma_f32 v[46:47], v[44:45], v[46:47], s[34:35] op_sel_hi:[1,1,0]
	s_nop 0
	v_pk_mul_f32 v[44:45], v[44:45], v[46:47]
	v_pk_mul_f32 v[46:47], v[42:43], v[42:43]
	v_pk_mul_f32 v[44:45], v[50:51], v[44:45]
	s_nop 0
	v_pk_mul_f32 v[50:51], v[40:41], v[44:45]
	v_pk_fma_f32 v[44:45], v[40:41], v[44:45], v[40:41] neg_lo:[1,0,0] neg_hi:[1,0,0]
	v_and_b32_e32 v40, 0x7fffffff, v42
	v_cndmask_b32_e32 v50, v44, v50, vcc
	v_cmp_gt_f32_e32 vcc, 0, v41
	v_and_b32_e32 v41, 0x7fffffff, v43
	v_pk_fma_f32 v[40:41], v[40:41], s[14:15], 1.0 op_sel_hi:[1,0,0]
	v_cndmask_b32_e32 v51, v45, v51, vcc
	v_rcp_f32_e32 v40, v40
	v_rcp_f32_e32 v41, v41
	v_cmp_gt_f32_e32 vcc, 0, v42
	v_pk_fma_f32 v[44:45], v[40:41], s[0:1], v[120:121] op_sel_hi:[1,0,0]
	s_nop 0
	v_pk_fma_f32 v[44:45], v[40:41], v[44:45], s[16:17] op_sel_hi:[1,1,0]
	s_nop 0
	v_pk_fma_f32 v[44:45], v[40:41], v[44:45], s[18:19] op_sel_hi:[1,1,0]
	s_nop 0
	v_pk_fma_f32 v[44:45], v[40:41], v[44:45], s[34:35] op_sel_hi:[1,1,0]
	s_nop 0
	v_pk_mul_f32 v[40:41], v[40:41], v[44:45]
	v_pk_mul_f32 v[44:45], v[46:47], s[36:37] op_sel_hi:[1,0]
	s_nop 0
	v_exp_f32_e32 v44, v44
	v_exp_f32_e32 v45, v45
	s_nop 0
	v_pk_mul_f32 v[40:41], v[44:45], v[40:41]
	s_nop 0
	v_pk_mul_f32 v[44:45], v[42:43], v[40:41]
	v_pk_fma_f32 v[40:41], v[42:43], v[40:41], v[42:43] neg_lo:[1,0,0] neg_hi:[1,0,0]
	v_cvt_pk_bf16_f32 v42, v50, v51
	v_cndmask_b32_e32 v44, v40, v44, vcc
	v_cmp_gt_f32_e32 vcc, 0, v43
	v_cvt_pk_bf16_f32 v40, v54, v55
	s_nop 0
	v_cndmask_b32_e32 v43, v41, v45, vcc
	v_cvt_pk_bf16_f32 v41, v52, v53
	v_cvt_pk_bf16_f32 v43, v44, v43
	global_store_dwordx4 v[48:49], v[40:43], off
	v_pk_mul_f32 v[44:45], v[36:37], v[36:37]
	v_cmp_gt_f32_e32 vcc, 0, v36
	v_and_b32_e32 v41, 0x7fffffff, v37
	v_and_b32_e32 v40, 0x7fffffff, v36
	v_pk_fma_f32 v[40:41], v[40:41], s[14:15], 1.0 op_sel_hi:[1,0,0]
	v_pk_mul_f32 v[44:45], v[44:45], s[36:37] op_sel_hi:[1,0]
	v_rcp_f32_e32 v40, v40
	v_rcp_f32_e32 v41, v41
	v_exp_f32_e32 v44, v44
	v_exp_f32_e32 v45, v45
	v_pk_fma_f32 v[42:43], v[40:41], s[0:1], v[120:121] op_sel_hi:[1,0,0]
	s_nop 0
; DEV bf16x8 pack8(f32x4 a, f32x4 b) { u32x4 w; w.x = cvt_pk_bf16(a[0], a[1]); w.y = cvt_pk_bf16(a[2], a[3]); w.z = cvt_pk_bf16(b[0], b[1]); w.w = cvt_pk_bf16(b[2], b[3]); return __builtin_bit_cast(bf16x8, w); }
; DEV f32x2 gelu_pk(f32x2 v) {
;     const f32x2 av = __builtin_elementwise_abs(v), d = av * 0.2316418882f + 1.0f;
;     f32x2 t; t.x = __builtin_amdgcn_rcpf(d.x); t.y = __builtin_amdgcn_rcpf(d.y);
;     f32x2 q = t * 0.5307027145f + (-0.7265760135f); q = q * t + 0.7107068705f; q = q * t + (-0.142248368f); q = q * t + 0.127414796f; q = q * t;
;     const f32x2 s = (v * v) * (-0.72134752044f);
;     f32x2 e; e.x = __builtin_amdgcn_exp2f(s.x); e.y = __builtin_amdgcn_exp2f(s.y);
;     const f32x2 m = v * (q * e), r = v - m;
;     f32x2 o; o.x = v.x < 0.f ? m.x : r.x; o.y = v.y < 0.f ? m.y : r.y; return o;
; }
; DEV f32x4 gelu4(f32x4 v) { f32x2 a = gelu_pk((f32x2){v[0], v[1]}), b = gelu_pk((f32x2){v[2], v[3]}); return (f32x4){a.x, a.y, b.x, b.y}; }
; template <int ACT, bool PERM>
; DEV void store_bf16_tile(AccRef acc, u16* O, int ld, int row0, int col0, const float* ss) {
;     ...
;             for (int bj = 0; bj < 2; ++bj) { f32x4 v0 = acc[ai][bj][m][0] * rs, v1 = acc[ai][bj][m][1] * rs; if (ACT == 1) { v0 = gelu4(v0); v1 = gelu4(v1); }
;                 if (PERM) *(u32x4*)(rowp + bj * 128) = __builtin_bit_cast(u32x4, pack8(v0, v1));
	v_pk_fma_f32 v[42:43], v[40:41], v[42:43], s[16:17] op_sel_hi:[1,1,0]
	s_nop 0
	v_pk_fma_f32 v[42:43], v[40:41], v[42:43], s[18:19] op_sel_hi:[1,1,0]
	s_nop 0
	v_pk_fma_f32 v[42:43], v[40:41], v[42:43], s[34:35] op_sel_hi:[1,1,0]
	s_nop 0
	v_pk_mul_f32 v[40:41], v[40:41], v[42:43]
	v_pk_mul_f32 v[42:43], v[38:39], v[38:39]
	v_pk_mul_f32 v[40:41], v[44:45], v[40:41]
	s_nop 0
	v_pk_mul_f32 v[44:45], v[36:37], v[40:41]
	v_pk_fma_f32 v[40:41], v[36:37], v[40:41], v[36:37] neg_lo:[1,0,0] neg_hi:[1,0,0]
	v_and_b32_e32 v36, 0x7fffffff, v38
	v_cndmask_b32_e32 v44, v40, v44, vcc
	v_cmp_gt_f32_e32 vcc, 0, v37
	v_and_b32_e32 v37, 0x7fffffff, v39
	v_pk_fma_f32 v[36:37], v[36:37], s[14:15], 1.0 op_sel_hi:[1,0,0]
	v_cndmask_b32_e32 v45, v41, v45, vcc
	v_rcp_f32_e32 v36, v36
	v_rcp_f32_e32 v37, v37
	v_cmp_gt_f32_e32 vcc, 0, v38
	v_pk_fma_f32 v[40:41], v[36:37], s[0:1], v[120:121] op_sel_hi:[1,0,0]
	s_nop 0
	v_pk_fma_f32 v[40:41], v[36:37], v[40:41], s[16:17] op_sel_hi:[1,1,0]
	s_nop 0
	v_pk_fma_f32 v[40:41], v[36:37], v[40:41], s[18:19] op_sel_hi:[1,1,0]
	s_nop 0
	v_pk_fma_f32 v[40:41], v[36:37], v[40:41], s[34:35] op_sel_hi:[1,1,0]
	s_nop 0
	v_pk_mul_f32 v[36:37], v[36:37], v[40:41]
	v_pk_mul_f32 v[40:41], v[42:43], s[36:37] op_sel_hi:[1,0]
	s_nop 0
	v_exp_f32_e32 v40, v40
	v_exp_f32_e32 v41, v41
	s_nop 0
	v_pk_mul_f32 v[36:37], v[40:41], v[36:37]
	s_nop 0
	v_pk_mul_f32 v[40:41], v[38:39], v[36:37]
	v_pk_fma_f32 v[36:37], v[38:39], v[36:37], v[38:39] neg_lo:[1,0,0] neg_hi:[1,0,0]
	s_nop 0
	v_cndmask_b32_e32 v42, v36, v40, vcc
	v_cmp_gt_f32_e32 vcc, 0, v39
	v_and_b32_e32 v36, 0x7fffffff, v32
	s_nop 0
	v_cndmask_b32_e32 v43, v37, v41, vcc
	v_and_b32_e32 v37, 0x7fffffff, v33
	v_pk_fma_f32 v[36:37], v[36:37], s[14:15], 1.0 op_sel_hi:[1,0,0]
	v_pk_mul_f32 v[40:41], v[32:33], v[32:33]
	v_rcp_f32_e32 v36, v36
	v_rcp_f32_e32 v37, v37
	v_pk_mul_f32 v[40:41], v[40:41], s[36:37] op_sel_hi:[1,0]
	v_cmp_gt_f32_e32 vcc, 0, v32
	v_exp_f32_e32 v40, v40
	v_pk_fma_f32 v[38:39], v[36:37], s[0:1], v[120:121] op_sel_hi:[1,0,0]
	v_exp_f32_e32 v41, v41
	v_pk_fma_f32 v[38:39], v[36:37], v[38:39], s[16:17] op_sel_hi:[1,1,0]
	s_nop 0
	v_pk_fma_f32 v[38:39], v[36:37], v[38:39], s[18:19] op_sel_hi:[1,1,0]
	s_nop 0
	v_pk_fma_f32 v[38:39], v[36:37], v[38:39], s[34:35] op_sel_hi:[1,1,0]
	s_nop 0
	v_pk_mul_f32 v[36:37], v[36:37], v[38:39]
	v_pk_mul_f32 v[38:39], v[34:35], v[34:35]
	v_pk_mul_f32 v[36:37], v[40:41], v[36:37]
	s_nop 0
	v_pk_mul_f32 v[40:41], v[32:33], v[36:37]
	v_pk_fma_f32 v[36:37], v[32:33], v[36:37], v[32:33] neg_lo:[1,0,0] neg_hi:[1,0,0]
	v_and_b32_e32 v32, 0x7fffffff, v34
	v_cndmask_b32_e32 v40, v36, v40, vcc
	v_cmp_gt_f32_e32 vcc, 0, v33
	v_and_b32_e32 v33, 0x7fffffff, v35
	v_pk_fma_f32 v[32:33], v[32:33], s[14:15], 1.0 op_sel_hi:[1,0,0]
	v_cndmask_b32_e32 v41, v37, v41, vcc
	v_rcp_f32_e32 v32, v32
	v_rcp_f32_e32 v33, v33
	v_cmp_gt_f32_e32 vcc, 0, v34
	v_pk_fma_f32 v[36:37], v[32:33], s[0:1], v[120:121] op_sel_hi:[1,0,0]
	s_nop 0
	v_pk_fma_f32 v[36:37], v[32:33], v[36:37], s[16:17] op_sel_hi:[1,1,0]
	s_nop 0
	v_pk_fma_f32 v[36:37], v[32:33], v[36:37], s[18:19] op_sel_hi:[1,1,0]
	s_nop 0
	v_pk_fma_f32 v[36:37], v[32:33], v[36:37], s[34:35] op_sel_hi:[1,1,0]
	s_nop 0
	v_pk_mul_f32 v[32:33], v[32:33], v[36:37]
	v_pk_mul_f32 v[36:37], v[38:39], s[36:37] op_sel_hi:[1,0]
	v_pk_mul_f32 v[38:39], v[28:29], v[28:29]
	v_exp_f32_e32 v36, v36
	v_exp_f32_e32 v37, v37
	v_pk_mul_f32 v[38:39], v[38:39], s[36:37] op_sel_hi:[1,0]
	v_pk_mul_f32 v[32:33], v[36:37], v[32:33]
	s_nop 0
	v_pk_mul_f32 v[36:37], v[34:35], v[32:33]
	v_pk_fma_f32 v[32:33], v[34:35], v[32:33], v[34:35] neg_lo:[1,0,0] neg_hi:[1,0,0]
	v_cvt_pk_bf16_f32 v34, v40, v41
	v_cndmask_b32_e32 v36, v32, v36, vcc
	v_cmp_gt_f32_e32 vcc, 0, v35
	v_cvt_pk_bf16_f32 v32, v44, v45
	v_exp_f32_e32 v38, v38
	v_cndmask_b32_e32 v35, v33, v37, vcc
	v_cvt_pk_bf16_f32 v33, v42, v43
	v_cvt_pk_bf16_f32 v35, v36, v35
	global_store_dwordx4 v[48:49], v[32:35], off offset:256
	v_exp_f32_e32 v39, v39
	v_cmp_gt_f32_e32 vcc, 0, v28
	v_and_b32_e32 v35, 0x7fffffff, v29
	v_and_b32_e32 v34, 0x7fffffff, v28
	v_pk_fma_f32 v[34:35], v[34:35], s[14:15], 1.0 op_sel_hi:[1,0,0]
	v_lshlrev_b64 v[32:33], 13, v[154:155]
	v_rcp_f32_e32 v34, v34
	v_rcp_f32_e32 v35, v35
	v_lshl_add_u64 v[32:33], v[130:131], 0, v[32:33]
	v_pk_fma_f32 v[36:37], v[34:35], s[0:1], v[120:121] op_sel_hi:[1,0,0]
	s_nop 0
	v_pk_fma_f32 v[36:37], v[34:35], v[36:37], s[16:17] op_sel_hi:[1,1,0]
	s_nop 0
	v_pk_fma_f32 v[36:37], v[34:35], v[36:37], s[18:19] op_sel_hi:[1,1,0]
	s_nop 0
	v_pk_fma_f32 v[36:37], v[34:35], v[36:37], s[34:35] op_sel_hi:[1,1,0]
	s_nop 0
	v_pk_mul_f32 v[34:35], v[34:35], v[36:37]
	v_pk_mul_f32 v[36:37], v[30:31], v[30:31]
	v_pk_mul_f32 v[34:35], v[38:39], v[34:35]
	s_nop 0
	v_pk_mul_f32 v[38:39], v[28:29], v[34:35]
	v_pk_fma_f32 v[34:35], v[28:29], v[34:35], v[28:29] neg_lo:[1,0,0] neg_hi:[1,0,0]
	v_and_b32_e32 v28, 0x7fffffff, v30
	v_cndmask_b32_e32 v38, v34, v38, vcc
	v_cmp_gt_f32_e32 vcc, 0, v29
	v_and_b32_e32 v29, 0x7fffffff, v31
	v_pk_fma_f32 v[28:29], v[28:29], s[14:15], 1.0 op_sel_hi:[1,0,0]
	v_cndmask_b32_e32 v39, v35, v39, vcc
	v_rcp_f32_e32 v28, v28
	v_rcp_f32_e32 v29, v29
	v_cmp_gt_f32_e32 vcc, 0, v30
	v_pk_fma_f32 v[34:35], v[28:29], s[0:1], v[120:121] op_sel_hi:[1,0,0]
	s_nop 0
	v_pk_fma_f32 v[34:35], v[28:29], v[34:35], s[16:17] op_sel_hi:[1,1,0]
	s_nop 0
	v_pk_fma_f32 v[34:35], v[28:29], v[34:35], s[18:19] op_sel_hi:[1,1,0]
	s_nop 0
	v_pk_fma_f32 v[34:35], v[28:29], v[34:35], s[34:35] op_sel_hi:[1,1,0]
	s_nop 0
	v_pk_mul_f32 v[28:29], v[28:29], v[34:35]
	v_pk_mul_f32 v[34:35], v[36:37], s[36:37] op_sel_hi:[1,0]
	s_nop 0
	v_exp_f32_e32 v34, v34
; DEV bf16x8 pack8(f32x4 a, f32x4 b) { u32x4 w; w.x = cvt_pk_bf16(a[0], a[1]); w.y = cvt_pk_bf16(a[2], a[3]); w.z = cvt_pk_bf16(b[0], b[1]); w.w = cvt_pk_bf16(b[2], b[3]); return __builtin_bit_cast(bf16x8, w); }
; DEV f32x2 gelu_pk(f32x2 v) {
;     const f32x2 av = __builtin_elementwise_abs(v), d = av * 0.2316418882f + 1.0f;
;     f32x2 t; t.x = __builtin_amdgcn_rcpf(d.x); t.y = __builtin_amdgcn_rcpf(d.y);
;     f32x2 q = t * 0.5307027145f + (-0.7265760135f); q = q * t + 0.7107068705f; q = q * t + (-0.142248368f); q = q * t + 0.127414796f; q = q * t;
;     const f32x2 s = (v * v) * (-0.72134752044f);
;     f32x2 e; e.x = __builtin_amdgcn_exp2f(s.x); e.y = __builtin_amdgcn_exp2f(s.y);
;     const f32x2 m = v * (q * e), r = v - m;
;     f32x2 o; o.x = v.x < 0.f ? m.x : r.x; o.y = v.y < 0.f ? m.y : r.y; return o;
; }
; DEV f32x4 gelu4(f32x4 v) { f32x2 a = gelu_pk((f32x2){v[0], v[1]}), b = gelu_pk((f32x2){v[2], v[3]}); return (f32x4){a.x, a.y, b.x, b.y}; }
; template <int ACT, bool PERM>
; DEV void store_bf16_tile(AccRef acc, u16* O, int ld, int row0, int col0, const float* ss) {
;     ...
;             for (int bj = 0; bj < 2; ++bj) { f32x4 v0 = acc[ai][bj][m][0] * rs, v1 = acc[ai][bj][m][1] * rs; if (ACT == 1) { v0 = gelu4(v0); v1 = gelu4(v1); }
;                 if (PERM) *(u32x4*)(rowp + bj * 128) = __builtin_bit_cast(u32x4, pack8(v0, v1));
	v_exp_f32_e32 v35, v35
	s_nop 0
	v_pk_mul_f32 v[28:29], v[34:35], v[28:29]
	s_nop 0
	v_pk_mul_f32 v[34:35], v[30:31], v[28:29]
	v_pk_fma_f32 v[28:29], v[30:31], v[28:29], v[30:31] neg_lo:[1,0,0] neg_hi:[1,0,0]
	s_nop 0
	v_cndmask_b32_e32 v36, v28, v34, vcc
	v_cmp_gt_f32_e32 vcc, 0, v31
	v_and_b32_e32 v28, 0x7fffffff, v24
	s_nop 0
	v_cndmask_b32_e32 v37, v29, v35, vcc
	v_and_b32_e32 v29, 0x7fffffff, v25
	v_pk_fma_f32 v[28:29], v[28:29], s[14:15], 1.0 op_sel_hi:[1,0,0]
	v_pk_mul_f32 v[34:35], v[24:25], v[24:25]
	v_rcp_f32_e32 v28, v28
	v_rcp_f32_e32 v29, v29
	v_pk_mul_f32 v[34:35], v[34:35], s[36:37] op_sel_hi:[1,0]
	v_cmp_gt_f32_e32 vcc, 0, v24
	v_exp_f32_e32 v34, v34
	v_pk_fma_f32 v[30:31], v[28:29], s[0:1], v[120:121] op_sel_hi:[1,0,0]
	v_exp_f32_e32 v35, v35
	v_pk_fma_f32 v[30:31], v[28:29], v[30:31], s[16:17] op_sel_hi:[1,1,0]
	s_nop 0
	v_pk_fma_f32 v[30:31], v[28:29], v[30:31], s[18:19] op_sel_hi:[1,1,0]
	s_nop 0
	v_pk_fma_f32 v[30:31], v[28:29], v[30:31], s[34:35] op_sel_hi:[1,1,0]
	s_nop 0
	v_pk_mul_f32 v[28:29], v[28:29], v[30:31]
	v_pk_mul_f32 v[30:31], v[26:27], v[26:27]
	v_pk_mul_f32 v[28:29], v[34:35], v[28:29]
	s_nop 0
	v_pk_mul_f32 v[34:35], v[24:25], v[28:29]
	v_pk_fma_f32 v[28:29], v[24:25], v[28:29], v[24:25] neg_lo:[1,0,0] neg_hi:[1,0,0]
	v_and_b32_e32 v24, 0x7fffffff, v26
	v_cndmask_b32_e32 v34, v28, v34, vcc
	v_cmp_gt_f32_e32 vcc, 0, v25
	v_and_b32_e32 v25, 0x7fffffff, v27
	v_pk_fma_f32 v[24:25], v[24:25], s[14:15], 1.0 op_sel_hi:[1,0,0]
	v_cndmask_b32_e32 v35, v29, v35, vcc
	v_rcp_f32_e32 v24, v24
	v_rcp_f32_e32 v25, v25
	v_cmp_gt_f32_e32 vcc, 0, v26
	v_pk_fma_f32 v[28:29], v[24:25], s[0:1], v[120:121] op_sel_hi:[1,0,0]
	s_nop 0
	v_pk_fma_f32 v[28:29], v[24:25], v[28:29], s[16:17] op_sel_hi:[1,1,0]
	s_nop 0
	v_pk_fma_f32 v[28:29], v[24:25], v[28:29], s[18:19] op_sel_hi:[1,1,0]
	s_nop 0
	v_pk_fma_f32 v[28:29], v[24:25], v[28:29], s[34:35] op_sel_hi:[1,1,0]
	s_nop 0
	v_pk_mul_f32 v[24:25], v[24:25], v[28:29]
	v_pk_mul_f32 v[28:29], v[30:31], s[36:37] op_sel_hi:[1,0]
	s_nop 0
	v_exp_f32_e32 v28, v28
	v_exp_f32_e32 v29, v29
	s_nop 0
	v_pk_mul_f32 v[24:25], v[28:29], v[24:25]
	s_nop 0
	v_pk_mul_f32 v[28:29], v[26:27], v[24:25]
	v_pk_fma_f32 v[24:25], v[26:27], v[24:25], v[26:27] neg_lo:[1,0,0] neg_hi:[1,0,0]
	v_cvt_pk_bf16_f32 v26, v34, v35
	v_cndmask_b32_e32 v28, v24, v28, vcc
	v_cmp_gt_f32_e32 vcc, 0, v27
	v_cvt_pk_bf16_f32 v24, v38, v39
	s_nop 0
	v_cndmask_b32_e32 v27, v25, v29, vcc
	v_cvt_pk_bf16_f32 v25, v36, v37
	v_cvt_pk_bf16_f32 v27, v28, v27
	global_store_dwordx4 v[32:33], v[24:27], off
	v_pk_mul_f32 v[28:29], v[20:21], v[20:21]
	v_cmp_gt_f32_e32 vcc, 0, v20
	v_and_b32_e32 v25, 0x7fffffff, v21
	v_and_b32_e32 v24, 0x7fffffff, v20
	v_pk_fma_f32 v[24:25], v[24:25], s[14:15], 1.0 op_sel_hi:[1,0,0]
	v_pk_mul_f32 v[28:29], v[28:29], s[36:37] op_sel_hi:[1,0]
	v_rcp_f32_e32 v24, v24
	v_rcp_f32_e32 v25, v25
	v_exp_f32_e32 v28, v28
	v_exp_f32_e32 v29, v29
	v_pk_fma_f32 v[26:27], v[24:25], s[0:1], v[120:121] op_sel_hi:[1,0,0]
	s_nop 0
	v_pk_fma_f32 v[26:27], v[24:25], v[26:27], s[16:17] op_sel_hi:[1,1,0]
	s_nop 0
	v_pk_fma_f32 v[26:27], v[24:25], v[26:27], s[18:19] op_sel_hi:[1,1,0]
	s_nop 0
	v_pk_fma_f32 v[26:27], v[24:25], v[26:27], s[34:35] op_sel_hi:[1,1,0]
	s_nop 0
	v_pk_mul_f32 v[24:25], v[24:25], v[26:27]
	v_pk_mul_f32 v[26:27], v[22:23], v[22:23]
	v_pk_mul_f32 v[24:25], v[28:29], v[24:25]
	s_nop 0
	v_pk_mul_f32 v[28:29], v[20:21], v[24:25]
	v_pk_fma_f32 v[24:25], v[20:21], v[24:25], v[20:21] neg_lo:[1,0,0] neg_hi:[1,0,0]
	v_and_b32_e32 v20, 0x7fffffff, v22
	v_cndmask_b32_e32 v28, v24, v28, vcc
	v_cmp_gt_f32_e32 vcc, 0, v21
	v_and_b32_e32 v21, 0x7fffffff, v23
	v_pk_fma_f32 v[20:21], v[20:21], s[14:15], 1.0 op_sel_hi:[1,0,0]
	v_cndmask_b32_e32 v29, v25, v29, vcc
	v_rcp_f32_e32 v20, v20
	v_rcp_f32_e32 v21, v21
	v_cmp_gt_f32_e32 vcc, 0, v22
	v_pk_fma_f32 v[24:25], v[20:21], s[0:1], v[120:121] op_sel_hi:[1,0,0]
	s_nop 0
	v_pk_fma_f32 v[24:25], v[20:21], v[24:25], s[16:17] op_sel_hi:[1,1,0]
	s_nop 0
	v_pk_fma_f32 v[24:25], v[20:21], v[24:25], s[18:19] op_sel_hi:[1,1,0]
	s_nop 0
	v_pk_fma_f32 v[24:25], v[20:21], v[24:25], s[34:35] op_sel_hi:[1,1,0]
	s_nop 0
	v_pk_mul_f32 v[20:21], v[20:21], v[24:25]
	v_pk_mul_f32 v[24:25], v[26:27], s[36:37] op_sel_hi:[1,0]
	s_nop 0
	v_exp_f32_e32 v24, v24
	v_exp_f32_e32 v25, v25
	s_nop 0
	v_pk_mul_f32 v[20:21], v[24:25], v[20:21]
	s_nop 0
	v_pk_mul_f32 v[24:25], v[22:23], v[20:21]
	v_pk_fma_f32 v[20:21], v[22:23], v[20:21], v[22:23] neg_lo:[1,0,0] neg_hi:[1,0,0]
	s_nop 0
	v_cndmask_b32_e32 v26, v20, v24, vcc
	v_cmp_gt_f32_e32 vcc, 0, v23
	v_and_b32_e32 v20, 0x7fffffff, v16
	s_nop 0
	v_cndmask_b32_e32 v27, v21, v25, vcc
	v_and_b32_e32 v21, 0x7fffffff, v17
	v_pk_fma_f32 v[20:21], v[20:21], s[14:15], 1.0 op_sel_hi:[1,0,0]
	v_pk_mul_f32 v[24:25], v[16:17], v[16:17]
	v_rcp_f32_e32 v20, v20
	v_rcp_f32_e32 v21, v21
	v_pk_mul_f32 v[24:25], v[24:25], s[36:37] op_sel_hi:[1,0]
	v_cmp_gt_f32_e32 vcc, 0, v16
	v_exp_f32_e32 v24, v24
	v_pk_fma_f32 v[22:23], v[20:21], s[0:1], v[120:121] op_sel_hi:[1,0,0]
	v_exp_f32_e32 v25, v25
	v_pk_fma_f32 v[22:23], v[20:21], v[22:23], s[16:17] op_sel_hi:[1,1,0]
	s_nop 0
	v_pk_fma_f32 v[22:23], v[20:21], v[22:23], s[18:19] op_sel_hi:[1,1,0]
	s_nop 0
	v_pk_fma_f32 v[22:23], v[20:21], v[22:23], s[34:35] op_sel_hi:[1,1,0]
	s_nop 0
	v_pk_mul_f32 v[20:21], v[20:21], v[22:23]
	v_pk_mul_f32 v[22:23], v[18:19], v[18:19]
	v_pk_mul_f32 v[20:21], v[24:25], v[20:21]
	s_nop 0
	v_pk_mul_f32 v[24:25], v[16:17], v[20:21]
	v_pk_fma_f32 v[20:21], v[16:17], v[20:21], v[16:17] neg_lo:[1,0,0] neg_hi:[1,0,0]
	v_and_b32_e32 v16, 0x7fffffff, v18
	v_cndmask_b32_e32 v24, v20, v24, vcc
; DEV bf16x8 pack8(f32x4 a, f32x4 b) { u32x4 w; w.x = cvt_pk_bf16(a[0], a[1]); w.y = cvt_pk_bf16(a[2], a[3]); w.z = cvt_pk_bf16(b[0], b[1]); w.w = cvt_pk_bf16(b[2], b[3]); return __builtin_bit_cast(bf16x8, w); }
; DEV f32x2 gelu_pk(f32x2 v) {
;     const f32x2 av = __builtin_elementwise_abs(v), d = av * 0.2316418882f + 1.0f;
;     f32x2 t; t.x = __builtin_amdgcn_rcpf(d.x); t.y = __builtin_amdgcn_rcpf(d.y);
;     f32x2 q = t * 0.5307027145f + (-0.7265760135f); q = q * t + 0.7107068705f; q = q * t + (-0.142248368f); q = q * t + 0.127414796f; q = q * t;
;     const f32x2 s = (v * v) * (-0.72134752044f);
;     f32x2 e; e.x = __builtin_amdgcn_exp2f(s.x); e.y = __builtin_amdgcn_exp2f(s.y);
;     const f32x2 m = v * (q * e), r = v - m;
;     f32x2 o; o.x = v.x < 0.f ? m.x : r.x; o.y = v.y < 0.f ? m.y : r.y; return o;
; }
; DEV f32x4 gelu4(f32x4 v) { f32x2 a = gelu_pk((f32x2){v[0], v[1]}), b = gelu_pk((f32x2){v[2], v[3]}); return (f32x4){a.x, a.y, b.x, b.y}; }
; template <int ACT, bool PERM>
; DEV void store_bf16_tile(AccRef acc, u16* O, int ld, int row0, int col0, const float* ss) {
;     ...
;             for (int bj = 0; bj < 2; ++bj) { f32x4 v0 = acc[ai][bj][m][0] * rs, v1 = acc[ai][bj][m][1] * rs; if (ACT == 1) { v0 = gelu4(v0); v1 = gelu4(v1); }
;                 if (PERM) *(u32x4*)(rowp + bj * 128) = __builtin_bit_cast(u32x4, pack8(v0, v1));
	v_cmp_gt_f32_e32 vcc, 0, v17
	v_and_b32_e32 v17, 0x7fffffff, v19
	v_pk_fma_f32 v[16:17], v[16:17], s[14:15], 1.0 op_sel_hi:[1,0,0]
	v_cndmask_b32_e32 v25, v21, v25, vcc
	v_rcp_f32_e32 v16, v16
	v_rcp_f32_e32 v17, v17
	v_cmp_gt_f32_e32 vcc, 0, v18
	v_pk_fma_f32 v[20:21], v[16:17], s[0:1], v[120:121] op_sel_hi:[1,0,0]
	s_nop 0
	v_pk_fma_f32 v[20:21], v[16:17], v[20:21], s[16:17] op_sel_hi:[1,1,0]
	s_nop 0
	v_pk_fma_f32 v[20:21], v[16:17], v[20:21], s[18:19] op_sel_hi:[1,1,0]
	s_nop 0
	v_pk_fma_f32 v[20:21], v[16:17], v[20:21], s[34:35] op_sel_hi:[1,1,0]
	s_nop 0
	v_pk_mul_f32 v[16:17], v[16:17], v[20:21]
	v_pk_mul_f32 v[20:21], v[22:23], s[36:37] op_sel_hi:[1,0]
	v_pk_mul_f32 v[22:23], v[12:13], v[12:13]
	v_exp_f32_e32 v20, v20
	v_exp_f32_e32 v21, v21
	v_pk_mul_f32 v[22:23], v[22:23], s[36:37] op_sel_hi:[1,0]
	v_pk_mul_f32 v[16:17], v[20:21], v[16:17]
	s_nop 0
	v_pk_mul_f32 v[20:21], v[18:19], v[16:17]
	v_pk_fma_f32 v[16:17], v[18:19], v[16:17], v[18:19] neg_lo:[1,0,0] neg_hi:[1,0,0]
	v_cvt_pk_bf16_f32 v18, v24, v25
	v_cndmask_b32_e32 v20, v16, v20, vcc
	v_cmp_gt_f32_e32 vcc, 0, v19
	v_cvt_pk_bf16_f32 v16, v28, v29
	v_exp_f32_e32 v22, v22
	v_cndmask_b32_e32 v19, v17, v21, vcc
	v_cvt_pk_bf16_f32 v17, v26, v27
	v_cvt_pk_bf16_f32 v19, v20, v19
	global_store_dwordx4 v[32:33], v[16:19], off offset:256
	v_exp_f32_e32 v23, v23
	v_cmp_gt_f32_e32 vcc, 0, v12
	v_and_b32_e32 v19, 0x7fffffff, v13
	v_and_b32_e32 v18, 0x7fffffff, v12
	v_pk_fma_f32 v[18:19], v[18:19], s[14:15], 1.0 op_sel_hi:[1,0,0]
	v_lshlrev_b64 v[16:17], 13, v[152:153]
	v_rcp_f32_e32 v18, v18
	v_rcp_f32_e32 v19, v19
	v_lshl_add_u64 v[16:17], v[130:131], 0, v[16:17]
	v_pk_fma_f32 v[20:21], v[18:19], s[0:1], v[120:121] op_sel_hi:[1,0,0]
	s_nop 0
	v_pk_fma_f32 v[20:21], v[18:19], v[20:21], s[16:17] op_sel_hi:[1,1,0]
	s_nop 0
	v_pk_fma_f32 v[20:21], v[18:19], v[20:21], s[18:19] op_sel_hi:[1,1,0]
	s_nop 0
	v_pk_fma_f32 v[20:21], v[18:19], v[20:21], s[34:35] op_sel_hi:[1,1,0]
	s_nop 0
	v_pk_mul_f32 v[18:19], v[18:19], v[20:21]
	v_pk_mul_f32 v[20:21], v[14:15], v[14:15]
	v_pk_mul_f32 v[18:19], v[22:23], v[18:19]
	s_nop 0
	v_pk_mul_f32 v[22:23], v[12:13], v[18:19]
	v_pk_fma_f32 v[18:19], v[12:13], v[18:19], v[12:13] neg_lo:[1,0,0] neg_hi:[1,0,0]
	v_and_b32_e32 v12, 0x7fffffff, v14
	v_cndmask_b32_e32 v22, v18, v22, vcc
	v_cmp_gt_f32_e32 vcc, 0, v13
	v_and_b32_e32 v13, 0x7fffffff, v15
	v_pk_fma_f32 v[12:13], v[12:13], s[14:15], 1.0 op_sel_hi:[1,0,0]
	v_cndmask_b32_e32 v23, v19, v23, vcc
	v_rcp_f32_e32 v12, v12
	v_rcp_f32_e32 v13, v13
	v_cmp_gt_f32_e32 vcc, 0, v14
	v_pk_fma_f32 v[18:19], v[12:13], s[0:1], v[120:121] op_sel_hi:[1,0,0]
	s_nop 0
	v_pk_fma_f32 v[18:19], v[12:13], v[18:19], s[16:17] op_sel_hi:[1,1,0]
	s_nop 0
	v_pk_fma_f32 v[18:19], v[12:13], v[18:19], s[18:19] op_sel_hi:[1,1,0]
	s_nop 0
	v_pk_fma_f32 v[18:19], v[12:13], v[18:19], s[34:35] op_sel_hi:[1,1,0]
	s_nop 0
	v_pk_mul_f32 v[12:13], v[12:13], v[18:19]
	v_pk_mul_f32 v[18:19], v[20:21], s[36:37] op_sel_hi:[1,0]
	s_nop 0
	v_exp_f32_e32 v18, v18
	v_exp_f32_e32 v19, v19
	s_nop 0
	v_pk_mul_f32 v[12:13], v[18:19], v[12:13]
	s_nop 0
	v_pk_mul_f32 v[18:19], v[14:15], v[12:13]
	v_pk_fma_f32 v[12:13], v[14:15], v[12:13], v[14:15] neg_lo:[1,0,0] neg_hi:[1,0,0]
	s_nop 0
	v_cndmask_b32_e32 v20, v12, v18, vcc
	v_cmp_gt_f32_e32 vcc, 0, v15
	v_and_b32_e32 v12, 0x7fffffff, v8
	s_nop 0
	v_cndmask_b32_e32 v21, v13, v19, vcc
	v_and_b32_e32 v13, 0x7fffffff, v9
	v_pk_fma_f32 v[12:13], v[12:13], s[14:15], 1.0 op_sel_hi:[1,0,0]
	v_pk_mul_f32 v[18:19], v[8:9], v[8:9]
	v_rcp_f32_e32 v12, v12
	v_rcp_f32_e32 v13, v13
	v_pk_mul_f32 v[18:19], v[18:19], s[36:37] op_sel_hi:[1,0]
	v_cmp_gt_f32_e32 vcc, 0, v8
	v_exp_f32_e32 v18, v18
	v_pk_fma_f32 v[14:15], v[12:13], s[0:1], v[120:121] op_sel_hi:[1,0,0]
	v_exp_f32_e32 v19, v19
	v_pk_fma_f32 v[14:15], v[12:13], v[14:15], s[16:17] op_sel_hi:[1,1,0]
	s_nop 0
	v_pk_fma_f32 v[14:15], v[12:13], v[14:15], s[18:19] op_sel_hi:[1,1,0]
	s_nop 0
	v_pk_fma_f32 v[14:15], v[12:13], v[14:15], s[34:35] op_sel_hi:[1,1,0]
	s_nop 0
	v_pk_mul_f32 v[12:13], v[12:13], v[14:15]
	v_pk_mul_f32 v[14:15], v[10:11], v[10:11]
	v_pk_mul_f32 v[12:13], v[18:19], v[12:13]
	s_nop 0
	v_pk_mul_f32 v[18:19], v[8:9], v[12:13]
	v_pk_fma_f32 v[12:13], v[8:9], v[12:13], v[8:9] neg_lo:[1,0,0] neg_hi:[1,0,0]
	v_and_b32_e32 v8, 0x7fffffff, v10
	v_cndmask_b32_e32 v18, v12, v18, vcc
	v_cmp_gt_f32_e32 vcc, 0, v9
	v_and_b32_e32 v9, 0x7fffffff, v11
	v_pk_fma_f32 v[8:9], v[8:9], s[14:15], 1.0 op_sel_hi:[1,0,0]
	v_cndmask_b32_e32 v19, v13, v19, vcc
	v_rcp_f32_e32 v8, v8
	v_rcp_f32_e32 v9, v9
	v_cmp_gt_f32_e32 vcc, 0, v10
	v_pk_fma_f32 v[12:13], v[8:9], s[0:1], v[120:121] op_sel_hi:[1,0,0]
	s_nop 0
	v_pk_fma_f32 v[12:13], v[8:9], v[12:13], s[16:17] op_sel_hi:[1,1,0]
	s_nop 0
; DEV bf16x8 pack8(f32x4 a, f32x4 b) { u32x4 w; w.x = cvt_pk_bf16(a[0], a[1]); w.y = cvt_pk_bf16(a[2], a[3]); w.z = cvt_pk_bf16(b[0], b[1]); w.w = cvt_pk_bf16(b[2], b[3]); return __builtin_bit_cast(bf16x8, w); }
; DEV u32x2 pack4(f32x4 a) { u32x2 w; w.x = cvt_pk_bf16(a[0], a[1]); w.y = cvt_pk_bf16(a[2], a[3]); return w; }
; DEV f32x2 gelu_pk(f32x2 v) {
;     const f32x2 av = __builtin_elementwise_abs(v), d = av * 0.2316418882f + 1.0f;
;     f32x2 t; t.x = __builtin_amdgcn_rcpf(d.x); t.y = __builtin_amdgcn_rcpf(d.y);
;     f32x2 q = t * 0.5307027145f + (-0.7265760135f); q = q * t + 0.7107068705f; q = q * t + (-0.142248368f); q = q * t + 0.127414796f; q = q * t;
;     const f32x2 s = (v * v) * (-0.72134752044f);
;     f32x2 e; e.x = __builtin_amdgcn_exp2f(s.x); e.y = __builtin_amdgcn_exp2f(s.y);
;     const f32x2 m = v * (q * e), r = v - m;
;     f32x2 o; o.x = v.x < 0.f ? m.x : r.x; o.y = v.y < 0.f ? m.y : r.y; return o;
; }
; DEV f32x4 gelu4(f32x4 v) { f32x2 a = gelu_pk((f32x2){v[0], v[1]}), b = gelu_pk((f32x2){v[2], v[3]}); return (f32x4){a.x, a.y, b.x, b.y}; }
; template <int ACT, bool PERM>
; DEV void store_bf16_tile(AccRef acc, u16* O, int ld, int row0, int col0, const float* ss) {
;     ...
;         for (int m = 0; m < 4; ++m) { u16* rowp = O + (size_t)(row0 + ai * 128 + m * 16) * ld + col0; const float rs = rsv[ai][m];
; #pragma unroll
;             for (int bj = 0; bj < 2; ++bj) { f32x4 v0 = acc[ai][bj][m][0] * rs, v1 = acc[ai][bj][m][1] * rs; if (ACT == 1) { v0 = gelu4(v0); v1 = gelu4(v1); }
;                 if (PERM) *(u32x4*)(rowp + bj * 128) = __builtin_bit_cast(u32x4, pack8(v0, v1));
;                 else { *(u32x2*)(rowp + bj * 128) = pack4(v0); *(u32x2*)(rowp + bj * 128 + 16) = pack4(v1); } } }
	v_pk_fma_f32 v[12:13], v[8:9], v[12:13], s[18:19] op_sel_hi:[1,1,0]
	s_nop 0
	v_pk_fma_f32 v[12:13], v[8:9], v[12:13], s[34:35] op_sel_hi:[1,1,0]
	s_nop 0
	v_pk_mul_f32 v[8:9], v[8:9], v[12:13]
	v_pk_mul_f32 v[12:13], v[14:15], s[36:37] op_sel_hi:[1,0]
	s_nop 0
	v_exp_f32_e32 v12, v12
	v_exp_f32_e32 v13, v13
	s_nop 0
	v_pk_mul_f32 v[8:9], v[12:13], v[8:9]
	s_nop 0
	v_pk_mul_f32 v[12:13], v[10:11], v[8:9]
	v_pk_fma_f32 v[8:9], v[10:11], v[8:9], v[10:11] neg_lo:[1,0,0] neg_hi:[1,0,0]
	v_cvt_pk_bf16_f32 v10, v18, v19
	v_cndmask_b32_e32 v12, v8, v12, vcc
	v_cmp_gt_f32_e32 vcc, 0, v11
	v_cvt_pk_bf16_f32 v8, v22, v23
	s_nop 0
	v_cndmask_b32_e32 v11, v9, v13, vcc
	v_cvt_pk_bf16_f32 v9, v20, v21
	v_cvt_pk_bf16_f32 v11, v12, v11
	global_store_dwordx4 v[16:17], v[8:11], off
	v_pk_mul_f32 v[12:13], v[4:5], v[4:5]
	v_cmp_gt_f32_e32 vcc, 0, v4
	v_and_b32_e32 v9, 0x7fffffff, v5
	v_and_b32_e32 v8, 0x7fffffff, v4
	v_pk_fma_f32 v[8:9], v[8:9], s[14:15], 1.0 op_sel_hi:[1,0,0]
	v_pk_mul_f32 v[12:13], v[12:13], s[36:37] op_sel_hi:[1,0]
	v_rcp_f32_e32 v8, v8
	v_rcp_f32_e32 v9, v9
	v_exp_f32_e32 v12, v12
	v_exp_f32_e32 v13, v13
	v_pk_fma_f32 v[10:11], v[8:9], s[0:1], v[120:121] op_sel_hi:[1,0,0]
	s_nop 0
	v_pk_fma_f32 v[10:11], v[8:9], v[10:11], s[16:17] op_sel_hi:[1,1,0]
	s_nop 0
	v_pk_fma_f32 v[10:11], v[8:9], v[10:11], s[18:19] op_sel_hi:[1,1,0]
	s_nop 0
	v_pk_fma_f32 v[10:11], v[8:9], v[10:11], s[34:35] op_sel_hi:[1,1,0]
	s_nop 0
	v_pk_mul_f32 v[8:9], v[8:9], v[10:11]
	v_pk_mul_f32 v[10:11], v[6:7], v[6:7]
	v_pk_mul_f32 v[8:9], v[12:13], v[8:9]
	s_nop 0
	v_pk_mul_f32 v[12:13], v[4:5], v[8:9]
	v_pk_fma_f32 v[8:9], v[4:5], v[8:9], v[4:5] neg_lo:[1,0,0] neg_hi:[1,0,0]
	v_and_b32_e32 v4, 0x7fffffff, v6
	v_cndmask_b32_e32 v12, v8, v12, vcc
	v_cmp_gt_f32_e32 vcc, 0, v5
	v_and_b32_e32 v5, 0x7fffffff, v7
	v_pk_fma_f32 v[4:5], v[4:5], s[14:15], 1.0 op_sel_hi:[1,0,0]
	v_cndmask_b32_e32 v13, v9, v13, vcc
	v_rcp_f32_e32 v4, v4
	v_rcp_f32_e32 v5, v5
	v_cmp_gt_f32_e32 vcc, 0, v6
	v_pk_fma_f32 v[8:9], v[4:5], s[0:1], v[120:121] op_sel_hi:[1,0,0]
	s_nop 0
	v_pk_fma_f32 v[8:9], v[4:5], v[8:9], s[16:17] op_sel_hi:[1,1,0]
	s_nop 0
	v_pk_fma_f32 v[8:9], v[4:5], v[8:9], s[18:19] op_sel_hi:[1,1,0]
	s_nop 0
	v_pk_fma_f32 v[8:9], v[4:5], v[8:9], s[34:35] op_sel_hi:[1,1,0]
	s_nop 0
	v_pk_mul_f32 v[4:5], v[4:5], v[8:9]
	v_pk_mul_f32 v[8:9], v[10:11], s[36:37] op_sel_hi:[1,0]
	s_nop 0
	v_exp_f32_e32 v8, v8
	v_exp_f32_e32 v9, v9
	s_nop 0
	v_pk_mul_f32 v[4:5], v[8:9], v[4:5]
	s_nop 0
	v_pk_mul_f32 v[8:9], v[6:7], v[4:5]
	v_pk_fma_f32 v[4:5], v[6:7], v[4:5], v[6:7] neg_lo:[1,0,0] neg_hi:[1,0,0]
	s_nop 0
	v_cndmask_b32_e32 v10, v4, v8, vcc
	v_cmp_gt_f32_e32 vcc, 0, v7
	v_and_b32_e32 v4, 0x7fffffff, v0
	s_nop 0
	v_cndmask_b32_e32 v11, v5, v9, vcc
	v_and_b32_e32 v5, 0x7fffffff, v1
	v_pk_fma_f32 v[4:5], v[4:5], s[14:15], 1.0 op_sel_hi:[1,0,0]
	v_pk_mul_f32 v[8:9], v[0:1], v[0:1]
	v_rcp_f32_e32 v4, v4
	v_rcp_f32_e32 v5, v5
	v_pk_mul_f32 v[8:9], v[8:9], s[36:37] op_sel_hi:[1,0]
	v_cmp_gt_f32_e32 vcc, 0, v0
	v_exp_f32_e32 v8, v8
	v_pk_fma_f32 v[6:7], v[4:5], s[0:1], v[120:121] op_sel_hi:[1,0,0]
	v_exp_f32_e32 v9, v9
	v_pk_fma_f32 v[6:7], v[4:5], v[6:7], s[16:17] op_sel_hi:[1,1,0]
	s_nop 0
	v_pk_fma_f32 v[6:7], v[4:5], v[6:7], s[18:19] op_sel_hi:[1,1,0]
	s_nop 0
	v_pk_fma_f32 v[6:7], v[4:5], v[6:7], s[34:35] op_sel_hi:[1,1,0]
	s_nop 0
	v_pk_mul_f32 v[4:5], v[4:5], v[6:7]
	v_pk_mul_f32 v[6:7], v[2:3], v[2:3]
	v_pk_mul_f32 v[4:5], v[8:9], v[4:5]
	s_nop 0
	v_pk_mul_f32 v[8:9], v[0:1], v[4:5]
	v_pk_fma_f32 v[4:5], v[0:1], v[4:5], v[0:1] neg_lo:[1,0,0] neg_hi:[1,0,0]
	v_and_b32_e32 v0, 0x7fffffff, v2
	v_cndmask_b32_e32 v8, v4, v8, vcc
	v_cmp_gt_f32_e32 vcc, 0, v1
	v_and_b32_e32 v1, 0x7fffffff, v3
	v_pk_fma_f32 v[0:1], v[0:1], s[14:15], 1.0 op_sel_hi:[1,0,0]
	v_cndmask_b32_e32 v9, v5, v9, vcc
	v_rcp_f32_e32 v0, v0
	v_rcp_f32_e32 v1, v1
	v_cmp_gt_f32_e32 vcc, 0, v2
	v_pk_fma_f32 v[4:5], v[0:1], s[0:1], v[120:121] op_sel_hi:[1,0,0]
	s_nop 0
	v_pk_fma_f32 v[4:5], v[0:1], v[4:5], s[16:17] op_sel_hi:[1,1,0]
	s_nop 0
	v_pk_fma_f32 v[4:5], v[0:1], v[4:5], s[18:19] op_sel_hi:[1,1,0]
	s_nop 0
	v_pk_fma_f32 v[4:5], v[0:1], v[4:5], s[34:35] op_sel_hi:[1,1,0]
	s_nop 0
	v_pk_mul_f32 v[0:1], v[0:1], v[4:5]
	v_pk_mul_f32 v[4:5], v[6:7], s[36:37] op_sel_hi:[1,0]
	s_nop 0
	v_exp_f32_e32 v4, v4
	v_exp_f32_e32 v5, v5
	s_nop 0
	v_pk_mul_f32 v[0:1], v[4:5], v[0:1]
	s_nop 0
	v_pk_mul_f32 v[4:5], v[2:3], v[0:1]
	v_pk_fma_f32 v[0:1], v[2:3], v[0:1], v[2:3] neg_lo:[1,0,0] neg_hi:[1,0,0]
	v_cvt_pk_bf16_f32 v2, v8, v9
	v_cndmask_b32_e32 v4, v0, v4, vcc
	v_cmp_gt_f32_e32 vcc, 0, v3
	v_cvt_pk_bf16_f32 v0, v12, v13
	s_nop 0
	v_cndmask_b32_e32 v3, v1, v5, vcc
	v_cvt_pk_bf16_f32 v1, v10, v11
	v_cvt_pk_bf16_f32 v3, v4, v3
	global_store_dwordx4 v[16:17], v[0:3], off offset:256
	s_branch .LBB0_584
